# a4 + self-max no-ops removed in attention, loop-invariant LDS base sums hoisted out of the K loops, accumulator zero-init with 64-bit moves
# speedup vs baseline: 1.0314x; 1.0057x over previous
; #define G_GLOAD(XR, WR, KT) { _Pragma("unroll") for (int i_ = 0; i_ < 4; ++i_) XR[i_] = *(const u32x4*)(Xt + ((size_t)(64 * i_) * ldx + (KT) * 64) * 2 + xoff); \
;     _Pragma("unroll") for (int i_ = 0; i_ < 4; ++i_) WR[i_] = *(const u32x4*)(Wtb + ((size_t)(64 * i_) * K + (KT) * 64) * 2 + woff); }
; #define G_LSTORE(XR, WR, STG) { char* xs_ = lds + (STG) * G_STAGE; char* ws_ = xs_ + G_XB; \
;     _Pragma("unroll") for (int i_ = 0; i_ < 4; ++i_) *(u32x4*)(xs_ + (lrow + 64 * i_) * LROW + lch * 16) = XR[i_]; \
;     _Pragma("unroll") for (int i_ = 0; i_ < 4; ++i_) *(u32x4*)(ws_ + (lrow + 64 * i_) * LROW + lch * 16) = WR[i_]; }
; template <class Epi>
; DI void gemm_phase(const bf16_t* __restrict__ X, const int ldx, const bf16_t* __restrict__ Wt, const int N, const int K, const Epi& epi, char* lds) {
;     ...
;     const int L = chunk * 32 + slot, band = L / (4 * nNt), rem = L % (4 * nNt);
;     const int mt_ = band * 4 + (rem & 3), nt_ = rem >> 2;
;     const char* Xt = (const char*)(X + (size_t)(mt_ * 256) * ldx);
;     const char* Wtb = (const char*)(Wt + (size_t)(nt_ * 256) * K);
;     const unsigned xoff = (unsigned)(lrow * ldx + lch * 8) * 2u, woff = (unsigned)(lrow * K + lch * 8) * 2u;
;     const bool has_next = !Epi::kFull && (chunk + 8 < nchunks);
;     const int Ln = (has_next ? chunk + 8 : chunk) * 32 + slot, band_n = Ln / (4 * nNt), rem_n = Ln % (4 * nNt);
;     const char* Xt_n = (const char*)(X + (size_t)((band_n * 4 + (rem_n & 3)) * 256) * ldx);
;     const char* Wtb_n = (const char*)(Wt + (size_t)((rem_n >> 2) * 256) * K);
;     f32x16 acc[2][2][2];
;     ...
;     asm volatile("" ::: "memory");
;     if (Epi::kFull || chunk == xcd) {
;       G_GLOAD(xr0, wr0, 0);
;       G_LSTORE(xr0, wr0, 0);
;       __syncthreads();
;       G_GLOAD(xr0, wr0, 1);
;     }
; #pragma unroll
;     for (int c = 0; c < 2; ++c)
; #pragma unroll
;       for (int a = 0; a < 2; ++a)
; #pragma unroll
;         for (int b = 0; b < 2; ++b)
; #pragma unroll
;           for (int i = 0; i < 16; ++i) acc[c][a][b][i] = 0.f;
.LBB0_85:
	s_add_i32 s46, s26, 8
	s_cmp_gt_u32 s26, 59
	s_cselect_b64 s[24:25], -1, 0
	s_cmp_lt_u32 s26, 60
	s_cselect_b32 s26, s46, s26
	s_cselect_b32 s5, 0, 15
	s_cselect_b32 s28, 1, 15
	s_lshl_b32 s26, s26, 5
	v_readlane_b32 s27, v254, 3
	s_add_i32 s26, s26, s27
	s_mul_hi_u32 s27, s26, 0xf0f0f0f1
	s_lshr_b32 s27, s27, 6
	s_mul_i32 s29, s27, 0x44
	s_sub_i32 s31, s26, s29
	s_lshl_b32 s26, s27, 10
	s_lshl_b32 s27, s31, 8
	s_and_b32 s27, s27, 0x300
	s_or_b32 s26, s27, s26
	s_ashr_i32 s27, s26, 31
	s_lshl_b64 s[26:27], s[26:27], 11
	s_add_u32 s29, s6, s26
	s_addc_u32 s30, s7, s27
	s_lshl_b32 s26, s31, 17
	s_and_b32 s26, s26, 0xf80000
	s_add_u32 s31, s44, s26
	v_mov_b32_e32 v2, 0
	s_addc_u32 s33, s45, 0
	s_mov_b32 s34, 3
	v_mov_b32_e32 v3, v2
	v_mov_b64_e32 v[4:5], v[2:3]
	v_mov_b64_e32 v[6:7], v[2:3]
	v_mov_b64_e32 v[8:9], v[2:3]
	v_mov_b64_e32 v[10:11], v[2:3]
	v_mov_b64_e32 v[12:13], v[2:3]
	v_mov_b64_e32 v[14:15], v[2:3]
	v_mov_b64_e32 v[16:17], v[2:3]
	s_waitcnt vmcnt(5)
	v_mov_b64_e32 v[34:35], v[2:3]
	v_mov_b64_e32 v[36:37], v[2:3]
	s_waitcnt vmcnt(4)
	v_mov_b64_e32 v[38:39], v[2:3]
	v_mov_b64_e32 v[40:41], v[2:3]
	s_waitcnt vmcnt(3)
	v_mov_b64_e32 v[42:43], v[2:3]
	v_mov_b64_e32 v[44:45], v[2:3]
	s_waitcnt vmcnt(2)
	v_mov_b64_e32 v[46:47], v[2:3]
	v_mov_b64_e32 v[48:49], v[2:3]
	v_mov_b64_e32 v[18:19], v[2:3]
	v_mov_b64_e32 v[20:21], v[2:3]
	v_mov_b64_e32 v[22:23], v[2:3]
	v_mov_b64_e32 v[24:25], v[2:3]
	v_mov_b64_e32 v[26:27], v[2:3]
	v_mov_b64_e32 v[28:29], v[2:3]
	v_mov_b64_e32 v[30:31], v[2:3]
	v_mov_b64_e32 v[32:33], v[2:3]
	s_waitcnt vmcnt(1)
	v_mov_b64_e32 v[50:51], v[2:3]
	v_mov_b64_e32 v[52:53], v[2:3]
	s_waitcnt vmcnt(0)
	v_mov_b64_e32 v[54:55], v[2:3]
	v_mov_b64_e32 v[56:57], v[2:3]
	v_mov_b64_e32 v[58:59], v[2:3]
	v_mov_b64_e32 v[60:61], v[2:3]
	v_mov_b64_e32 v[62:63], v[2:3]
	v_mov_b64_e32 v[64:65], v[2:3]
	v_mov_b64_e32 v[66:67], v[2:3]
	v_mov_b64_e32 v[68:69], v[2:3]
	v_mov_b64_e32 v[70:71], v[2:3]
	v_mov_b64_e32 v[72:73], v[2:3]
	v_mov_b64_e32 v[74:75], v[2:3]
	v_mov_b64_e32 v[76:77], v[2:3]
	v_mov_b64_e32 v[78:79], v[2:3]
	v_mov_b64_e32 v[80:81], v[2:3]
	v_mov_b64_e32 v[98:99], v[2:3]
	v_mov_b64_e32 v[100:101], v[2:3]
	v_mov_b64_e32 v[102:103], v[2:3]
	v_mov_b64_e32 v[104:105], v[2:3]
	v_mov_b64_e32 v[106:107], v[2:3]
	v_mov_b64_e32 v[108:109], v[2:3]
	v_mov_b64_e32 v[110:111], v[2:3]
	v_mov_b64_e32 v[112:113], v[2:3]
	v_mov_b64_e32 v[82:83], v[2:3]
	v_mov_b64_e32 v[84:85], v[2:3]
	v_mov_b64_e32 v[86:87], v[2:3]
	v_mov_b64_e32 v[88:89], v[2:3]
	v_mov_b64_e32 v[90:91], v[2:3]
	v_mov_b64_e32 v[92:93], v[2:3]
	v_mov_b64_e32 v[94:95], v[2:3]
	v_mov_b64_e32 v[96:97], v[2:3]
	v_mov_b64_e32 v[114:115], v[2:3]
	v_mov_b64_e32 v[116:117], v[2:3]
	v_mov_b64_e32 v[118:119], v[2:3]
	v_mov_b64_e32 v[120:121], v[2:3]
	v_mov_b64_e32 v[122:123], v[2:3]
	v_mov_b64_e32 v[124:125], v[2:3]
	v_mov_b64_e32 v[126:127], v[2:3]
	v_mov_b64_e32 v[128:129], v[2:3]
	v_add_u32_e32 v232, s91, v162
	v_add_u32_e32 v233, s1, v162
	v_add_u32_e32 v234, s76, v162
	v_add_u32_e32 v235, v178, v179
	v_add_u32_e32 v236, v178, v180
	v_add_u32_e32 v237, v181, v173
.LBB0_86:
	ds_read_b128 v[164:167], v235
	ds_read_b128 v[168:171], v235 offset:4608
	ds_read_b128 v[174:177], v236 offset:36864
	ds_read_b128 v[194:197], v236 offset:41472
	ds_read_b128 v[202:205], v236 offset:46080
	ds_read_b128 v[210:213], v236 offset:50688
	ds_read_b128 v[214:217], v184 offset:32
	ds_read_b128 v[218:221], v184 offset:4640
	s_add_i32 s35, s34, -3
	s_cmp_lt_u32 s35, 14
	s_cselect_b64 s[36:37], -1, 0
	s_and_b64 s[26:27], s[36:37], exec
	s_cselect_b32 s27, s11, s33
	s_cselect_b32 s26, s10, s31
	s_cselect_b32 s39, s9, s30
	s_cselect_b32 s38, s8, s29
	s_add_i32 s47, s34, -1
	s_waitcnt lgkmcnt(5)
	v_mfma_f32_32x32x16_bf16 v[114:129], v[174:177], v[164:167], v[114:129]
	v_mfma_f32_32x32x16_bf16 v[82:97], v[174:177], v[168:171], v[82:97]
	s_waitcnt lgkmcnt(4)
	v_mfma_f32_32x32x16_bf16 v[98:113], v[194:197], v[164:167], v[98:113]
	v_mfma_f32_32x32x16_bf16 v[66:81], v[194:197], v[168:171], v[66:81]
	s_waitcnt lgkmcnt(3)
	v_mfma_f32_32x32x16_bf16 v[50:65], v[202:205], v[164:167], v[50:65]
	s_and_b64 s[36:37], s[36:37], exec
	s_cselect_b32 s36, s47, s5
	v_mfma_f32_32x32x16_bf16 v[18:33], v[202:205], v[168:171], v[18:33]
	s_waitcnt lgkmcnt(2)
	v_mfma_f32_32x32x16_bf16 v[34:49], v[210:213], v[164:167], v[34:49]
	ds_read_b128 v[164:167], v185 offset:36896
	ds_read_b128 v[174:177], v185 offset:41504
	v_mfma_f32_32x32x16_bf16 v[2:17], v[210:213], v[168:171], v[2:17]
	s_lshl_b32 s96, s36, 7
	s_add_u32 s100, s38, s96
	s_addc_u32 s101, s39, 0
	s_waitcnt vmcnt(6)
	ds_write_b128 v186, v[142:145] offset:9216
	ds_write_b128 v186, v[134:137]
	global_load_dwordx4 v[134:137], v162, s[100:101]
	global_load_dwordx4 v[142:145], v232, s[100:101]
	s_waitcnt vmcnt(7)
	ds_write_b128 v186, v[130:133] offset:18432
	s_waitcnt vmcnt(6)
	ds_write_b128 v186, v[150:153] offset:27648
	global_load_dwordx4 v[130:133], v233, s[100:101]
	global_load_dwordx4 v[150:153], v234, s[100:101]
	ds_read_b128 v[168:171], v185 offset:46112
	ds_read_b128 v[194:197], v185 offset:50720
	ds_read_b128 v[202:205], v184 offset:64
	ds_read_b128 v[210:213], v184 offset:4672
	s_waitcnt lgkmcnt(9)
	v_mfma_f32_32x32x16_bf16 v[114:129], v[164:167], v[214:217], v[114:129]
	v_mfma_f32_32x32x16_bf16 v[82:97], v[164:167], v[218:221], v[82:97]
	s_waitcnt lgkmcnt(8)
	v_mfma_f32_32x32x16_bf16 v[98:113], v[174:177], v[214:217], v[98:113]
	v_mfma_f32_32x32x16_bf16 v[66:81], v[174:177], v[218:221], v[66:81]
	s_waitcnt lgkmcnt(3)
	v_mfma_f32_32x32x16_bf16 v[50:65], v[168:171], v[214:217], v[50:65]
	v_mfma_f32_32x32x16_bf16 v[18:33], v[168:171], v[218:221], v[18:33]
	ds_read_b128 v[164:167], v185 offset:36928
	ds_read_b128 v[168:171], v185 offset:41536
	s_waitcnt lgkmcnt(4)
; #define G_GLOAD(XR, WR, KT) { _Pragma("unroll") for (int i_ = 0; i_ < 4; ++i_) XR[i_] = *(const u32x4*)(Xt + ((size_t)(64 * i_) * ldx + (KT) * 64) * 2 + xoff); \
;     _Pragma("unroll") for (int i_ = 0; i_ < 4; ++i_) WR[i_] = *(const u32x4*)(Wtb + ((size_t)(64 * i_) * K + (KT) * 64) * 2 + woff); }
; #define G_LSTORE(XR, WR, STG) { char* xs_ = lds + (STG) * G_STAGE; char* ws_ = xs_ + G_XB; \
;     _Pragma("unroll") for (int i_ = 0; i_ < 4; ++i_) *(u32x4*)(xs_ + (lrow + 64 * i_) * LROW + lch * 16) = XR[i_]; \
;     _Pragma("unroll") for (int i_ = 0; i_ < 4; ++i_) *(u32x4*)(ws_ + (lrow + 64 * i_) * LROW + lch * 16) = WR[i_]; }
; template <class Epi>
; DI void gemm_phase(const bf16_t* __restrict__ X, const int ldx, const bf16_t* __restrict__ Wt, const int N, const int K, const Epi& epi, char* lds) {
;     ...
;     asm volatile("" ::: "memory");
;     if (Epi::kFull || chunk == xcd) {
;       G_GLOAD(xr0, wr0, 0);
;       G_LSTORE(xr0, wr0, 0);
;       __syncthreads();
;       G_GLOAD(xr0, wr0, 1);
;     }
; #pragma unroll
;     for (int c = 0; c < 2; ++c)
; #pragma unroll
;       for (int a = 0; a < 2; ++a)
; #pragma unroll
;         for (int b = 0; b < 2; ++b)
; #pragma unroll
;           for (int i = 0; i < 16; ++i) acc[c][a][b][i] = 0.f;
	v_mfma_f32_32x32x16_bf16 v[34:49], v[194:197], v[214:217], v[34:49]
	v_mfma_f32_32x32x16_bf16 v[2:17], v[194:197], v[218:221], v[2:17]
	s_add_u32 s100, s26, s96
	s_addc_u32 s101, s27, 0
	s_waitcnt vmcnt(6)
	ds_write_b128 v187, v[154:157] offset:9216
	ds_write_b128 v187, v[138:141]
	global_load_dwordx4 v[138:141], v162, s[100:101]
	global_load_dwordx4 v[154:157], v232, s[100:101]
	ds_read_b128 v[174:177], v185 offset:46144
	ds_read_b128 v[194:197], v185 offset:50752
	ds_read_b128 v[214:217], v184 offset:96
	ds_read_b128 v[218:221], v184 offset:4704
	s_waitcnt lgkmcnt(7)
	v_mfma_f32_32x32x16_bf16 v[114:129], v[164:167], v[202:205], v[114:129]
	v_mfma_f32_32x32x16_bf16 v[82:97], v[164:167], v[210:213], v[82:97]
	s_waitcnt lgkmcnt(6)
	v_mfma_f32_32x32x16_bf16 v[98:113], v[168:171], v[202:205], v[98:113]
	v_mfma_f32_32x32x16_bf16 v[66:81], v[168:171], v[210:213], v[66:81]
	s_waitcnt lgkmcnt(3)
	v_mfma_f32_32x32x16_bf16 v[50:65], v[174:177], v[202:205], v[50:65]
	ds_read_b128 v[164:167], v185 offset:36960
	ds_read_b128 v[168:171], v185 offset:41568
	v_mfma_f32_32x32x16_bf16 v[18:33], v[174:177], v[210:213], v[18:33]
	s_waitcnt lgkmcnt(4)
	v_mfma_f32_32x32x16_bf16 v[34:49], v[194:197], v[202:205], v[34:49]
	v_mfma_f32_32x32x16_bf16 v[2:17], v[194:197], v[210:213], v[2:17]
	s_waitcnt vmcnt(7)
	ds_write_b128 v187, v[146:149] offset:18432
	s_waitcnt vmcnt(6)
	ds_write_b128 v187, v[158:161] offset:27648
	global_load_dwordx4 v[146:149], v233, s[100:101]
	global_load_dwordx4 v[158:161], v234, s[100:101]
	ds_read_b128 v[174:177], v185 offset:46176
	ds_read_b128 v[194:197], v185 offset:50784
	s_waitcnt lgkmcnt(5)
	v_mfma_f32_32x32x16_bf16 v[114:129], v[164:167], v[214:217], v[114:129]
	v_mfma_f32_32x32x16_bf16 v[82:97], v[164:167], v[218:221], v[82:97]
	s_waitcnt lgkmcnt(4)
	v_mfma_f32_32x32x16_bf16 v[98:113], v[168:171], v[214:217], v[98:113]
	v_mfma_f32_32x32x16_bf16 v[66:81], v[168:171], v[218:221], v[66:81]
	s_waitcnt lgkmcnt(1)
	v_mfma_f32_32x32x16_bf16 v[50:65], v[174:177], v[214:217], v[50:65]
	v_mfma_f32_32x32x16_bf16 v[18:33], v[174:177], v[218:221], v[18:33]
	s_waitcnt lgkmcnt(0)
	v_mfma_f32_32x32x16_bf16 v[34:49], v[194:197], v[214:217], v[34:49]
	v_mfma_f32_32x32x16_bf16 v[2:17], v[194:197], v[218:221], v[2:17]
	s_barrier
	ds_read_b128 v[164:167], v188
	ds_read_b128 v[168:171], v188 offset:4608
	ds_read_b128 v[174:177], v189
	ds_read_b128 v[194:197], v189 offset:4608
	ds_read_b128 v[202:205], v189 offset:9216
	ds_read_b128 v[210:213], v189 offset:13824
	ds_read_b128 v[214:217], v237 offset:32
	ds_read_b128 v[218:221], v190 offset:32
	s_cmp_lt_u32 s35, 13
	s_cselect_b64 s[26:27], -1, 0
	s_and_b64 s[26:27], s[26:27], exec
	s_cselect_b32 s37, s9, s30
	s_cselect_b32 s36, s8, s29
	s_cselect_b32 s27, s11, s33
	s_cselect_b32 s26, s10, s31
	s_waitcnt lgkmcnt(5)
	v_mfma_f32_32x32x16_bf16 v[114:129], v[174:177], v[164:167], v[114:129]
	v_mfma_f32_32x32x16_bf16 v[82:97], v[174:177], v[168:171], v[82:97]
	s_waitcnt lgkmcnt(4)
	v_mfma_f32_32x32x16_bf16 v[98:113], v[194:197], v[164:167], v[98:113]
	v_mfma_f32_32x32x16_bf16 v[66:81], v[194:197], v[168:171], v[66:81]
	s_waitcnt lgkmcnt(3)
	v_mfma_f32_32x32x16_bf16 v[50:65], v[202:205], v[164:167], v[50:65]
	v_add_u32_e32 v172, v182, v173
	s_cselect_b32 s38, s34, s28
	v_mfma_f32_32x32x16_bf16 v[18:33], v[202:205], v[168:171], v[18:33]
	s_waitcnt lgkmcnt(2)
	v_mfma_f32_32x32x16_bf16 v[34:49], v[210:213], v[164:167], v[34:49]
	ds_read_b128 v[164:167], v172 offset:32
	ds_read_b128 v[174:177], v191 offset:32
	v_mfma_f32_32x32x16_bf16 v[2:17], v[210:213], v[168:171], v[2:17]
	s_lshl_b32 s96, s38, 7
	s_add_u32 s100, s36, s96
	s_addc_u32 s101, s37, 0
	s_waitcnt vmcnt(6)
	ds_write_b128 v183, v[142:145] offset:9216
	ds_write_b128 v183, v[134:137]
	global_load_dwordx4 v[134:137], v162, s[100:101]
	global_load_dwordx4 v[142:145], v232, s[100:101]
	s_waitcnt vmcnt(7)
	ds_write_b128 v183, v[130:133] offset:18432
	s_waitcnt vmcnt(6)
	ds_write_b128 v183, v[150:153] offset:27648
	global_load_dwordx4 v[130:133], v233, s[100:101]
	global_load_dwordx4 v[150:153], v234, s[100:101]
	ds_read_b128 v[168:171], v208 offset:32
	ds_read_b128 v[194:197], v209 offset:32
	ds_read_b128 v[202:205], v237 offset:64
	ds_read_b128 v[210:213], v190 offset:64
	s_waitcnt lgkmcnt(9)
	v_mfma_f32_32x32x16_bf16 v[114:129], v[164:167], v[214:217], v[114:129]
	v_mfma_f32_32x32x16_bf16 v[82:97], v[164:167], v[218:221], v[82:97]
	s_waitcnt lgkmcnt(8)
	v_mfma_f32_32x32x16_bf16 v[98:113], v[174:177], v[214:217], v[98:113]
	v_mfma_f32_32x32x16_bf16 v[66:81], v[174:177], v[218:221], v[66:81]
	s_waitcnt lgkmcnt(3)
	v_mfma_f32_32x32x16_bf16 v[50:65], v[168:171], v[214:217], v[50:65]
	v_mfma_f32_32x32x16_bf16 v[18:33], v[168:171], v[218:221], v[18:33]
	ds_read_b128 v[164:167], v172 offset:64
	ds_read_b128 v[168:171], v191 offset:64
	s_waitcnt lgkmcnt(4)
	v_mfma_f32_32x32x16_bf16 v[34:49], v[194:197], v[214:217], v[34:49]
	v_mfma_f32_32x32x16_bf16 v[2:17], v[194:197], v[218:221], v[2:17]
	s_add_u32 s100, s26, s96
	s_addc_u32 s101, s27, 0
	s_waitcnt vmcnt(6)
	ds_write_b128 v183, v[154:157] offset:46080
	ds_write_b128 v183, v[138:141] offset:36864
	global_load_dwordx4 v[138:141], v162, s[100:101]
	global_load_dwordx4 v[154:157], v232, s[100:101]
	ds_read_b128 v[174:177], v208 offset:64
	ds_read_b128 v[194:197], v209 offset:64
	ds_read_b128 v[214:217], v237 offset:96
	ds_read_b128 v[218:221], v190 offset:96
	s_waitcnt lgkmcnt(7)
	v_mfma_f32_32x32x16_bf16 v[114:129], v[164:167], v[202:205], v[114:129]
	v_mfma_f32_32x32x16_bf16 v[82:97], v[164:167], v[210:213], v[82:97]
	s_waitcnt lgkmcnt(6)
; #define G_GLOAD(XR, WR, KT) { _Pragma("unroll") for (int i_ = 0; i_ < 4; ++i_) XR[i_] = *(const u32x4*)(Xt + ((size_t)(64 * i_) * ldx + (KT) * 64) * 2 + xoff); \
;     _Pragma("unroll") for (int i_ = 0; i_ < 4; ++i_) WR[i_] = *(const u32x4*)(Wtb + ((size_t)(64 * i_) * K + (KT) * 64) * 2 + woff); }
; #define G_LSTORE(XR, WR, STG) { char* xs_ = lds + (STG) * G_STAGE; char* ws_ = xs_ + G_XB; \
;     _Pragma("unroll") for (int i_ = 0; i_ < 4; ++i_) *(u32x4*)(xs_ + (lrow + 64 * i_) * LROW + lch * 16) = XR[i_]; \
;     _Pragma("unroll") for (int i_ = 0; i_ < 4; ++i_) *(u32x4*)(ws_ + (lrow + 64 * i_) * LROW + lch * 16) = WR[i_]; }
; template <class Epi>
; DI void gemm_phase(const bf16_t* __restrict__ X, const int ldx, const bf16_t* __restrict__ Wt, const int N, const int K, const Epi& epi, char* lds) {
;     ...
;     asm volatile("" ::: "memory");
;     if (Epi::kFull || chunk == xcd) {
;       G_GLOAD(xr0, wr0, 0);
;       G_LSTORE(xr0, wr0, 0);
;       __syncthreads();
;       G_GLOAD(xr0, wr0, 1);
;     }
; #pragma unroll
;     for (int c = 0; c < 2; ++c)
; #pragma unroll
;       for (int a = 0; a < 2; ++a)
; #pragma unroll
;         for (int b = 0; b < 2; ++b)
; #pragma unroll
;           for (int i = 0; i < 16; ++i) acc[c][a][b][i] = 0.f;
;   DI void operator()(int tok0, int feat0, f32x16 (&acc)[2][2], int r, int hh) const {
;     ...
;       } else if (feat0 == 4096) {
;         if (hh == 0) {
; #pragma unroll
;           for (int i = 0; i < 16; ++i) {
;             const float xv = acc[0][mt][i] + bf[i];
;             const float ls = fminf(xv, 0.f) - log1pf(expf(-fabsf(xv)));
;             lf[((size_t)(b * 16 + i)) * SEQ + s] = ls;
;           }
;         }
	v_mfma_f32_32x32x16_bf16 v[98:113], v[168:171], v[202:205], v[98:113]
	v_mfma_f32_32x32x16_bf16 v[66:81], v[168:171], v[210:213], v[66:81]
	s_waitcnt lgkmcnt(3)
	v_mfma_f32_32x32x16_bf16 v[50:65], v[174:177], v[202:205], v[50:65]
	ds_read_b128 v[164:167], v172 offset:96
	ds_read_b128 v[168:171], v191 offset:96
	v_mfma_f32_32x32x16_bf16 v[18:33], v[174:177], v[210:213], v[18:33]
	s_waitcnt lgkmcnt(4)
	v_mfma_f32_32x32x16_bf16 v[34:49], v[194:197], v[202:205], v[34:49]
	v_mfma_f32_32x32x16_bf16 v[2:17], v[194:197], v[210:213], v[2:17]
	s_waitcnt vmcnt(7)
	ds_write_b128 v183, v[146:149] offset:55296
	s_waitcnt vmcnt(6)
	ds_write_b128 v183, v[158:161] offset:64512
	global_load_dwordx4 v[146:149], v233, s[100:101]
	global_load_dwordx4 v[158:161], v234, s[100:101]
	ds_read_b128 v[174:177], v208 offset:96
	ds_read_b128 v[194:197], v209 offset:96
	s_waitcnt lgkmcnt(5)
	v_mfma_f32_32x32x16_bf16 v[114:129], v[164:167], v[214:217], v[114:129]
	v_mfma_f32_32x32x16_bf16 v[82:97], v[164:167], v[218:221], v[82:97]
	s_waitcnt lgkmcnt(4)
	v_mfma_f32_32x32x16_bf16 v[98:113], v[168:171], v[214:217], v[98:113]
	v_mfma_f32_32x32x16_bf16 v[66:81], v[168:171], v[218:221], v[66:81]
	s_waitcnt lgkmcnt(1)
	v_mfma_f32_32x32x16_bf16 v[50:65], v[174:177], v[214:217], v[50:65]
	v_mfma_f32_32x32x16_bf16 v[18:33], v[174:177], v[218:221], v[18:33]
	s_waitcnt lgkmcnt(0)
	v_mfma_f32_32x32x16_bf16 v[34:49], v[194:197], v[214:217], v[34:49]
	v_mfma_f32_32x32x16_bf16 v[2:17], v[194:197], v[218:221], v[2:17]
	s_add_i32 s34, s34, 2
	s_cmp_gt_u32 s35, 13
	s_barrier
	s_cbranch_scc0 .LBB0_86
	v_mov_b32_e32 v212, v192
	s_ashr_i32 s47, s2, 14
	v_ashrrev_i32_e32 v164, 1, v212
	v_and_b32_e32 v164, 0xffffff80, v164
	v_bfe_u32 v0, v212, 5, 1
	v_add_u32_e32 v165, s3, v164
	s_movk_i32 s3, 0x1000
	v_ashrrev_i32_e32 v213, 10, v165
	v_and_b32_e32 v210, 0x380, v165
	v_and_b32_e32 v166, 0xdf, v212
	v_lshlrev_b32_e32 v211, 4, v0
	v_cmp_eq_u32_e32 vcc, s3, v165
	v_cmp_eq_u32_e64 s[10:11], 0, v0
	s_movk_i32 s3, 0x400
	v_mov_b32_e32 v0, s4
	v_or_b32_e32 v164, s4, v166
	v_cmp_lt_i32_e64 s[8:9], 1, v213
	v_or_b32_e32 v215, v210, v211
	s_and_b64 s[26:27], s[10:11], vcc
	v_cmp_gt_u32_e32 vcc, s3, v165
	v_bitop3_b32 v214, v166, s53, v0 bitop3:0xc8
	s_and_saveexec_b64 s[2:3], s[8:9]
	s_xor_b64 s[28:29], exec, s[2:3]
	s_cbranch_execz .LBB0_99
	v_cmp_lt_i32_e64 s[10:11], 2, v213
	s_and_saveexec_b64 s[2:3], s[10:11]
	s_xor_b64 s[30:31], exec, s[2:3]
	s_cbranch_execz .LBB0_96
	v_cmp_ne_u32_e64 s[10:11], 3, v213
	s_and_saveexec_b64 s[2:3], s[10:11]
	s_xor_b64 s[34:35], exec, s[2:3]
	s_cbranch_execz .LBB0_93
	s_and_saveexec_b64 s[36:37], s[26:27]
	s_cbranch_execz .LBB0_92
	v_lshlrev_b32_e32 v0, 2, v214
	v_lshl_add_u64 v[166:167], s[16:17], 0, v[0:1]
	global_load_dword v0, v1, s[18:19]
	v_mov_b32_e32 v197, 0x7f800000
	v_mov_b32_e32 v196, 0x3ecc95a3
	s_lshl_b32 s38, s47, 4
	s_ashr_i32 s39, s38, 31
	s_lshl_b64 s[2:3], s[38:39], 16
	s_waitcnt vmcnt(0)
	v_add_f32_e32 v0, v114, v0
	v_mul_f32_e64 v168, |v0|, s54
	v_fma_f32 v169, |v0|, s54, -v168
	v_rndne_f32_e32 v170, v168
	v_fma_f32 v169, |v0|, s55, v169
	v_sub_f32_e32 v168, v168, v170
	v_add_f32_e32 v168, v168, v169
	v_exp_f32_e32 v168, v168
	v_cvt_i32_f32_e32 v169, v170
	v_cmp_ngt_f32_e64 s[10:11], |v0|, s56
	v_min_f32_e32 v165, 0, v0
	v_ldexp_f32 v168, v168, v169
	v_cndmask_b32_e64 v168, 0, v168, s[10:11]
	v_cmp_nlt_f32_e64 s[10:11], |v0|, s57
	s_nop 1
	v_cndmask_b32_e64 v0, v197, v168, s[10:11]
	v_add_f32_e32 v170, 1.0, v0
	v_add_f32_e32 v168, -1.0, v170
	v_sub_f32_e32 v169, v168, v170
	v_add_f32_e32 v169, 1.0, v169
	v_sub_f32_e32 v168, v0, v168
	v_add_f32_e32 v171, v168, v169
	v_frexp_mant_f32_e32 v168, v170
	v_cmp_gt_f32_e64 s[10:11], s59, v168
	v_cvt_f64_f32_e32 v[168:169], v170
	v_frexp_exp_i32_f64_e32 v168, v[168:169]
	v_subbrev_co_u32_e64 v168, s[10:11], 0, v168, s[10:11]
	v_sub_u32_e32 v169, 0, v168
	v_ldexp_f32 v170, v170, v169
	v_ldexp_f32 v169, v171, v169
	v_add_f32_e32 v171, -1.0, v170
	v_add_f32_e32 v172, 1.0, v171
	v_sub_f32_e32 v172, v170, v172
	v_add_f32_e32 v172, v169, v172
	v_add_f32_e32 v174, v171, v172
	v_sub_f32_e32 v171, v171, v174
	v_add_f32_e32 v171, v172, v171
	v_add_f32_e32 v172, 1.0, v170
	v_add_f32_e32 v175, -1.0, v172
	v_sub_f32_e32 v170, v170, v175
	v_add_f32_e32 v169, v169, v170
	v_add_f32_e32 v170, v172, v169
	v_sub_f32_e32 v172, v172, v170
	v_add_f32_e32 v169, v169, v172
	v_rcp_f32_e32 v172, v170
	v_cvt_f32_i32_e32 v168, v168
	v_cmp_neq_f32_e64 s[10:11], s58, v0
	v_mul_f32_e32 v175, v174, v172
	v_mul_f32_e32 v176, v170, v175
	v_fma_f32 v177, v175, v170, -v176
	v_fmac_f32_e32 v177, v175, v169
	v_add_f32_e32 v194, v176, v177
	v_sub_f32_e32 v195, v174, v194
	v_sub_f32_e32 v174, v174, v195
	v_sub_f32_e32 v176, v194, v176
	v_sub_f32_e32 v174, v174, v194
	v_add_f32_e32 v171, v171, v174
	v_sub_f32_e32 v174, v176, v177
	v_add_f32_e32 v171, v174, v171
	v_add_f32_e32 v174, v195, v171
	v_mul_f32_e32 v176, v172, v174
	v_mul_f32_e32 v177, v170, v176
	v_fma_f32 v170, v176, v170, -v177
	v_fmac_f32_e32 v170, v176, v169
	v_sub_f32_e32 v169, v195, v174
	v_add_f32_e32 v169, v171, v169
	v_add_f32_e32 v171, v177, v170
	v_sub_f32_e32 v194, v174, v171
	v_sub_f32_e32 v174, v174, v194
	v_sub_f32_e32 v177, v171, v177
	v_sub_f32_e32 v171, v174, v171
	v_add_f32_e32 v169, v169, v171
	v_sub_f32_e32 v170, v177, v170
	v_add_f32_e32 v169, v170, v169
	v_add_f32_e32 v170, v175, v176
	v_add_f32_e32 v169, v194, v169
	v_sub_f32_e32 v171, v170, v175
	v_mul_f32_e32 v169, v172, v169
	v_sub_f32_e32 v171, v176, v171
	v_add_f32_e32 v169, v171, v169
	v_mul_f32_e32 v175, 0x3f317218, v168
	v_add_f32_e32 v171, v170, v169
	v_fma_f32 v176, v168, s60, -v175
	v_mul_f32_e32 v172, v171, v171
;   DI void operator()(int tok0, int feat0, f32x16 (&acc)[2][2], int r, int hh) const {
;     ...
;       } else if (feat0 == 4096) {
;         if (hh == 0) {
; #pragma unroll
;           for (int i = 0; i < 16; ++i) {
;             const float xv = acc[0][mt][i] + bf[i];
;             const float ls = fminf(xv, 0.f) - log1pf(expf(-fabsf(xv)));
;             lf[((size_t)(b * 16 + i)) * SEQ + s] = ls;
;           }
;         }
	v_fmac_f32_e32 v176, 0xb102e308, v168
	v_sub_f32_e32 v168, v171, v170
	v_fmamk_f32 v174, v172, 0x3e9b6dac, v196
	v_sub_f32_e32 v168, v169, v168
	v_add_f32_e32 v169, v175, v176
	v_fmaak_f32 v174, v172, v174, 0x3f2aaada
	v_sub_f32_e32 v170, v169, v175
	v_ldexp_f32 v175, v171, 1
	v_mul_f32_e32 v171, v171, v172
	v_mul_f32_e32 v171, v171, v174
	v_add_f32_e32 v172, v175, v171
	v_sub_f32_e32 v174, v172, v175
	v_ldexp_f32 v168, v168, 1
	v_sub_f32_e32 v171, v171, v174
	v_add_f32_e32 v168, v168, v171
	v_add_f32_e32 v171, v172, v168
	v_sub_f32_e32 v172, v171, v172
	v_sub_f32_e32 v168, v168, v172
	v_add_f32_e32 v172, v169, v171
	v_sub_f32_e32 v174, v172, v169
	v_sub_f32_e32 v175, v172, v174
	v_sub_f32_e32 v170, v176, v170
	v_sub_f32_e32 v169, v169, v175
	v_sub_f32_e32 v171, v171, v174
	v_add_f32_e32 v169, v171, v169
	v_add_f32_e32 v171, v170, v168
	v_sub_f32_e32 v174, v171, v170
	v_sub_f32_e32 v175, v171, v174
	v_sub_f32_e32 v170, v170, v175
	v_sub_f32_e32 v168, v168, v174
	v_add_f32_e32 v169, v171, v169
	v_add_f32_e32 v168, v168, v170
	v_add_f32_e32 v170, v172, v169
	v_sub_f32_e32 v171, v170, v172
	v_sub_f32_e32 v169, v169, v171
	v_add_f32_e32 v168, v168, v169
	v_add_f32_e32 v168, v170, v168
	v_cndmask_b32_e64 v168, v197, v168, s[10:11]
	v_cmp_lt_f32_e64 s[10:11], |v0|, s61
	s_nop 1
	v_cndmask_b32_e64 v0, v168, v0, s[10:11]
	v_sub_f32_e32 v0, v165, v0
	v_lshl_add_u64 v[168:169], v[166:167], 0, s[2:3]
	global_store_dword v[168:169], v0, off
	global_load_dword v0, v1, s[18:19] offset:4
	s_or_b32 s2, s38, 1
	s_ashr_i32 s3, s2, 31
	s_lshl_b64 s[2:3], s[2:3], 16
	s_waitcnt vmcnt(0)
	v_add_f32_e32 v0, v115, v0
	v_mul_f32_e64 v168, |v0|, s54
	v_fma_f32 v169, |v0|, s54, -v168
	v_rndne_f32_e32 v170, v168
	v_fma_f32 v169, |v0|, s55, v169
	v_sub_f32_e32 v168, v168, v170
	v_add_f32_e32 v168, v168, v169
	v_exp_f32_e32 v168, v168
	v_cvt_i32_f32_e32 v169, v170
	v_cmp_ngt_f32_e64 s[10:11], |v0|, s56
	v_min_f32_e32 v165, 0, v0
	v_ldexp_f32 v168, v168, v169
	v_cndmask_b32_e64 v168, 0, v168, s[10:11]
	v_cmp_nlt_f32_e64 s[10:11], |v0|, s57
	s_nop 1
	v_cndmask_b32_e64 v0, v197, v168, s[10:11]
	v_add_f32_e32 v170, 1.0, v0
	v_add_f32_e32 v168, -1.0, v170
	v_sub_f32_e32 v169, v168, v170
	v_add_f32_e32 v169, 1.0, v169
	v_sub_f32_e32 v168, v0, v168
	v_add_f32_e32 v171, v168, v169
	v_frexp_mant_f32_e32 v168, v170
	v_cmp_gt_f32_e64 s[10:11], s59, v168
	v_cvt_f64_f32_e32 v[168:169], v170
	v_frexp_exp_i32_f64_e32 v168, v[168:169]
	v_subbrev_co_u32_e64 v168, s[10:11], 0, v168, s[10:11]
	v_sub_u32_e32 v169, 0, v168
	v_ldexp_f32 v170, v170, v169
	v_ldexp_f32 v169, v171, v169
	v_add_f32_e32 v171, -1.0, v170
	v_add_f32_e32 v172, 1.0, v171
	v_sub_f32_e32 v172, v170, v172
	v_add_f32_e32 v172, v169, v172
	v_add_f32_e32 v174, v171, v172
	v_sub_f32_e32 v171, v171, v174
	v_add_f32_e32 v171, v172, v171
	v_add_f32_e32 v172, 1.0, v170
	v_add_f32_e32 v175, -1.0, v172
	v_sub_f32_e32 v170, v170, v175
	v_add_f32_e32 v169, v169, v170
	v_add_f32_e32 v170, v172, v169
	v_sub_f32_e32 v172, v172, v170
	v_add_f32_e32 v169, v169, v172
	v_rcp_f32_e32 v172, v170
	v_cvt_f32_i32_e32 v168, v168
	v_cmp_neq_f32_e64 s[10:11], s58, v0
	v_mul_f32_e32 v175, v174, v172
	v_mul_f32_e32 v176, v170, v175
	v_fma_f32 v177, v175, v170, -v176
	v_fmac_f32_e32 v177, v175, v169
	v_add_f32_e32 v194, v176, v177
	v_sub_f32_e32 v195, v174, v194
	v_sub_f32_e32 v174, v174, v195
	v_sub_f32_e32 v176, v194, v176
	v_sub_f32_e32 v174, v174, v194
	v_add_f32_e32 v171, v171, v174
	v_sub_f32_e32 v174, v176, v177
	v_add_f32_e32 v171, v174, v171
	v_add_f32_e32 v174, v195, v171
	v_mul_f32_e32 v176, v172, v174
	v_mul_f32_e32 v177, v170, v176
	v_fma_f32 v170, v176, v170, -v177
	v_fmac_f32_e32 v170, v176, v169
	v_sub_f32_e32 v169, v195, v174
	v_add_f32_e32 v169, v171, v169
	v_add_f32_e32 v171, v177, v170
	v_sub_f32_e32 v194, v174, v171
	v_sub_f32_e32 v174, v174, v194
	v_sub_f32_e32 v177, v171, v177
	v_sub_f32_e32 v171, v174, v171
	v_add_f32_e32 v169, v169, v171
	v_sub_f32_e32 v170, v177, v170
	v_add_f32_e32 v169, v170, v169
	v_add_f32_e32 v170, v175, v176
	v_add_f32_e32 v169, v194, v169
	v_sub_f32_e32 v171, v170, v175
	v_mul_f32_e32 v169, v172, v169
	v_sub_f32_e32 v171, v176, v171
	v_add_f32_e32 v169, v171, v169
	v_mul_f32_e32 v175, 0x3f317218, v168
	v_add_f32_e32 v171, v170, v169
	v_fma_f32 v176, v168, s60, -v175
	v_mul_f32_e32 v172, v171, v171
	v_fmac_f32_e32 v176, 0xb102e308, v168
	v_sub_f32_e32 v168, v171, v170
	v_fmamk_f32 v174, v172, 0x3e9b6dac, v196
	v_sub_f32_e32 v168, v169, v168
	v_add_f32_e32 v169, v175, v176
	v_fmaak_f32 v174, v172, v174, 0x3f2aaada
	v_sub_f32_e32 v170, v169, v175
	v_ldexp_f32 v175, v171, 1
	v_mul_f32_e32 v171, v171, v172
	v_mul_f32_e32 v171, v171, v174
	v_add_f32_e32 v172, v175, v171
	v_sub_f32_e32 v174, v172, v175
	v_ldexp_f32 v168, v168, 1
	v_sub_f32_e32 v171, v171, v174
	v_add_f32_e32 v168, v168, v171
	v_add_f32_e32 v171, v172, v168
	v_sub_f32_e32 v172, v171, v172
	v_sub_f32_e32 v168, v168, v172
	v_add_f32_e32 v172, v169, v171
	v_sub_f32_e32 v174, v172, v169
	v_sub_f32_e32 v175, v172, v174
	v_sub_f32_e32 v170, v176, v170
	v_sub_f32_e32 v169, v169, v175
	v_sub_f32_e32 v171, v171, v174
	v_add_f32_e32 v169, v171, v169
	v_add_f32_e32 v171, v170, v168
	v_sub_f32_e32 v174, v171, v170
	v_sub_f32_e32 v175, v171, v174
	v_sub_f32_e32 v170, v170, v175
	v_sub_f32_e32 v168, v168, v174
	v_add_f32_e32 v169, v171, v169
	v_add_f32_e32 v168, v168, v170
	v_add_f32_e32 v170, v172, v169
	v_sub_f32_e32 v171, v170, v172
	v_sub_f32_e32 v169, v169, v171
	v_add_f32_e32 v168, v168, v169
	v_add_f32_e32 v168, v170, v168
	v_cndmask_b32_e64 v168, v197, v168, s[10:11]
	v_cmp_lt_f32_e64 s[10:11], |v0|, s61
	s_nop 1
	v_cndmask_b32_e64 v0, v168, v0, s[10:11]
	v_sub_f32_e32 v0, v165, v0
	v_lshl_add_u64 v[168:169], v[166:167], 0, s[2:3]
	global_store_dword v[168:169], v0, off
	global_load_dword v0, v1, s[18:19] offset:8
	s_or_b32 s2, s38, 2
	s_ashr_i32 s3, s2, 31
	s_lshl_b64 s[2:3], s[2:3], 16
	s_waitcnt vmcnt(0)
;   DI void operator()(int tok0, int feat0, f32x16 (&acc)[2][2], int r, int hh) const {
;     ...
;       } else if (feat0 == 4096) {
;         if (hh == 0) {
; #pragma unroll
;           for (int i = 0; i < 16; ++i) {
;             const float xv = acc[0][mt][i] + bf[i];
;             const float ls = fminf(xv, 0.f) - log1pf(expf(-fabsf(xv)));
;             lf[((size_t)(b * 16 + i)) * SEQ + s] = ls;
;           }
;         }
	v_add_f32_e32 v0, v116, v0
	v_mul_f32_e64 v168, |v0|, s54
	v_fma_f32 v169, |v0|, s54, -v168
	v_rndne_f32_e32 v170, v168
	v_fma_f32 v169, |v0|, s55, v169
	v_sub_f32_e32 v168, v168, v170
	v_add_f32_e32 v168, v168, v169
	v_exp_f32_e32 v168, v168
	v_cvt_i32_f32_e32 v169, v170
	v_cmp_ngt_f32_e64 s[10:11], |v0|, s56
	v_min_f32_e32 v165, 0, v0
	v_ldexp_f32 v168, v168, v169
	v_cndmask_b32_e64 v168, 0, v168, s[10:11]
	v_cmp_nlt_f32_e64 s[10:11], |v0|, s57
	s_nop 1
	v_cndmask_b32_e64 v0, v197, v168, s[10:11]
	v_add_f32_e32 v170, 1.0, v0
	v_add_f32_e32 v168, -1.0, v170
	v_sub_f32_e32 v169, v168, v170
	v_add_f32_e32 v169, 1.0, v169
	v_sub_f32_e32 v168, v0, v168
	v_add_f32_e32 v171, v168, v169
	v_frexp_mant_f32_e32 v168, v170
	v_cmp_gt_f32_e64 s[10:11], s59, v168
	v_cvt_f64_f32_e32 v[168:169], v170
	v_frexp_exp_i32_f64_e32 v168, v[168:169]
	v_subbrev_co_u32_e64 v168, s[10:11], 0, v168, s[10:11]
	v_sub_u32_e32 v169, 0, v168
	v_ldexp_f32 v170, v170, v169
	v_ldexp_f32 v169, v171, v169
	v_add_f32_e32 v171, -1.0, v170
	v_add_f32_e32 v172, 1.0, v171
	v_sub_f32_e32 v172, v170, v172
	v_add_f32_e32 v172, v169, v172
	v_add_f32_e32 v174, v171, v172
	v_sub_f32_e32 v171, v171, v174
	v_add_f32_e32 v171, v172, v171
	v_add_f32_e32 v172, 1.0, v170
	v_add_f32_e32 v175, -1.0, v172
	v_sub_f32_e32 v170, v170, v175
	v_add_f32_e32 v169, v169, v170
	v_add_f32_e32 v170, v172, v169
	v_sub_f32_e32 v172, v172, v170
	v_add_f32_e32 v169, v169, v172
	v_rcp_f32_e32 v172, v170
	v_cvt_f32_i32_e32 v168, v168
	v_cmp_neq_f32_e64 s[10:11], s58, v0
	v_mul_f32_e32 v175, v174, v172
	v_mul_f32_e32 v176, v170, v175
	v_fma_f32 v177, v175, v170, -v176
	v_fmac_f32_e32 v177, v175, v169
	v_add_f32_e32 v194, v176, v177
	v_sub_f32_e32 v195, v174, v194
	v_sub_f32_e32 v174, v174, v195
	v_sub_f32_e32 v176, v194, v176
	v_sub_f32_e32 v174, v174, v194
	v_add_f32_e32 v171, v171, v174
	v_sub_f32_e32 v174, v176, v177
	v_add_f32_e32 v171, v174, v171
	v_add_f32_e32 v174, v195, v171
	v_mul_f32_e32 v176, v172, v174
	v_mul_f32_e32 v177, v170, v176
	v_fma_f32 v170, v176, v170, -v177
	v_fmac_f32_e32 v170, v176, v169
	v_sub_f32_e32 v169, v195, v174
	v_add_f32_e32 v169, v171, v169
	v_add_f32_e32 v171, v177, v170
	v_sub_f32_e32 v194, v174, v171
	v_sub_f32_e32 v174, v174, v194
	v_sub_f32_e32 v177, v171, v177
	v_sub_f32_e32 v171, v174, v171
	v_add_f32_e32 v169, v169, v171
	v_sub_f32_e32 v170, v177, v170
	v_add_f32_e32 v169, v170, v169
	v_add_f32_e32 v170, v175, v176
	v_add_f32_e32 v169, v194, v169
	v_sub_f32_e32 v171, v170, v175
	v_mul_f32_e32 v169, v172, v169
	v_sub_f32_e32 v171, v176, v171
	v_add_f32_e32 v169, v171, v169
	v_mul_f32_e32 v175, 0x3f317218, v168
	v_add_f32_e32 v171, v170, v169
	v_fma_f32 v176, v168, s60, -v175
	v_mul_f32_e32 v172, v171, v171
	v_fmac_f32_e32 v176, 0xb102e308, v168
	v_sub_f32_e32 v168, v171, v170
	v_fmamk_f32 v174, v172, 0x3e9b6dac, v196
	v_sub_f32_e32 v168, v169, v168
	v_add_f32_e32 v169, v175, v176
	v_fmaak_f32 v174, v172, v174, 0x3f2aaada
	v_sub_f32_e32 v170, v169, v175
	v_ldexp_f32 v175, v171, 1
	v_mul_f32_e32 v171, v171, v172
	v_mul_f32_e32 v171, v171, v174
	v_add_f32_e32 v172, v175, v171
	v_sub_f32_e32 v174, v172, v175
	v_ldexp_f32 v168, v168, 1
	v_sub_f32_e32 v171, v171, v174
	v_add_f32_e32 v168, v168, v171
	v_add_f32_e32 v171, v172, v168
	v_sub_f32_e32 v172, v171, v172
	v_sub_f32_e32 v168, v168, v172
	v_add_f32_e32 v172, v169, v171
	v_sub_f32_e32 v174, v172, v169
	v_sub_f32_e32 v175, v172, v174
	v_sub_f32_e32 v170, v176, v170
	v_sub_f32_e32 v169, v169, v175
	v_sub_f32_e32 v171, v171, v174
	v_add_f32_e32 v169, v171, v169
	v_add_f32_e32 v171, v170, v168
	v_sub_f32_e32 v174, v171, v170
	v_sub_f32_e32 v175, v171, v174
	v_sub_f32_e32 v170, v170, v175
	v_sub_f32_e32 v168, v168, v174
	v_add_f32_e32 v169, v171, v169
	v_add_f32_e32 v168, v168, v170
	v_add_f32_e32 v170, v172, v169
	v_sub_f32_e32 v171, v170, v172
	v_sub_f32_e32 v169, v169, v171
	v_add_f32_e32 v168, v168, v169
	v_add_f32_e32 v168, v170, v168
	v_cndmask_b32_e64 v168, v197, v168, s[10:11]
	v_cmp_lt_f32_e64 s[10:11], |v0|, s61
	s_nop 1
	v_cndmask_b32_e64 v0, v168, v0, s[10:11]
	v_sub_f32_e32 v0, v165, v0
	v_lshl_add_u64 v[168:169], v[166:167], 0, s[2:3]
	global_store_dword v[168:169], v0, off
	global_load_dword v0, v1, s[18:19] offset:12
	s_or_b32 s2, s38, 3
	s_ashr_i32 s3, s2, 31
	s_lshl_b64 s[2:3], s[2:3], 16
	s_waitcnt vmcnt(0)
;   DI void operator()(int tok0, int feat0, f32x16 (&acc)[2][2], int r, int hh) const {
;     ...
;       } else if (feat0 == 4096) {
;         if (hh == 0) {
; #pragma unroll
;           for (int i = 0; i < 16; ++i) {
;             const float xv = acc[0][mt][i] + bf[i];
;             const float ls = fminf(xv, 0.f) - log1pf(expf(-fabsf(xv)));
;             lf[((size_t)(b * 16 + i)) * SEQ + s] = ls;
;           }
;         }
	v_add_f32_e32 v0, v117, v0
	v_mul_f32_e64 v168, |v0|, s54
	v_fma_f32 v169, |v0|, s54, -v168
	v_rndne_f32_e32 v170, v168
	v_fma_f32 v169, |v0|, s55, v169
	v_sub_f32_e32 v168, v168, v170
	v_add_f32_e32 v168, v168, v169
	v_exp_f32_e32 v168, v168
	v_cvt_i32_f32_e32 v169, v170
	v_cmp_ngt_f32_e64 s[10:11], |v0|, s56
	v_min_f32_e32 v165, 0, v0
	v_ldexp_f32 v168, v168, v169
	v_cndmask_b32_e64 v168, 0, v168, s[10:11]
	v_cmp_nlt_f32_e64 s[10:11], |v0|, s57
	s_nop 1
	v_cndmask_b32_e64 v0, v197, v168, s[10:11]
	v_add_f32_e32 v170, 1.0, v0
	v_add_f32_e32 v168, -1.0, v170
	v_sub_f32_e32 v169, v168, v170
	v_add_f32_e32 v169, 1.0, v169
	v_sub_f32_e32 v168, v0, v168
	v_add_f32_e32 v171, v168, v169
	v_frexp_mant_f32_e32 v168, v170
	v_cmp_gt_f32_e64 s[10:11], s59, v168
	v_cvt_f64_f32_e32 v[168:169], v170
	v_frexp_exp_i32_f64_e32 v168, v[168:169]
	v_subbrev_co_u32_e64 v168, s[10:11], 0, v168, s[10:11]
	v_sub_u32_e32 v169, 0, v168
	v_ldexp_f32 v170, v170, v169
	v_ldexp_f32 v169, v171, v169
	v_add_f32_e32 v171, -1.0, v170
	v_add_f32_e32 v172, 1.0, v171
	v_sub_f32_e32 v172, v170, v172
	v_add_f32_e32 v172, v169, v172
	v_add_f32_e32 v174, v171, v172
	v_sub_f32_e32 v171, v171, v174
	v_add_f32_e32 v171, v172, v171
	v_add_f32_e32 v172, 1.0, v170
	v_add_f32_e32 v175, -1.0, v172
	v_sub_f32_e32 v170, v170, v175
	v_add_f32_e32 v169, v169, v170
	v_add_f32_e32 v170, v172, v169
	v_sub_f32_e32 v172, v172, v170
	v_add_f32_e32 v169, v169, v172
	v_rcp_f32_e32 v172, v170
	v_cvt_f32_i32_e32 v168, v168
	v_cmp_neq_f32_e64 s[10:11], s58, v0
	v_mul_f32_e32 v175, v174, v172
	v_mul_f32_e32 v176, v170, v175
	v_fma_f32 v177, v175, v170, -v176
	v_fmac_f32_e32 v177, v175, v169
	v_add_f32_e32 v194, v176, v177
	v_sub_f32_e32 v195, v174, v194
	v_sub_f32_e32 v174, v174, v195
	v_sub_f32_e32 v176, v194, v176
	v_sub_f32_e32 v174, v174, v194
	v_add_f32_e32 v171, v171, v174
	v_sub_f32_e32 v174, v176, v177
	v_add_f32_e32 v171, v174, v171
	v_add_f32_e32 v174, v195, v171
	v_mul_f32_e32 v176, v172, v174
	v_mul_f32_e32 v177, v170, v176
	v_fma_f32 v170, v176, v170, -v177
	v_fmac_f32_e32 v170, v176, v169
	v_sub_f32_e32 v169, v195, v174
	v_add_f32_e32 v169, v171, v169
	v_add_f32_e32 v171, v177, v170
	v_sub_f32_e32 v194, v174, v171
	v_sub_f32_e32 v174, v174, v194
	v_sub_f32_e32 v177, v171, v177
	v_sub_f32_e32 v171, v174, v171
	v_add_f32_e32 v169, v169, v171
	v_sub_f32_e32 v170, v177, v170
	v_add_f32_e32 v169, v170, v169
	v_add_f32_e32 v170, v175, v176
	v_add_f32_e32 v169, v194, v169
	v_sub_f32_e32 v171, v170, v175
	v_mul_f32_e32 v169, v172, v169
	v_sub_f32_e32 v171, v176, v171
	v_add_f32_e32 v169, v171, v169
	v_mul_f32_e32 v175, 0x3f317218, v168
	v_add_f32_e32 v171, v170, v169
	v_fma_f32 v176, v168, s60, -v175
	v_mul_f32_e32 v172, v171, v171
	v_fmac_f32_e32 v176, 0xb102e308, v168
	v_sub_f32_e32 v168, v171, v170
	v_fmamk_f32 v174, v172, 0x3e9b6dac, v196
	v_sub_f32_e32 v168, v169, v168
	v_add_f32_e32 v169, v175, v176
	v_fmaak_f32 v174, v172, v174, 0x3f2aaada
	v_sub_f32_e32 v170, v169, v175
	v_ldexp_f32 v175, v171, 1
	v_mul_f32_e32 v171, v171, v172
	v_mul_f32_e32 v171, v171, v174
	v_add_f32_e32 v172, v175, v171
	v_sub_f32_e32 v174, v172, v175
	v_ldexp_f32 v168, v168, 1
	v_sub_f32_e32 v171, v171, v174
	v_add_f32_e32 v168, v168, v171
	v_add_f32_e32 v171, v172, v168
	v_sub_f32_e32 v172, v171, v172
	v_sub_f32_e32 v168, v168, v172
	v_add_f32_e32 v172, v169, v171
	v_sub_f32_e32 v174, v172, v169
	v_sub_f32_e32 v175, v172, v174
	v_sub_f32_e32 v170, v176, v170
	v_sub_f32_e32 v169, v169, v175
	v_sub_f32_e32 v171, v171, v174
	v_add_f32_e32 v169, v171, v169
	v_add_f32_e32 v171, v170, v168
	v_sub_f32_e32 v174, v171, v170
	v_sub_f32_e32 v175, v171, v174
	v_sub_f32_e32 v170, v170, v175
	v_sub_f32_e32 v168, v168, v174
	v_add_f32_e32 v169, v171, v169
	v_add_f32_e32 v168, v168, v170
	v_add_f32_e32 v170, v172, v169
	v_sub_f32_e32 v171, v170, v172
	v_sub_f32_e32 v169, v169, v171
	v_add_f32_e32 v168, v168, v169
	v_add_f32_e32 v168, v170, v168
	v_cndmask_b32_e64 v168, v197, v168, s[10:11]
	v_cmp_lt_f32_e64 s[10:11], |v0|, s61
	s_nop 1
	v_cndmask_b32_e64 v0, v168, v0, s[10:11]
	v_sub_f32_e32 v0, v165, v0
	v_lshl_add_u64 v[168:169], v[166:167], 0, s[2:3]
	global_store_dword v[168:169], v0, off
	global_load_dword v0, v1, s[18:19] offset:16
	s_or_b32 s2, s38, 4
	s_ashr_i32 s3, s2, 31
	s_lshl_b64 s[2:3], s[2:3], 16
	s_waitcnt vmcnt(0)
;   DI void operator()(int tok0, int feat0, f32x16 (&acc)[2][2], int r, int hh) const {
;     ...
;       } else if (feat0 == 4096) {
;         if (hh == 0) {
; #pragma unroll
;           for (int i = 0; i < 16; ++i) {
;             const float xv = acc[0][mt][i] + bf[i];
;             const float ls = fminf(xv, 0.f) - log1pf(expf(-fabsf(xv)));
;             lf[((size_t)(b * 16 + i)) * SEQ + s] = ls;
;           }
;         }
	v_add_f32_e32 v0, v118, v0
	v_mul_f32_e64 v168, |v0|, s54
	v_fma_f32 v169, |v0|, s54, -v168
	v_rndne_f32_e32 v170, v168
	v_fma_f32 v169, |v0|, s55, v169
	v_sub_f32_e32 v168, v168, v170
	v_add_f32_e32 v168, v168, v169
	v_exp_f32_e32 v168, v168
	v_cvt_i32_f32_e32 v169, v170
	v_cmp_ngt_f32_e64 s[10:11], |v0|, s56
	v_min_f32_e32 v165, 0, v0
	v_ldexp_f32 v168, v168, v169
	v_cndmask_b32_e64 v168, 0, v168, s[10:11]
	v_cmp_nlt_f32_e64 s[10:11], |v0|, s57
	s_nop 1
	v_cndmask_b32_e64 v0, v197, v168, s[10:11]
	v_add_f32_e32 v170, 1.0, v0
	v_add_f32_e32 v168, -1.0, v170
	v_sub_f32_e32 v169, v168, v170
	v_add_f32_e32 v169, 1.0, v169
	v_sub_f32_e32 v168, v0, v168
	v_add_f32_e32 v171, v168, v169
	v_frexp_mant_f32_e32 v168, v170
	v_cmp_gt_f32_e64 s[10:11], s59, v168
	v_cvt_f64_f32_e32 v[168:169], v170
	v_frexp_exp_i32_f64_e32 v168, v[168:169]
	v_subbrev_co_u32_e64 v168, s[10:11], 0, v168, s[10:11]
	v_sub_u32_e32 v169, 0, v168
	v_ldexp_f32 v170, v170, v169
	v_ldexp_f32 v169, v171, v169
	v_add_f32_e32 v171, -1.0, v170
	v_add_f32_e32 v172, 1.0, v171
	v_sub_f32_e32 v172, v170, v172
	v_add_f32_e32 v172, v169, v172
	v_add_f32_e32 v174, v171, v172
	v_sub_f32_e32 v171, v171, v174
	v_add_f32_e32 v171, v172, v171
	v_add_f32_e32 v172, 1.0, v170
	v_add_f32_e32 v175, -1.0, v172
	v_sub_f32_e32 v170, v170, v175
	v_add_f32_e32 v169, v169, v170
	v_add_f32_e32 v170, v172, v169
	v_sub_f32_e32 v172, v172, v170
	v_add_f32_e32 v169, v169, v172
	v_rcp_f32_e32 v172, v170
	v_cvt_f32_i32_e32 v168, v168
	v_cmp_neq_f32_e64 s[10:11], s58, v0
	v_mul_f32_e32 v175, v174, v172
	v_mul_f32_e32 v176, v170, v175
	v_fma_f32 v177, v175, v170, -v176
	v_fmac_f32_e32 v177, v175, v169
	v_add_f32_e32 v194, v176, v177
	v_sub_f32_e32 v195, v174, v194
	v_sub_f32_e32 v174, v174, v195
	v_sub_f32_e32 v176, v194, v176
	v_sub_f32_e32 v174, v174, v194
	v_add_f32_e32 v171, v171, v174
	v_sub_f32_e32 v174, v176, v177
	v_add_f32_e32 v171, v174, v171
	v_add_f32_e32 v174, v195, v171
	v_mul_f32_e32 v176, v172, v174
	v_mul_f32_e32 v177, v170, v176
	v_fma_f32 v170, v176, v170, -v177
	v_fmac_f32_e32 v170, v176, v169
	v_sub_f32_e32 v169, v195, v174
	v_add_f32_e32 v169, v171, v169
	v_add_f32_e32 v171, v177, v170
	v_sub_f32_e32 v194, v174, v171
	v_sub_f32_e32 v174, v174, v194
	v_sub_f32_e32 v177, v171, v177
	v_sub_f32_e32 v171, v174, v171
	v_add_f32_e32 v169, v169, v171
	v_sub_f32_e32 v170, v177, v170
	v_add_f32_e32 v169, v170, v169
	v_add_f32_e32 v170, v175, v176
	v_add_f32_e32 v169, v194, v169
	v_sub_f32_e32 v171, v170, v175
	v_mul_f32_e32 v169, v172, v169
	v_sub_f32_e32 v171, v176, v171
	v_add_f32_e32 v169, v171, v169
	v_mul_f32_e32 v175, 0x3f317218, v168
	v_add_f32_e32 v171, v170, v169
	v_fma_f32 v176, v168, s60, -v175
	v_mul_f32_e32 v172, v171, v171
	v_fmac_f32_e32 v176, 0xb102e308, v168
	v_sub_f32_e32 v168, v171, v170
	v_fmamk_f32 v174, v172, 0x3e9b6dac, v196
	v_sub_f32_e32 v168, v169, v168
	v_add_f32_e32 v169, v175, v176
	v_fmaak_f32 v174, v172, v174, 0x3f2aaada
	v_sub_f32_e32 v170, v169, v175
	v_ldexp_f32 v175, v171, 1
	v_mul_f32_e32 v171, v171, v172
	v_mul_f32_e32 v171, v171, v174
	v_add_f32_e32 v172, v175, v171
	v_sub_f32_e32 v174, v172, v175
	v_ldexp_f32 v168, v168, 1
	v_sub_f32_e32 v171, v171, v174
	v_add_f32_e32 v168, v168, v171
	v_add_f32_e32 v171, v172, v168
	v_sub_f32_e32 v172, v171, v172
	v_sub_f32_e32 v168, v168, v172
	v_add_f32_e32 v172, v169, v171
	v_sub_f32_e32 v174, v172, v169
	v_sub_f32_e32 v175, v172, v174
	v_sub_f32_e32 v170, v176, v170
	v_sub_f32_e32 v169, v169, v175
	v_sub_f32_e32 v171, v171, v174
	v_add_f32_e32 v169, v171, v169
	v_add_f32_e32 v171, v170, v168
	v_sub_f32_e32 v174, v171, v170
	v_sub_f32_e32 v175, v171, v174
	v_sub_f32_e32 v170, v170, v175
	v_sub_f32_e32 v168, v168, v174
	v_add_f32_e32 v169, v171, v169
	v_add_f32_e32 v168, v168, v170
	v_add_f32_e32 v170, v172, v169
	v_sub_f32_e32 v171, v170, v172
	v_sub_f32_e32 v169, v169, v171
	v_add_f32_e32 v168, v168, v169
	v_add_f32_e32 v168, v170, v168
	v_cndmask_b32_e64 v168, v197, v168, s[10:11]
	v_cmp_lt_f32_e64 s[10:11], |v0|, s61
	s_nop 1
	v_cndmask_b32_e64 v0, v168, v0, s[10:11]
	v_sub_f32_e32 v0, v165, v0
	v_lshl_add_u64 v[168:169], v[166:167], 0, s[2:3]
	global_store_dword v[168:169], v0, off
	global_load_dword v0, v1, s[18:19] offset:20
	s_or_b32 s2, s38, 5
	s_ashr_i32 s3, s2, 31
	s_lshl_b64 s[2:3], s[2:3], 16
	s_waitcnt vmcnt(0)
;   DI void operator()(int tok0, int feat0, f32x16 (&acc)[2][2], int r, int hh) const {
;     ...
;       } else if (feat0 == 4096) {
;         if (hh == 0) {
; #pragma unroll
;           for (int i = 0; i < 16; ++i) {
;             const float xv = acc[0][mt][i] + bf[i];
;             const float ls = fminf(xv, 0.f) - log1pf(expf(-fabsf(xv)));
;             lf[((size_t)(b * 16 + i)) * SEQ + s] = ls;
;           }
;         }
	v_add_f32_e32 v0, v119, v0
	v_mul_f32_e64 v168, |v0|, s54
	v_fma_f32 v169, |v0|, s54, -v168
	v_rndne_f32_e32 v170, v168
	v_fma_f32 v169, |v0|, s55, v169
	v_sub_f32_e32 v168, v168, v170
	v_add_f32_e32 v168, v168, v169
	v_exp_f32_e32 v168, v168
	v_cvt_i32_f32_e32 v169, v170
	v_cmp_ngt_f32_e64 s[10:11], |v0|, s56
	v_min_f32_e32 v165, 0, v0
	v_ldexp_f32 v168, v168, v169
	v_cndmask_b32_e64 v168, 0, v168, s[10:11]
	v_cmp_nlt_f32_e64 s[10:11], |v0|, s57
	s_nop 1
	v_cndmask_b32_e64 v0, v197, v168, s[10:11]
	v_add_f32_e32 v170, 1.0, v0
	v_add_f32_e32 v168, -1.0, v170
	v_sub_f32_e32 v169, v168, v170
	v_add_f32_e32 v169, 1.0, v169
	v_sub_f32_e32 v168, v0, v168
	v_add_f32_e32 v171, v168, v169
	v_frexp_mant_f32_e32 v168, v170
	v_cmp_gt_f32_e64 s[10:11], s59, v168
	v_cvt_f64_f32_e32 v[168:169], v170
	v_frexp_exp_i32_f64_e32 v168, v[168:169]
	v_subbrev_co_u32_e64 v168, s[10:11], 0, v168, s[10:11]
	v_sub_u32_e32 v169, 0, v168
	v_ldexp_f32 v170, v170, v169
	v_ldexp_f32 v169, v171, v169
	v_add_f32_e32 v171, -1.0, v170
	v_add_f32_e32 v172, 1.0, v171
	v_sub_f32_e32 v172, v170, v172
	v_add_f32_e32 v172, v169, v172
	v_add_f32_e32 v174, v171, v172
	v_sub_f32_e32 v171, v171, v174
	v_add_f32_e32 v171, v172, v171
	v_add_f32_e32 v172, 1.0, v170
	v_add_f32_e32 v175, -1.0, v172
	v_sub_f32_e32 v170, v170, v175
	v_add_f32_e32 v169, v169, v170
	v_add_f32_e32 v170, v172, v169
	v_sub_f32_e32 v172, v172, v170
	v_add_f32_e32 v169, v169, v172
	v_rcp_f32_e32 v172, v170
	v_cvt_f32_i32_e32 v168, v168
	v_cmp_neq_f32_e64 s[10:11], s58, v0
	v_mul_f32_e32 v175, v174, v172
	v_mul_f32_e32 v176, v170, v175
	v_fma_f32 v177, v175, v170, -v176
	v_fmac_f32_e32 v177, v175, v169
	v_add_f32_e32 v194, v176, v177
	v_sub_f32_e32 v195, v174, v194
	v_sub_f32_e32 v174, v174, v195
	v_sub_f32_e32 v176, v194, v176
	v_sub_f32_e32 v174, v174, v194
	v_add_f32_e32 v171, v171, v174
	v_sub_f32_e32 v174, v176, v177
	v_add_f32_e32 v171, v174, v171
	v_add_f32_e32 v174, v195, v171
	v_mul_f32_e32 v176, v172, v174
	v_mul_f32_e32 v177, v170, v176
	v_fma_f32 v170, v176, v170, -v177
	v_fmac_f32_e32 v170, v176, v169
	v_sub_f32_e32 v169, v195, v174
	v_add_f32_e32 v169, v171, v169
	v_add_f32_e32 v171, v177, v170
	v_sub_f32_e32 v194, v174, v171
	v_sub_f32_e32 v174, v174, v194
	v_sub_f32_e32 v177, v171, v177
	v_sub_f32_e32 v171, v174, v171
	v_add_f32_e32 v169, v169, v171
	v_sub_f32_e32 v170, v177, v170
	v_add_f32_e32 v169, v170, v169
	v_add_f32_e32 v170, v175, v176
	v_add_f32_e32 v169, v194, v169
	v_sub_f32_e32 v171, v170, v175
	v_mul_f32_e32 v169, v172, v169
	v_sub_f32_e32 v171, v176, v171
	v_add_f32_e32 v169, v171, v169
	v_mul_f32_e32 v175, 0x3f317218, v168
	v_add_f32_e32 v171, v170, v169
	v_fma_f32 v176, v168, s60, -v175
	v_mul_f32_e32 v172, v171, v171
	v_fmac_f32_e32 v176, 0xb102e308, v168
	v_sub_f32_e32 v168, v171, v170
	v_fmamk_f32 v174, v172, 0x3e9b6dac, v196
	v_sub_f32_e32 v168, v169, v168
	v_add_f32_e32 v169, v175, v176
	v_fmaak_f32 v174, v172, v174, 0x3f2aaada
	v_sub_f32_e32 v170, v169, v175
	v_ldexp_f32 v175, v171, 1
	v_mul_f32_e32 v171, v171, v172
	v_mul_f32_e32 v171, v171, v174
	v_add_f32_e32 v172, v175, v171
	v_sub_f32_e32 v174, v172, v175
	v_ldexp_f32 v168, v168, 1
	v_sub_f32_e32 v171, v171, v174
	v_add_f32_e32 v168, v168, v171
	v_add_f32_e32 v171, v172, v168
	v_sub_f32_e32 v172, v171, v172
	v_sub_f32_e32 v168, v168, v172
	v_add_f32_e32 v172, v169, v171
	v_sub_f32_e32 v174, v172, v169
	v_sub_f32_e32 v175, v172, v174
	v_sub_f32_e32 v170, v176, v170
	v_sub_f32_e32 v169, v169, v175
	v_sub_f32_e32 v171, v171, v174
	v_add_f32_e32 v169, v171, v169
	v_add_f32_e32 v171, v170, v168
	v_sub_f32_e32 v174, v171, v170
	v_sub_f32_e32 v175, v171, v174
	v_sub_f32_e32 v170, v170, v175
	v_sub_f32_e32 v168, v168, v174
	v_add_f32_e32 v169, v171, v169
	v_add_f32_e32 v168, v168, v170
	v_add_f32_e32 v170, v172, v169
	v_sub_f32_e32 v171, v170, v172
	v_sub_f32_e32 v169, v169, v171
	v_add_f32_e32 v168, v168, v169
	v_add_f32_e32 v168, v170, v168
	v_cndmask_b32_e64 v168, v197, v168, s[10:11]
	v_cmp_lt_f32_e64 s[10:11], |v0|, s61
	s_nop 1
	v_cndmask_b32_e64 v0, v168, v0, s[10:11]
	v_sub_f32_e32 v0, v165, v0
	v_lshl_add_u64 v[168:169], v[166:167], 0, s[2:3]
	global_store_dword v[168:169], v0, off
	global_load_dword v0, v1, s[18:19] offset:24
	s_or_b32 s2, s38, 6
	s_ashr_i32 s3, s2, 31
	s_lshl_b64 s[2:3], s[2:3], 16
	s_waitcnt vmcnt(0)
;   DI void operator()(int tok0, int feat0, f32x16 (&acc)[2][2], int r, int hh) const {
;     ...
;       } else if (feat0 == 4096) {
;         if (hh == 0) {
; #pragma unroll
;           for (int i = 0; i < 16; ++i) {
;             const float xv = acc[0][mt][i] + bf[i];
;             const float ls = fminf(xv, 0.f) - log1pf(expf(-fabsf(xv)));
;             lf[((size_t)(b * 16 + i)) * SEQ + s] = ls;
;           }
;         }
	v_add_f32_e32 v0, v120, v0
	v_mul_f32_e64 v168, |v0|, s54
	v_fma_f32 v169, |v0|, s54, -v168
	v_rndne_f32_e32 v170, v168
	v_fma_f32 v169, |v0|, s55, v169
	v_sub_f32_e32 v168, v168, v170
	v_add_f32_e32 v168, v168, v169
	v_exp_f32_e32 v168, v168
	v_cvt_i32_f32_e32 v169, v170
	v_cmp_ngt_f32_e64 s[10:11], |v0|, s56
	v_min_f32_e32 v165, 0, v0
	v_ldexp_f32 v168, v168, v169
	v_cndmask_b32_e64 v168, 0, v168, s[10:11]
	v_cmp_nlt_f32_e64 s[10:11], |v0|, s57
	s_nop 1
	v_cndmask_b32_e64 v0, v197, v168, s[10:11]
	v_add_f32_e32 v170, 1.0, v0
	v_add_f32_e32 v168, -1.0, v170
	v_sub_f32_e32 v169, v168, v170
	v_add_f32_e32 v169, 1.0, v169
	v_sub_f32_e32 v168, v0, v168
	v_add_f32_e32 v171, v168, v169
	v_frexp_mant_f32_e32 v168, v170
	v_cmp_gt_f32_e64 s[10:11], s59, v168
	v_cvt_f64_f32_e32 v[168:169], v170
	v_frexp_exp_i32_f64_e32 v168, v[168:169]
	v_subbrev_co_u32_e64 v168, s[10:11], 0, v168, s[10:11]
	v_sub_u32_e32 v169, 0, v168
	v_ldexp_f32 v170, v170, v169
	v_ldexp_f32 v169, v171, v169
	v_add_f32_e32 v171, -1.0, v170
	v_add_f32_e32 v172, 1.0, v171
	v_sub_f32_e32 v172, v170, v172
	v_add_f32_e32 v172, v169, v172
	v_add_f32_e32 v174, v171, v172
	v_sub_f32_e32 v171, v171, v174
	v_add_f32_e32 v171, v172, v171
	v_add_f32_e32 v172, 1.0, v170
	v_add_f32_e32 v175, -1.0, v172
	v_sub_f32_e32 v170, v170, v175
	v_add_f32_e32 v169, v169, v170
	v_add_f32_e32 v170, v172, v169
	v_sub_f32_e32 v172, v172, v170
	v_add_f32_e32 v169, v169, v172
	v_rcp_f32_e32 v172, v170
	v_cvt_f32_i32_e32 v168, v168
	v_cmp_neq_f32_e64 s[10:11], s58, v0
	v_mul_f32_e32 v175, v174, v172
	v_mul_f32_e32 v176, v170, v175
	v_fma_f32 v177, v175, v170, -v176
	v_fmac_f32_e32 v177, v175, v169
	v_add_f32_e32 v194, v176, v177
	v_sub_f32_e32 v195, v174, v194
	v_sub_f32_e32 v174, v174, v195
	v_sub_f32_e32 v176, v194, v176
	v_sub_f32_e32 v174, v174, v194
	v_add_f32_e32 v171, v171, v174
	v_sub_f32_e32 v174, v176, v177
	v_add_f32_e32 v171, v174, v171
	v_add_f32_e32 v174, v195, v171
	v_mul_f32_e32 v176, v172, v174
	v_mul_f32_e32 v177, v170, v176
	v_fma_f32 v170, v176, v170, -v177
	v_fmac_f32_e32 v170, v176, v169
	v_sub_f32_e32 v169, v195, v174
	v_add_f32_e32 v169, v171, v169
	v_add_f32_e32 v171, v177, v170
	v_sub_f32_e32 v194, v174, v171
	v_sub_f32_e32 v174, v174, v194
	v_sub_f32_e32 v177, v171, v177
	v_sub_f32_e32 v171, v174, v171
	v_add_f32_e32 v169, v169, v171
	v_sub_f32_e32 v170, v177, v170
	v_add_f32_e32 v169, v170, v169
	v_add_f32_e32 v170, v175, v176
	v_add_f32_e32 v169, v194, v169
	v_sub_f32_e32 v171, v170, v175
	v_mul_f32_e32 v169, v172, v169
	v_sub_f32_e32 v171, v176, v171
	v_add_f32_e32 v169, v171, v169
	v_mul_f32_e32 v175, 0x3f317218, v168
	v_add_f32_e32 v171, v170, v169
	v_fma_f32 v176, v168, s60, -v175
	v_mul_f32_e32 v172, v171, v171
	v_fmac_f32_e32 v176, 0xb102e308, v168
	v_sub_f32_e32 v168, v171, v170
	v_fmamk_f32 v174, v172, 0x3e9b6dac, v196
	v_sub_f32_e32 v168, v169, v168
	v_add_f32_e32 v169, v175, v176
	v_fmaak_f32 v174, v172, v174, 0x3f2aaada
	v_sub_f32_e32 v170, v169, v175
	v_ldexp_f32 v175, v171, 1
	v_mul_f32_e32 v171, v171, v172
	v_mul_f32_e32 v171, v171, v174
	v_add_f32_e32 v172, v175, v171
	v_sub_f32_e32 v174, v172, v175
	v_ldexp_f32 v168, v168, 1
	v_sub_f32_e32 v171, v171, v174
	v_add_f32_e32 v168, v168, v171
	v_add_f32_e32 v171, v172, v168
	v_sub_f32_e32 v172, v171, v172
	v_sub_f32_e32 v168, v168, v172
	v_add_f32_e32 v172, v169, v171
	v_sub_f32_e32 v174, v172, v169
	v_sub_f32_e32 v175, v172, v174
	v_sub_f32_e32 v170, v176, v170
	v_sub_f32_e32 v169, v169, v175
	v_sub_f32_e32 v171, v171, v174
	v_add_f32_e32 v169, v171, v169
	v_add_f32_e32 v171, v170, v168
	v_sub_f32_e32 v174, v171, v170
	v_sub_f32_e32 v175, v171, v174
	v_sub_f32_e32 v170, v170, v175
	v_sub_f32_e32 v168, v168, v174
	v_add_f32_e32 v169, v171, v169
	v_add_f32_e32 v168, v168, v170
	v_add_f32_e32 v170, v172, v169
	v_sub_f32_e32 v171, v170, v172
	v_sub_f32_e32 v169, v169, v171
	v_add_f32_e32 v168, v168, v169
	v_add_f32_e32 v168, v170, v168
	v_cndmask_b32_e64 v168, v197, v168, s[10:11]
	v_cmp_lt_f32_e64 s[10:11], |v0|, s61
	s_nop 1
	v_cndmask_b32_e64 v0, v168, v0, s[10:11]
	v_sub_f32_e32 v0, v165, v0
	v_lshl_add_u64 v[168:169], v[166:167], 0, s[2:3]
	global_store_dword v[168:169], v0, off
	global_load_dword v0, v1, s[18:19] offset:28
	s_or_b32 s2, s38, 7
	s_ashr_i32 s3, s2, 31
	s_lshl_b64 s[2:3], s[2:3], 16
	s_waitcnt vmcnt(0)
;   DI void operator()(int tok0, int feat0, f32x16 (&acc)[2][2], int r, int hh) const {
;     ...
;       } else if (feat0 == 4096) {
;         if (hh == 0) {
; #pragma unroll
;           for (int i = 0; i < 16; ++i) {
;             const float xv = acc[0][mt][i] + bf[i];
;             const float ls = fminf(xv, 0.f) - log1pf(expf(-fabsf(xv)));
;             lf[((size_t)(b * 16 + i)) * SEQ + s] = ls;
;           }
;         }
	v_add_f32_e32 v0, v121, v0
	v_mul_f32_e64 v168, |v0|, s54
	v_fma_f32 v169, |v0|, s54, -v168
	v_rndne_f32_e32 v170, v168
	v_fma_f32 v169, |v0|, s55, v169
	v_sub_f32_e32 v168, v168, v170
	v_add_f32_e32 v168, v168, v169
	v_exp_f32_e32 v168, v168
	v_cvt_i32_f32_e32 v169, v170
	v_cmp_ngt_f32_e64 s[10:11], |v0|, s56
	v_min_f32_e32 v165, 0, v0
	v_ldexp_f32 v168, v168, v169
	v_cndmask_b32_e64 v168, 0, v168, s[10:11]
	v_cmp_nlt_f32_e64 s[10:11], |v0|, s57
	s_nop 1
	v_cndmask_b32_e64 v0, v197, v168, s[10:11]
	v_add_f32_e32 v170, 1.0, v0
	v_add_f32_e32 v168, -1.0, v170
	v_sub_f32_e32 v169, v168, v170
	v_add_f32_e32 v169, 1.0, v169
	v_sub_f32_e32 v168, v0, v168
	v_add_f32_e32 v171, v168, v169
	v_frexp_mant_f32_e32 v168, v170
	v_cmp_gt_f32_e64 s[10:11], s59, v168
	v_cvt_f64_f32_e32 v[168:169], v170
	v_frexp_exp_i32_f64_e32 v168, v[168:169]
	v_subbrev_co_u32_e64 v168, s[10:11], 0, v168, s[10:11]
	v_sub_u32_e32 v169, 0, v168
	v_ldexp_f32 v170, v170, v169
	v_ldexp_f32 v169, v171, v169
	v_add_f32_e32 v171, -1.0, v170
	v_add_f32_e32 v172, 1.0, v171
	v_sub_f32_e32 v172, v170, v172
	v_add_f32_e32 v172, v169, v172
	v_add_f32_e32 v174, v171, v172
	v_sub_f32_e32 v171, v171, v174
	v_add_f32_e32 v171, v172, v171
	v_add_f32_e32 v172, 1.0, v170
	v_add_f32_e32 v175, -1.0, v172
	v_sub_f32_e32 v170, v170, v175
	v_add_f32_e32 v169, v169, v170
	v_add_f32_e32 v170, v172, v169
	v_sub_f32_e32 v172, v172, v170
	v_add_f32_e32 v169, v169, v172
	v_rcp_f32_e32 v172, v170
	v_cvt_f32_i32_e32 v168, v168
	v_cmp_neq_f32_e64 s[10:11], s58, v0
	v_mul_f32_e32 v175, v174, v172
	v_mul_f32_e32 v176, v170, v175
	v_fma_f32 v177, v175, v170, -v176
	v_fmac_f32_e32 v177, v175, v169
	v_add_f32_e32 v194, v176, v177
	v_sub_f32_e32 v195, v174, v194
	v_sub_f32_e32 v174, v174, v195
	v_sub_f32_e32 v176, v194, v176
	v_sub_f32_e32 v174, v174, v194
	v_add_f32_e32 v171, v171, v174
	v_sub_f32_e32 v174, v176, v177
	v_add_f32_e32 v171, v174, v171
	v_add_f32_e32 v174, v195, v171
	v_mul_f32_e32 v176, v172, v174
	v_mul_f32_e32 v177, v170, v176
	v_fma_f32 v170, v176, v170, -v177
	v_fmac_f32_e32 v170, v176, v169
	v_sub_f32_e32 v169, v195, v174
	v_add_f32_e32 v169, v171, v169
	v_add_f32_e32 v171, v177, v170
	v_sub_f32_e32 v194, v174, v171
	v_sub_f32_e32 v174, v174, v194
	v_sub_f32_e32 v177, v171, v177
	v_sub_f32_e32 v171, v174, v171
	v_add_f32_e32 v169, v169, v171
	v_sub_f32_e32 v170, v177, v170
	v_add_f32_e32 v169, v170, v169
	v_add_f32_e32 v170, v175, v176
	v_add_f32_e32 v169, v194, v169
	v_sub_f32_e32 v171, v170, v175
	v_mul_f32_e32 v169, v172, v169
	v_sub_f32_e32 v171, v176, v171
	v_add_f32_e32 v169, v171, v169
	v_mul_f32_e32 v175, 0x3f317218, v168
	v_add_f32_e32 v171, v170, v169
	v_fma_f32 v176, v168, s60, -v175
	v_mul_f32_e32 v172, v171, v171
	v_fmac_f32_e32 v176, 0xb102e308, v168
	v_sub_f32_e32 v168, v171, v170
	v_fmamk_f32 v174, v172, 0x3e9b6dac, v196
	v_sub_f32_e32 v168, v169, v168
	v_add_f32_e32 v169, v175, v176
	v_fmaak_f32 v174, v172, v174, 0x3f2aaada
	v_sub_f32_e32 v170, v169, v175
	v_ldexp_f32 v175, v171, 1
	v_mul_f32_e32 v171, v171, v172
	v_mul_f32_e32 v171, v171, v174
	v_add_f32_e32 v172, v175, v171
	v_sub_f32_e32 v174, v172, v175
	v_ldexp_f32 v168, v168, 1
	v_sub_f32_e32 v171, v171, v174
	v_add_f32_e32 v168, v168, v171
	v_add_f32_e32 v171, v172, v168
	v_sub_f32_e32 v172, v171, v172
	v_sub_f32_e32 v168, v168, v172
	v_add_f32_e32 v172, v169, v171
	v_sub_f32_e32 v174, v172, v169
	v_sub_f32_e32 v175, v172, v174
	v_sub_f32_e32 v170, v176, v170
	v_sub_f32_e32 v169, v169, v175
	v_sub_f32_e32 v171, v171, v174
	v_add_f32_e32 v169, v171, v169
	v_add_f32_e32 v171, v170, v168
	v_sub_f32_e32 v174, v171, v170
	v_sub_f32_e32 v175, v171, v174
	v_sub_f32_e32 v170, v170, v175
	v_sub_f32_e32 v168, v168, v174
	v_add_f32_e32 v169, v171, v169
	v_add_f32_e32 v168, v168, v170
	v_add_f32_e32 v170, v172, v169
	v_sub_f32_e32 v171, v170, v172
	v_sub_f32_e32 v169, v169, v171
	v_add_f32_e32 v168, v168, v169
	v_add_f32_e32 v168, v170, v168
	v_cndmask_b32_e64 v168, v197, v168, s[10:11]
	v_cmp_lt_f32_e64 s[10:11], |v0|, s61
	s_nop 1
	v_cndmask_b32_e64 v0, v168, v0, s[10:11]
	v_sub_f32_e32 v0, v165, v0
	v_lshl_add_u64 v[168:169], v[166:167], 0, s[2:3]
	global_store_dword v[168:169], v0, off
	global_load_dword v0, v1, s[18:19] offset:32
	s_or_b32 s2, s38, 8
	s_ashr_i32 s3, s2, 31
	s_lshl_b64 s[2:3], s[2:3], 16
	s_waitcnt vmcnt(0)
;   DI void operator()(int tok0, int feat0, f32x16 (&acc)[2][2], int r, int hh) const {
;     ...
;       } else if (feat0 == 4096) {
;         if (hh == 0) {
; #pragma unroll
;           for (int i = 0; i < 16; ++i) {
;             const float xv = acc[0][mt][i] + bf[i];
;             const float ls = fminf(xv, 0.f) - log1pf(expf(-fabsf(xv)));
;             lf[((size_t)(b * 16 + i)) * SEQ + s] = ls;
;           }
;         }
	v_add_f32_e32 v0, v122, v0
	v_mul_f32_e64 v168, |v0|, s54
	v_fma_f32 v169, |v0|, s54, -v168
	v_rndne_f32_e32 v170, v168
	v_fma_f32 v169, |v0|, s55, v169
	v_sub_f32_e32 v168, v168, v170
	v_add_f32_e32 v168, v168, v169
	v_exp_f32_e32 v168, v168
	v_cvt_i32_f32_e32 v169, v170
	v_cmp_ngt_f32_e64 s[10:11], |v0|, s56
	v_min_f32_e32 v165, 0, v0
	v_ldexp_f32 v168, v168, v169
	v_cndmask_b32_e64 v168, 0, v168, s[10:11]
	v_cmp_nlt_f32_e64 s[10:11], |v0|, s57
	s_nop 1
	v_cndmask_b32_e64 v0, v197, v168, s[10:11]
	v_add_f32_e32 v170, 1.0, v0
	v_add_f32_e32 v168, -1.0, v170
	v_sub_f32_e32 v169, v168, v170
	v_add_f32_e32 v169, 1.0, v169
	v_sub_f32_e32 v168, v0, v168
	v_add_f32_e32 v171, v168, v169
	v_frexp_mant_f32_e32 v168, v170
	v_cmp_gt_f32_e64 s[10:11], s59, v168
	v_cvt_f64_f32_e32 v[168:169], v170
	v_frexp_exp_i32_f64_e32 v168, v[168:169]
	v_subbrev_co_u32_e64 v168, s[10:11], 0, v168, s[10:11]
	v_sub_u32_e32 v169, 0, v168
	v_ldexp_f32 v170, v170, v169
	v_ldexp_f32 v169, v171, v169
	v_add_f32_e32 v171, -1.0, v170
	v_add_f32_e32 v172, 1.0, v171
	v_sub_f32_e32 v172, v170, v172
	v_add_f32_e32 v172, v169, v172
	v_add_f32_e32 v174, v171, v172
	v_sub_f32_e32 v171, v171, v174
	v_add_f32_e32 v171, v172, v171
	v_add_f32_e32 v172, 1.0, v170
	v_add_f32_e32 v175, -1.0, v172
	v_sub_f32_e32 v170, v170, v175
	v_add_f32_e32 v169, v169, v170
	v_add_f32_e32 v170, v172, v169
	v_sub_f32_e32 v172, v172, v170
	v_add_f32_e32 v169, v169, v172
	v_rcp_f32_e32 v172, v170
	v_cvt_f32_i32_e32 v168, v168
	v_cmp_neq_f32_e64 s[10:11], s58, v0
	v_mul_f32_e32 v175, v174, v172
	v_mul_f32_e32 v176, v170, v175
	v_fma_f32 v177, v175, v170, -v176
	v_fmac_f32_e32 v177, v175, v169
	v_add_f32_e32 v194, v176, v177
	v_sub_f32_e32 v195, v174, v194
	v_sub_f32_e32 v174, v174, v195
	v_sub_f32_e32 v176, v194, v176
	v_sub_f32_e32 v174, v174, v194
	v_add_f32_e32 v171, v171, v174
	v_sub_f32_e32 v174, v176, v177
	v_add_f32_e32 v171, v174, v171
	v_add_f32_e32 v174, v195, v171
	v_mul_f32_e32 v176, v172, v174
	v_mul_f32_e32 v177, v170, v176
	v_fma_f32 v170, v176, v170, -v177
	v_fmac_f32_e32 v170, v176, v169
	v_sub_f32_e32 v169, v195, v174
	v_add_f32_e32 v169, v171, v169
	v_add_f32_e32 v171, v177, v170
	v_sub_f32_e32 v194, v174, v171
	v_sub_f32_e32 v174, v174, v194
	v_sub_f32_e32 v177, v171, v177
	v_sub_f32_e32 v171, v174, v171
	v_add_f32_e32 v169, v169, v171
	v_sub_f32_e32 v170, v177, v170
	v_add_f32_e32 v169, v170, v169
	v_add_f32_e32 v170, v175, v176
	v_add_f32_e32 v169, v194, v169
	v_sub_f32_e32 v171, v170, v175
	v_mul_f32_e32 v169, v172, v169
	v_sub_f32_e32 v171, v176, v171
	v_add_f32_e32 v169, v171, v169
	v_mul_f32_e32 v175, 0x3f317218, v168
	v_add_f32_e32 v171, v170, v169
	v_fma_f32 v176, v168, s60, -v175
	v_mul_f32_e32 v172, v171, v171
	v_fmac_f32_e32 v176, 0xb102e308, v168
	v_sub_f32_e32 v168, v171, v170
	v_fmamk_f32 v174, v172, 0x3e9b6dac, v196
	v_sub_f32_e32 v168, v169, v168
	v_add_f32_e32 v169, v175, v176
	v_fmaak_f32 v174, v172, v174, 0x3f2aaada
	v_sub_f32_e32 v170, v169, v175
	v_ldexp_f32 v175, v171, 1
	v_mul_f32_e32 v171, v171, v172
	v_mul_f32_e32 v171, v171, v174
	v_add_f32_e32 v172, v175, v171
	v_sub_f32_e32 v174, v172, v175
	v_ldexp_f32 v168, v168, 1
	v_sub_f32_e32 v171, v171, v174
	v_add_f32_e32 v168, v168, v171
	v_add_f32_e32 v171, v172, v168
	v_sub_f32_e32 v172, v171, v172
	v_sub_f32_e32 v168, v168, v172
	v_add_f32_e32 v172, v169, v171
	v_sub_f32_e32 v174, v172, v169
	v_sub_f32_e32 v175, v172, v174
	v_sub_f32_e32 v170, v176, v170
	v_sub_f32_e32 v169, v169, v175
	v_sub_f32_e32 v171, v171, v174
	v_add_f32_e32 v169, v171, v169
	v_add_f32_e32 v171, v170, v168
	v_sub_f32_e32 v174, v171, v170
	v_sub_f32_e32 v175, v171, v174
	v_sub_f32_e32 v170, v170, v175
	v_sub_f32_e32 v168, v168, v174
	v_add_f32_e32 v169, v171, v169
	v_add_f32_e32 v168, v168, v170
	v_add_f32_e32 v170, v172, v169
	v_sub_f32_e32 v171, v170, v172
	v_sub_f32_e32 v169, v169, v171
	v_add_f32_e32 v168, v168, v169
	v_add_f32_e32 v168, v170, v168
	v_cndmask_b32_e64 v168, v197, v168, s[10:11]
	v_cmp_lt_f32_e64 s[10:11], |v0|, s61
	s_nop 1
	v_cndmask_b32_e64 v0, v168, v0, s[10:11]
	v_sub_f32_e32 v0, v165, v0
	v_lshl_add_u64 v[168:169], v[166:167], 0, s[2:3]
	global_store_dword v[168:169], v0, off
	global_load_dword v0, v1, s[18:19] offset:36
	s_or_b32 s2, s38, 9
	s_ashr_i32 s3, s2, 31
	s_lshl_b64 s[2:3], s[2:3], 16
	s_waitcnt vmcnt(0)
;   DI void operator()(int tok0, int feat0, f32x16 (&acc)[2][2], int r, int hh) const {
;     ...
;       } else if (feat0 == 4096) {
;         if (hh == 0) {
; #pragma unroll
;           for (int i = 0; i < 16; ++i) {
;             const float xv = acc[0][mt][i] + bf[i];
;             const float ls = fminf(xv, 0.f) - log1pf(expf(-fabsf(xv)));
;             lf[((size_t)(b * 16 + i)) * SEQ + s] = ls;
;           }
;         }
	v_add_f32_e32 v0, v123, v0
	v_mul_f32_e64 v168, |v0|, s54
	v_fma_f32 v169, |v0|, s54, -v168
	v_rndne_f32_e32 v170, v168
	v_fma_f32 v169, |v0|, s55, v169
	v_sub_f32_e32 v168, v168, v170
	v_add_f32_e32 v168, v168, v169
	v_exp_f32_e32 v168, v168
	v_cvt_i32_f32_e32 v169, v170
	v_cmp_ngt_f32_e64 s[10:11], |v0|, s56
	v_min_f32_e32 v165, 0, v0
	v_ldexp_f32 v168, v168, v169
	v_cndmask_b32_e64 v168, 0, v168, s[10:11]
	v_cmp_nlt_f32_e64 s[10:11], |v0|, s57
	s_nop 1
	v_cndmask_b32_e64 v0, v197, v168, s[10:11]
	v_add_f32_e32 v170, 1.0, v0
	v_add_f32_e32 v168, -1.0, v170
	v_sub_f32_e32 v169, v168, v170
	v_add_f32_e32 v169, 1.0, v169
	v_sub_f32_e32 v168, v0, v168
	v_add_f32_e32 v171, v168, v169
	v_frexp_mant_f32_e32 v168, v170
	v_cmp_gt_f32_e64 s[10:11], s59, v168
	v_cvt_f64_f32_e32 v[168:169], v170
	v_frexp_exp_i32_f64_e32 v168, v[168:169]
	v_subbrev_co_u32_e64 v168, s[10:11], 0, v168, s[10:11]
	v_sub_u32_e32 v169, 0, v168
	v_ldexp_f32 v170, v170, v169
	v_ldexp_f32 v169, v171, v169
	v_add_f32_e32 v171, -1.0, v170
	v_add_f32_e32 v172, 1.0, v171
	v_sub_f32_e32 v172, v170, v172
	v_add_f32_e32 v172, v169, v172
	v_add_f32_e32 v174, v171, v172
	v_sub_f32_e32 v171, v171, v174
	v_add_f32_e32 v171, v172, v171
	v_add_f32_e32 v172, 1.0, v170
	v_add_f32_e32 v175, -1.0, v172
	v_sub_f32_e32 v170, v170, v175
	v_add_f32_e32 v169, v169, v170
	v_add_f32_e32 v170, v172, v169
	v_sub_f32_e32 v172, v172, v170
	v_add_f32_e32 v169, v169, v172
	v_rcp_f32_e32 v172, v170
	v_cvt_f32_i32_e32 v168, v168
	v_cmp_neq_f32_e64 s[10:11], s58, v0
	v_mul_f32_e32 v175, v174, v172
	v_mul_f32_e32 v176, v170, v175
	v_fma_f32 v177, v175, v170, -v176
	v_fmac_f32_e32 v177, v175, v169
	v_add_f32_e32 v194, v176, v177
	v_sub_f32_e32 v195, v174, v194
	v_sub_f32_e32 v174, v174, v195
	v_sub_f32_e32 v176, v194, v176
	v_sub_f32_e32 v174, v174, v194
	v_add_f32_e32 v171, v171, v174
	v_sub_f32_e32 v174, v176, v177
	v_add_f32_e32 v171, v174, v171
	v_add_f32_e32 v174, v195, v171
	v_mul_f32_e32 v176, v172, v174
	v_mul_f32_e32 v177, v170, v176
	v_fma_f32 v170, v176, v170, -v177
	v_fmac_f32_e32 v170, v176, v169
	v_sub_f32_e32 v169, v195, v174
	v_add_f32_e32 v169, v171, v169
	v_add_f32_e32 v171, v177, v170
	v_sub_f32_e32 v194, v174, v171
	v_sub_f32_e32 v174, v174, v194
	v_sub_f32_e32 v177, v171, v177
	v_sub_f32_e32 v171, v174, v171
	v_add_f32_e32 v169, v169, v171
	v_sub_f32_e32 v170, v177, v170
	v_add_f32_e32 v169, v170, v169
	v_add_f32_e32 v170, v175, v176
	v_add_f32_e32 v169, v194, v169
	v_sub_f32_e32 v171, v170, v175
	v_mul_f32_e32 v169, v172, v169
	v_sub_f32_e32 v171, v176, v171
	v_add_f32_e32 v169, v171, v169
	v_mul_f32_e32 v175, 0x3f317218, v168
	v_add_f32_e32 v171, v170, v169
	v_fma_f32 v176, v168, s60, -v175
	v_mul_f32_e32 v172, v171, v171
	v_fmac_f32_e32 v176, 0xb102e308, v168
	v_sub_f32_e32 v168, v171, v170
	v_fmamk_f32 v174, v172, 0x3e9b6dac, v196
	v_sub_f32_e32 v168, v169, v168
	v_add_f32_e32 v169, v175, v176
	v_fmaak_f32 v174, v172, v174, 0x3f2aaada
	v_sub_f32_e32 v170, v169, v175
	v_ldexp_f32 v175, v171, 1
	v_mul_f32_e32 v171, v171, v172
	v_mul_f32_e32 v171, v171, v174
	v_add_f32_e32 v172, v175, v171
	v_sub_f32_e32 v174, v172, v175
	v_ldexp_f32 v168, v168, 1
	v_sub_f32_e32 v171, v171, v174
	v_add_f32_e32 v168, v168, v171
	v_add_f32_e32 v171, v172, v168
	v_sub_f32_e32 v172, v171, v172
	v_sub_f32_e32 v168, v168, v172
	v_add_f32_e32 v172, v169, v171
	v_sub_f32_e32 v174, v172, v169
	v_sub_f32_e32 v175, v172, v174
	v_sub_f32_e32 v170, v176, v170
	v_sub_f32_e32 v169, v169, v175
	v_sub_f32_e32 v171, v171, v174
	v_add_f32_e32 v169, v171, v169
	v_add_f32_e32 v171, v170, v168
	v_sub_f32_e32 v174, v171, v170
	v_sub_f32_e32 v175, v171, v174
	v_sub_f32_e32 v170, v170, v175
	v_sub_f32_e32 v168, v168, v174
	v_add_f32_e32 v169, v171, v169
	v_add_f32_e32 v168, v168, v170
	v_add_f32_e32 v170, v172, v169
	v_sub_f32_e32 v171, v170, v172
	v_sub_f32_e32 v169, v169, v171
	v_add_f32_e32 v168, v168, v169
	v_add_f32_e32 v168, v170, v168
	v_cndmask_b32_e64 v168, v197, v168, s[10:11]
	v_cmp_lt_f32_e64 s[10:11], |v0|, s61
	s_nop 1
	v_cndmask_b32_e64 v0, v168, v0, s[10:11]
	v_sub_f32_e32 v0, v165, v0
	v_lshl_add_u64 v[168:169], v[166:167], 0, s[2:3]
	global_store_dword v[168:169], v0, off
	global_load_dword v0, v1, s[18:19] offset:40
	s_or_b32 s2, s38, 10
	s_ashr_i32 s3, s2, 31
	s_lshl_b64 s[2:3], s[2:3], 16
	s_waitcnt vmcnt(0)
;   DI void operator()(int tok0, int feat0, f32x16 (&acc)[2][2], int r, int hh) const {
;     ...
;       } else if (feat0 == 4096) {
;         if (hh == 0) {
; #pragma unroll
;           for (int i = 0; i < 16; ++i) {
;             const float xv = acc[0][mt][i] + bf[i];
;             const float ls = fminf(xv, 0.f) - log1pf(expf(-fabsf(xv)));
;             lf[((size_t)(b * 16 + i)) * SEQ + s] = ls;
;           }
;         }
	v_add_f32_e32 v0, v124, v0
	v_mul_f32_e64 v168, |v0|, s54
	v_fma_f32 v169, |v0|, s54, -v168
	v_rndne_f32_e32 v170, v168
	v_fma_f32 v169, |v0|, s55, v169
	v_sub_f32_e32 v168, v168, v170
	v_add_f32_e32 v168, v168, v169
	v_exp_f32_e32 v168, v168
	v_cvt_i32_f32_e32 v169, v170
	v_cmp_ngt_f32_e64 s[10:11], |v0|, s56
	v_min_f32_e32 v165, 0, v0
	v_ldexp_f32 v168, v168, v169
	v_cndmask_b32_e64 v168, 0, v168, s[10:11]
	v_cmp_nlt_f32_e64 s[10:11], |v0|, s57
	s_nop 1
	v_cndmask_b32_e64 v0, v197, v168, s[10:11]
	v_add_f32_e32 v170, 1.0, v0
	v_add_f32_e32 v168, -1.0, v170
	v_sub_f32_e32 v169, v168, v170
	v_add_f32_e32 v169, 1.0, v169
	v_sub_f32_e32 v168, v0, v168
	v_add_f32_e32 v171, v168, v169
	v_frexp_mant_f32_e32 v168, v170
	v_cmp_gt_f32_e64 s[10:11], s59, v168
	v_cvt_f64_f32_e32 v[168:169], v170
	v_frexp_exp_i32_f64_e32 v168, v[168:169]
	v_subbrev_co_u32_e64 v168, s[10:11], 0, v168, s[10:11]
	v_sub_u32_e32 v169, 0, v168
	v_ldexp_f32 v170, v170, v169
	v_ldexp_f32 v169, v171, v169
	v_add_f32_e32 v171, -1.0, v170
	v_add_f32_e32 v172, 1.0, v171
	v_sub_f32_e32 v172, v170, v172
	v_add_f32_e32 v172, v169, v172
	v_add_f32_e32 v174, v171, v172
	v_sub_f32_e32 v171, v171, v174
	v_add_f32_e32 v171, v172, v171
	v_add_f32_e32 v172, 1.0, v170
	v_add_f32_e32 v175, -1.0, v172
	v_sub_f32_e32 v170, v170, v175
	v_add_f32_e32 v169, v169, v170
	v_add_f32_e32 v170, v172, v169
	v_sub_f32_e32 v172, v172, v170
	v_add_f32_e32 v169, v169, v172
	v_rcp_f32_e32 v172, v170
	v_cvt_f32_i32_e32 v168, v168
	v_cmp_neq_f32_e64 s[10:11], s58, v0
	v_mul_f32_e32 v175, v174, v172
	v_mul_f32_e32 v176, v170, v175
	v_fma_f32 v177, v175, v170, -v176
	v_fmac_f32_e32 v177, v175, v169
	v_add_f32_e32 v194, v176, v177
	v_sub_f32_e32 v195, v174, v194
	v_sub_f32_e32 v174, v174, v195
	v_sub_f32_e32 v176, v194, v176
	v_sub_f32_e32 v174, v174, v194
	v_add_f32_e32 v171, v171, v174
	v_sub_f32_e32 v174, v176, v177
	v_add_f32_e32 v171, v174, v171
	v_add_f32_e32 v174, v195, v171
	v_mul_f32_e32 v176, v172, v174
	v_mul_f32_e32 v177, v170, v176
	v_fma_f32 v170, v176, v170, -v177
	v_fmac_f32_e32 v170, v176, v169
	v_sub_f32_e32 v169, v195, v174
	v_add_f32_e32 v169, v171, v169
	v_add_f32_e32 v171, v177, v170
	v_sub_f32_e32 v194, v174, v171
	v_sub_f32_e32 v174, v174, v194
	v_sub_f32_e32 v177, v171, v177
	v_sub_f32_e32 v171, v174, v171
	v_add_f32_e32 v169, v169, v171
	v_sub_f32_e32 v170, v177, v170
	v_add_f32_e32 v169, v170, v169
	v_add_f32_e32 v170, v175, v176
	v_add_f32_e32 v169, v194, v169
	v_sub_f32_e32 v171, v170, v175
	v_mul_f32_e32 v169, v172, v169
	v_sub_f32_e32 v171, v176, v171
	v_add_f32_e32 v169, v171, v169
	v_mul_f32_e32 v175, 0x3f317218, v168
	v_add_f32_e32 v171, v170, v169
	v_fma_f32 v176, v168, s60, -v175
	v_mul_f32_e32 v172, v171, v171
	v_fmac_f32_e32 v176, 0xb102e308, v168
	v_sub_f32_e32 v168, v171, v170
	v_fmamk_f32 v174, v172, 0x3e9b6dac, v196
	v_sub_f32_e32 v168, v169, v168
	v_add_f32_e32 v169, v175, v176
	v_fmaak_f32 v174, v172, v174, 0x3f2aaada
	v_sub_f32_e32 v170, v169, v175
	v_ldexp_f32 v175, v171, 1
	v_mul_f32_e32 v171, v171, v172
	v_mul_f32_e32 v171, v171, v174
	v_add_f32_e32 v172, v175, v171
	v_sub_f32_e32 v174, v172, v175
	v_ldexp_f32 v168, v168, 1
	v_sub_f32_e32 v171, v171, v174
	v_add_f32_e32 v168, v168, v171
	v_add_f32_e32 v171, v172, v168
	v_sub_f32_e32 v172, v171, v172
	v_sub_f32_e32 v168, v168, v172
	v_add_f32_e32 v172, v169, v171
	v_sub_f32_e32 v174, v172, v169
	v_sub_f32_e32 v175, v172, v174
	v_sub_f32_e32 v170, v176, v170
	v_sub_f32_e32 v169, v169, v175
	v_sub_f32_e32 v171, v171, v174
	v_add_f32_e32 v169, v171, v169
	v_add_f32_e32 v171, v170, v168
	v_sub_f32_e32 v174, v171, v170
	v_sub_f32_e32 v175, v171, v174
	v_sub_f32_e32 v170, v170, v175
	v_sub_f32_e32 v168, v168, v174
	v_add_f32_e32 v169, v171, v169
	v_add_f32_e32 v168, v168, v170
	v_add_f32_e32 v170, v172, v169
	v_sub_f32_e32 v171, v170, v172
	v_sub_f32_e32 v169, v169, v171
	v_add_f32_e32 v168, v168, v169
	v_add_f32_e32 v168, v170, v168
	v_cndmask_b32_e64 v168, v197, v168, s[10:11]
	v_cmp_lt_f32_e64 s[10:11], |v0|, s61
	s_nop 1
	v_cndmask_b32_e64 v0, v168, v0, s[10:11]
	v_sub_f32_e32 v0, v165, v0
	v_lshl_add_u64 v[168:169], v[166:167], 0, s[2:3]
	global_store_dword v[168:169], v0, off
	global_load_dword v0, v1, s[18:19] offset:44
	s_or_b32 s2, s38, 11
	s_ashr_i32 s3, s2, 31
	s_lshl_b64 s[2:3], s[2:3], 16
	s_waitcnt vmcnt(0)
;   DI void operator()(int tok0, int feat0, f32x16 (&acc)[2][2], int r, int hh) const {
;     ...
;       } else if (feat0 == 4096) {
;         if (hh == 0) {
; #pragma unroll
;           for (int i = 0; i < 16; ++i) {
;             const float xv = acc[0][mt][i] + bf[i];
;             const float ls = fminf(xv, 0.f) - log1pf(expf(-fabsf(xv)));
;             lf[((size_t)(b * 16 + i)) * SEQ + s] = ls;
;           }
;         }
	v_add_f32_e32 v0, v125, v0
	v_mul_f32_e64 v168, |v0|, s54
	v_fma_f32 v169, |v0|, s54, -v168
	v_rndne_f32_e32 v170, v168
	v_fma_f32 v169, |v0|, s55, v169
	v_sub_f32_e32 v168, v168, v170
	v_add_f32_e32 v168, v168, v169
	v_exp_f32_e32 v168, v168
	v_cvt_i32_f32_e32 v169, v170
	v_cmp_ngt_f32_e64 s[10:11], |v0|, s56
	v_min_f32_e32 v165, 0, v0
	v_ldexp_f32 v168, v168, v169
	v_cndmask_b32_e64 v168, 0, v168, s[10:11]
	v_cmp_nlt_f32_e64 s[10:11], |v0|, s57
	s_nop 1
	v_cndmask_b32_e64 v0, v197, v168, s[10:11]
	v_add_f32_e32 v170, 1.0, v0
	v_add_f32_e32 v168, -1.0, v170
	v_sub_f32_e32 v169, v168, v170
	v_add_f32_e32 v169, 1.0, v169
	v_sub_f32_e32 v168, v0, v168
	v_add_f32_e32 v171, v168, v169
	v_frexp_mant_f32_e32 v168, v170
	v_cmp_gt_f32_e64 s[10:11], s59, v168
	v_cvt_f64_f32_e32 v[168:169], v170
	v_frexp_exp_i32_f64_e32 v168, v[168:169]
	v_subbrev_co_u32_e64 v168, s[10:11], 0, v168, s[10:11]
	v_sub_u32_e32 v169, 0, v168
	v_ldexp_f32 v170, v170, v169
	v_ldexp_f32 v169, v171, v169
	v_add_f32_e32 v171, -1.0, v170
	v_add_f32_e32 v172, 1.0, v171
	v_sub_f32_e32 v172, v170, v172
	v_add_f32_e32 v172, v169, v172
	v_add_f32_e32 v174, v171, v172
	v_sub_f32_e32 v171, v171, v174
	v_add_f32_e32 v171, v172, v171
	v_add_f32_e32 v172, 1.0, v170
	v_add_f32_e32 v175, -1.0, v172
	v_sub_f32_e32 v170, v170, v175
	v_add_f32_e32 v169, v169, v170
	v_add_f32_e32 v170, v172, v169
	v_sub_f32_e32 v172, v172, v170
	v_add_f32_e32 v169, v169, v172
	v_rcp_f32_e32 v172, v170
	v_cvt_f32_i32_e32 v168, v168
	v_cmp_neq_f32_e64 s[10:11], s58, v0
	v_mul_f32_e32 v175, v174, v172
	v_mul_f32_e32 v176, v170, v175
	v_fma_f32 v177, v175, v170, -v176
	v_fmac_f32_e32 v177, v175, v169
	v_add_f32_e32 v194, v176, v177
	v_sub_f32_e32 v195, v174, v194
	v_sub_f32_e32 v174, v174, v195
	v_sub_f32_e32 v176, v194, v176
	v_sub_f32_e32 v174, v174, v194
	v_add_f32_e32 v171, v171, v174
	v_sub_f32_e32 v174, v176, v177
	v_add_f32_e32 v171, v174, v171
	v_add_f32_e32 v174, v195, v171
	v_mul_f32_e32 v176, v172, v174
	v_mul_f32_e32 v177, v170, v176
	v_fma_f32 v170, v176, v170, -v177
	v_fmac_f32_e32 v170, v176, v169
	v_sub_f32_e32 v169, v195, v174
	v_add_f32_e32 v169, v171, v169
	v_add_f32_e32 v171, v177, v170
	v_sub_f32_e32 v194, v174, v171
	v_sub_f32_e32 v174, v174, v194
	v_sub_f32_e32 v177, v171, v177
	v_sub_f32_e32 v171, v174, v171
	v_add_f32_e32 v169, v169, v171
	v_sub_f32_e32 v170, v177, v170
	v_add_f32_e32 v169, v170, v169
	v_add_f32_e32 v170, v175, v176
	v_add_f32_e32 v169, v194, v169
	v_sub_f32_e32 v171, v170, v175
	v_mul_f32_e32 v169, v172, v169
	v_sub_f32_e32 v171, v176, v171
	v_add_f32_e32 v169, v171, v169
	v_mul_f32_e32 v175, 0x3f317218, v168
	v_add_f32_e32 v171, v170, v169
	v_fma_f32 v176, v168, s60, -v175
	v_mul_f32_e32 v172, v171, v171
	v_fmac_f32_e32 v176, 0xb102e308, v168
	v_sub_f32_e32 v168, v171, v170
	v_fmamk_f32 v174, v172, 0x3e9b6dac, v196
	v_sub_f32_e32 v168, v169, v168
	v_add_f32_e32 v169, v175, v176
	v_fmaak_f32 v174, v172, v174, 0x3f2aaada
	v_sub_f32_e32 v170, v169, v175
	v_ldexp_f32 v175, v171, 1
	v_mul_f32_e32 v171, v171, v172
	v_mul_f32_e32 v171, v171, v174
	v_add_f32_e32 v172, v175, v171
	v_sub_f32_e32 v174, v172, v175
	v_ldexp_f32 v168, v168, 1
	v_sub_f32_e32 v171, v171, v174
	v_add_f32_e32 v168, v168, v171
	v_add_f32_e32 v171, v172, v168
	v_sub_f32_e32 v172, v171, v172
	v_sub_f32_e32 v168, v168, v172
	v_add_f32_e32 v172, v169, v171
	v_sub_f32_e32 v174, v172, v169
	v_sub_f32_e32 v175, v172, v174
	v_sub_f32_e32 v170, v176, v170
	v_sub_f32_e32 v169, v169, v175
	v_sub_f32_e32 v171, v171, v174
	v_add_f32_e32 v169, v171, v169
	v_add_f32_e32 v171, v170, v168
	v_sub_f32_e32 v174, v171, v170
	v_sub_f32_e32 v175, v171, v174
	v_sub_f32_e32 v170, v170, v175
	v_sub_f32_e32 v168, v168, v174
	v_add_f32_e32 v169, v171, v169
	v_add_f32_e32 v168, v168, v170
	v_add_f32_e32 v170, v172, v169
	v_sub_f32_e32 v171, v170, v172
	v_sub_f32_e32 v169, v169, v171
	v_add_f32_e32 v168, v168, v169
	v_add_f32_e32 v168, v170, v168
	v_cndmask_b32_e64 v168, v197, v168, s[10:11]
	v_cmp_lt_f32_e64 s[10:11], |v0|, s61
	s_nop 1
	v_cndmask_b32_e64 v0, v168, v0, s[10:11]
	v_sub_f32_e32 v0, v165, v0
	v_lshl_add_u64 v[168:169], v[166:167], 0, s[2:3]
	global_store_dword v[168:169], v0, off
	global_load_dword v0, v1, s[18:19] offset:48
	s_or_b32 s2, s38, 12
	s_ashr_i32 s3, s2, 31
	s_lshl_b64 s[2:3], s[2:3], 16
	s_waitcnt vmcnt(0)
;   DI void operator()(int tok0, int feat0, f32x16 (&acc)[2][2], int r, int hh) const {
;     ...
;       } else if (feat0 == 4096) {
;         if (hh == 0) {
; #pragma unroll
;           for (int i = 0; i < 16; ++i) {
;             const float xv = acc[0][mt][i] + bf[i];
;             const float ls = fminf(xv, 0.f) - log1pf(expf(-fabsf(xv)));
;             lf[((size_t)(b * 16 + i)) * SEQ + s] = ls;
;           }
;         }
	v_add_f32_e32 v0, v126, v0
	v_mul_f32_e64 v168, |v0|, s54
	v_fma_f32 v169, |v0|, s54, -v168
	v_rndne_f32_e32 v170, v168
	v_fma_f32 v169, |v0|, s55, v169
	v_sub_f32_e32 v168, v168, v170
	v_add_f32_e32 v168, v168, v169
	v_exp_f32_e32 v168, v168
	v_cvt_i32_f32_e32 v169, v170
	v_cmp_ngt_f32_e64 s[10:11], |v0|, s56
	v_min_f32_e32 v165, 0, v0
	v_ldexp_f32 v168, v168, v169
	v_cndmask_b32_e64 v168, 0, v168, s[10:11]
	v_cmp_nlt_f32_e64 s[10:11], |v0|, s57
	s_nop 1
	v_cndmask_b32_e64 v0, v197, v168, s[10:11]
	v_add_f32_e32 v170, 1.0, v0
	v_add_f32_e32 v168, -1.0, v170
	v_sub_f32_e32 v169, v168, v170
	v_add_f32_e32 v169, 1.0, v169
	v_sub_f32_e32 v168, v0, v168
	v_add_f32_e32 v171, v168, v169
	v_frexp_mant_f32_e32 v168, v170
	v_cmp_gt_f32_e64 s[10:11], s59, v168
	v_cvt_f64_f32_e32 v[168:169], v170
	v_frexp_exp_i32_f64_e32 v168, v[168:169]
	v_subbrev_co_u32_e64 v168, s[10:11], 0, v168, s[10:11]
	v_sub_u32_e32 v169, 0, v168
	v_ldexp_f32 v170, v170, v169
	v_ldexp_f32 v169, v171, v169
	v_add_f32_e32 v171, -1.0, v170
	v_add_f32_e32 v172, 1.0, v171
	v_sub_f32_e32 v172, v170, v172
	v_add_f32_e32 v172, v169, v172
	v_add_f32_e32 v174, v171, v172
	v_sub_f32_e32 v171, v171, v174
	v_add_f32_e32 v171, v172, v171
	v_add_f32_e32 v172, 1.0, v170
	v_add_f32_e32 v175, -1.0, v172
	v_sub_f32_e32 v170, v170, v175
	v_add_f32_e32 v169, v169, v170
	v_add_f32_e32 v170, v172, v169
	v_sub_f32_e32 v172, v172, v170
	v_add_f32_e32 v169, v169, v172
	v_rcp_f32_e32 v172, v170
	v_cvt_f32_i32_e32 v168, v168
	v_cmp_neq_f32_e64 s[10:11], s58, v0
	v_mul_f32_e32 v175, v174, v172
	v_mul_f32_e32 v176, v170, v175
	v_fma_f32 v177, v175, v170, -v176
	v_fmac_f32_e32 v177, v175, v169
	v_add_f32_e32 v194, v176, v177
	v_sub_f32_e32 v195, v174, v194
	v_sub_f32_e32 v174, v174, v195
	v_sub_f32_e32 v176, v194, v176
	v_sub_f32_e32 v174, v174, v194
	v_add_f32_e32 v171, v171, v174
	v_sub_f32_e32 v174, v176, v177
	v_add_f32_e32 v171, v174, v171
	v_add_f32_e32 v174, v195, v171
	v_mul_f32_e32 v176, v172, v174
	v_mul_f32_e32 v177, v170, v176
	v_fma_f32 v170, v176, v170, -v177
	v_fmac_f32_e32 v170, v176, v169
	v_sub_f32_e32 v169, v195, v174
	v_add_f32_e32 v169, v171, v169
	v_add_f32_e32 v171, v177, v170
	v_sub_f32_e32 v194, v174, v171
	v_sub_f32_e32 v174, v174, v194
	v_sub_f32_e32 v177, v171, v177
	v_sub_f32_e32 v171, v174, v171
	v_add_f32_e32 v169, v169, v171
	v_sub_f32_e32 v170, v177, v170
	v_add_f32_e32 v169, v170, v169
	v_add_f32_e32 v170, v175, v176
	v_add_f32_e32 v169, v194, v169
	v_sub_f32_e32 v171, v170, v175
	v_mul_f32_e32 v169, v172, v169
	v_sub_f32_e32 v171, v176, v171
	v_add_f32_e32 v169, v171, v169
	v_mul_f32_e32 v175, 0x3f317218, v168
	v_add_f32_e32 v171, v170, v169
	v_fma_f32 v176, v168, s60, -v175
	v_mul_f32_e32 v172, v171, v171
	v_fmac_f32_e32 v176, 0xb102e308, v168
	v_sub_f32_e32 v168, v171, v170
	v_fmamk_f32 v174, v172, 0x3e9b6dac, v196
	v_sub_f32_e32 v168, v169, v168
	v_add_f32_e32 v169, v175, v176
	v_fmaak_f32 v174, v172, v174, 0x3f2aaada
	v_sub_f32_e32 v170, v169, v175
	v_ldexp_f32 v175, v171, 1
	v_mul_f32_e32 v171, v171, v172
	v_mul_f32_e32 v171, v171, v174
	v_add_f32_e32 v172, v175, v171
	v_sub_f32_e32 v174, v172, v175
	v_ldexp_f32 v168, v168, 1
	v_sub_f32_e32 v171, v171, v174
	v_add_f32_e32 v168, v168, v171
	v_add_f32_e32 v171, v172, v168
	v_sub_f32_e32 v172, v171, v172
	v_sub_f32_e32 v168, v168, v172
	v_add_f32_e32 v172, v169, v171
	v_sub_f32_e32 v174, v172, v169
	v_sub_f32_e32 v175, v172, v174
	v_sub_f32_e32 v170, v176, v170
	v_sub_f32_e32 v169, v169, v175
	v_sub_f32_e32 v171, v171, v174
	v_add_f32_e32 v169, v171, v169
	v_add_f32_e32 v171, v170, v168
	v_sub_f32_e32 v174, v171, v170
	v_sub_f32_e32 v175, v171, v174
	v_sub_f32_e32 v170, v170, v175
	v_sub_f32_e32 v168, v168, v174
	v_add_f32_e32 v169, v171, v169
	v_add_f32_e32 v168, v168, v170
	v_add_f32_e32 v170, v172, v169
	v_sub_f32_e32 v171, v170, v172
	v_sub_f32_e32 v169, v169, v171
	v_add_f32_e32 v168, v168, v169
	v_add_f32_e32 v168, v170, v168
	v_cndmask_b32_e64 v168, v197, v168, s[10:11]
	v_cmp_lt_f32_e64 s[10:11], |v0|, s61
	s_nop 1
	v_cndmask_b32_e64 v0, v168, v0, s[10:11]
	v_sub_f32_e32 v0, v165, v0
	v_lshl_add_u64 v[168:169], v[166:167], 0, s[2:3]
	global_store_dword v[168:169], v0, off
	global_load_dword v0, v1, s[18:19] offset:52
	s_or_b32 s2, s38, 13
	s_ashr_i32 s3, s2, 31
	s_lshl_b64 s[2:3], s[2:3], 16
	s_waitcnt vmcnt(0)
;   DI void operator()(int tok0, int feat0, f32x16 (&acc)[2][2], int r, int hh) const {
;     ...
;       } else if (feat0 == 4096) {
;         if (hh == 0) {
; #pragma unroll
;           for (int i = 0; i < 16; ++i) {
;             const float xv = acc[0][mt][i] + bf[i];
;             const float ls = fminf(xv, 0.f) - log1pf(expf(-fabsf(xv)));
;             lf[((size_t)(b * 16 + i)) * SEQ + s] = ls;
;           }
;         }
	v_add_f32_e32 v0, v127, v0
	v_mul_f32_e64 v168, |v0|, s54
	v_fma_f32 v169, |v0|, s54, -v168
	v_rndne_f32_e32 v170, v168
	v_fma_f32 v169, |v0|, s55, v169
	v_sub_f32_e32 v168, v168, v170
	v_add_f32_e32 v168, v168, v169
	v_exp_f32_e32 v168, v168
	v_cvt_i32_f32_e32 v169, v170
	v_cmp_ngt_f32_e64 s[10:11], |v0|, s56
	v_min_f32_e32 v165, 0, v0
	v_ldexp_f32 v168, v168, v169
	v_cndmask_b32_e64 v168, 0, v168, s[10:11]
	v_cmp_nlt_f32_e64 s[10:11], |v0|, s57
	s_nop 1
	v_cndmask_b32_e64 v0, v197, v168, s[10:11]
	v_add_f32_e32 v170, 1.0, v0
	v_add_f32_e32 v168, -1.0, v170
	v_sub_f32_e32 v169, v168, v170
	v_add_f32_e32 v169, 1.0, v169
	v_sub_f32_e32 v168, v0, v168
	v_add_f32_e32 v171, v168, v169
	v_frexp_mant_f32_e32 v168, v170
	v_cmp_gt_f32_e64 s[10:11], s59, v168
	v_cvt_f64_f32_e32 v[168:169], v170
	v_frexp_exp_i32_f64_e32 v168, v[168:169]
	v_subbrev_co_u32_e64 v168, s[10:11], 0, v168, s[10:11]
	v_sub_u32_e32 v169, 0, v168
	v_ldexp_f32 v170, v170, v169
	v_ldexp_f32 v169, v171, v169
	v_add_f32_e32 v171, -1.0, v170
	v_add_f32_e32 v172, 1.0, v171
	v_sub_f32_e32 v172, v170, v172
	v_add_f32_e32 v172, v169, v172
	v_add_f32_e32 v174, v171, v172
	v_sub_f32_e32 v171, v171, v174
	v_add_f32_e32 v171, v172, v171
	v_add_f32_e32 v172, 1.0, v170
	v_add_f32_e32 v175, -1.0, v172
	v_sub_f32_e32 v170, v170, v175
	v_add_f32_e32 v169, v169, v170
	v_add_f32_e32 v170, v172, v169
	v_sub_f32_e32 v172, v172, v170
	v_add_f32_e32 v169, v169, v172
	v_rcp_f32_e32 v172, v170
	v_cvt_f32_i32_e32 v168, v168
	v_cmp_neq_f32_e64 s[10:11], s58, v0
	v_mul_f32_e32 v175, v174, v172
	v_mul_f32_e32 v176, v170, v175
	v_fma_f32 v177, v175, v170, -v176
	v_fmac_f32_e32 v177, v175, v169
	v_add_f32_e32 v194, v176, v177
	v_sub_f32_e32 v195, v174, v194
	v_sub_f32_e32 v174, v174, v195
	v_sub_f32_e32 v176, v194, v176
	v_sub_f32_e32 v174, v174, v194
	v_add_f32_e32 v171, v171, v174
	v_sub_f32_e32 v174, v176, v177
	v_add_f32_e32 v171, v174, v171
	v_add_f32_e32 v174, v195, v171
	v_mul_f32_e32 v176, v172, v174
	v_mul_f32_e32 v177, v170, v176
	v_fma_f32 v170, v176, v170, -v177
	v_fmac_f32_e32 v170, v176, v169
	v_sub_f32_e32 v169, v195, v174
	v_add_f32_e32 v169, v171, v169
	v_add_f32_e32 v171, v177, v170
	v_sub_f32_e32 v194, v174, v171
	v_sub_f32_e32 v174, v174, v194
	v_sub_f32_e32 v177, v171, v177
	v_sub_f32_e32 v171, v174, v171
	v_add_f32_e32 v169, v169, v171
	v_sub_f32_e32 v170, v177, v170
	v_add_f32_e32 v169, v170, v169
	v_add_f32_e32 v170, v175, v176
	v_add_f32_e32 v169, v194, v169
	v_sub_f32_e32 v171, v170, v175
	v_mul_f32_e32 v169, v172, v169
	v_sub_f32_e32 v171, v176, v171
	v_add_f32_e32 v169, v171, v169
	v_mul_f32_e32 v175, 0x3f317218, v168
	v_add_f32_e32 v171, v170, v169
	v_fma_f32 v176, v168, s60, -v175
	v_mul_f32_e32 v172, v171, v171
	v_fmac_f32_e32 v176, 0xb102e308, v168
	v_sub_f32_e32 v168, v171, v170
	v_fmamk_f32 v174, v172, 0x3e9b6dac, v196
	v_sub_f32_e32 v168, v169, v168
	v_add_f32_e32 v169, v175, v176
	v_fmaak_f32 v174, v172, v174, 0x3f2aaada
	v_sub_f32_e32 v170, v169, v175
	v_ldexp_f32 v175, v171, 1
	v_mul_f32_e32 v171, v171, v172
	v_mul_f32_e32 v171, v171, v174
	v_add_f32_e32 v172, v175, v171
	v_sub_f32_e32 v174, v172, v175
	v_ldexp_f32 v168, v168, 1
	v_sub_f32_e32 v171, v171, v174
	v_add_f32_e32 v168, v168, v171
	v_add_f32_e32 v171, v172, v168
	v_sub_f32_e32 v172, v171, v172
	v_sub_f32_e32 v168, v168, v172
	v_add_f32_e32 v172, v169, v171
	v_sub_f32_e32 v174, v172, v169
	v_sub_f32_e32 v175, v172, v174
	v_sub_f32_e32 v170, v176, v170
	v_sub_f32_e32 v169, v169, v175
	v_sub_f32_e32 v171, v171, v174
	v_add_f32_e32 v169, v171, v169
	v_add_f32_e32 v171, v170, v168
	v_sub_f32_e32 v174, v171, v170
	v_sub_f32_e32 v175, v171, v174
	v_sub_f32_e32 v170, v170, v175
	v_sub_f32_e32 v168, v168, v174
	v_add_f32_e32 v169, v171, v169
	v_add_f32_e32 v168, v168, v170
	v_add_f32_e32 v170, v172, v169
	v_sub_f32_e32 v171, v170, v172
	v_sub_f32_e32 v169, v169, v171
	v_add_f32_e32 v168, v168, v169
	v_add_f32_e32 v168, v170, v168
	v_cndmask_b32_e64 v168, v197, v168, s[10:11]
	v_cmp_lt_f32_e64 s[10:11], |v0|, s61
	s_nop 1
	v_cndmask_b32_e64 v0, v168, v0, s[10:11]
	v_sub_f32_e32 v0, v165, v0
	v_lshl_add_u64 v[168:169], v[166:167], 0, s[2:3]
	global_store_dword v[168:169], v0, off
	global_load_dword v0, v1, s[18:19] offset:56
	s_or_b32 s2, s38, 14
	s_ashr_i32 s3, s2, 31
	s_lshl_b64 s[2:3], s[2:3], 16
	s_waitcnt vmcnt(0)
;   DI void operator()(int tok0, int feat0, f32x16 (&acc)[2][2], int r, int hh) const {
;     ...
;       } else if (feat0 == 4096) {
;         if (hh == 0) {
; #pragma unroll
;           for (int i = 0; i < 16; ++i) {
;             const float xv = acc[0][mt][i] + bf[i];
;             const float ls = fminf(xv, 0.f) - log1pf(expf(-fabsf(xv)));
;             lf[((size_t)(b * 16 + i)) * SEQ + s] = ls;
;           }
;         }
	v_add_f32_e32 v0, v128, v0
	v_mul_f32_e64 v168, |v0|, s54
	v_fma_f32 v169, |v0|, s54, -v168
	v_rndne_f32_e32 v170, v168
	v_fma_f32 v169, |v0|, s55, v169
	v_sub_f32_e32 v168, v168, v170
	v_add_f32_e32 v168, v168, v169
	v_exp_f32_e32 v168, v168
	v_cvt_i32_f32_e32 v169, v170
	v_cmp_ngt_f32_e64 s[10:11], |v0|, s56
	v_min_f32_e32 v165, 0, v0
	v_ldexp_f32 v168, v168, v169
	v_cndmask_b32_e64 v168, 0, v168, s[10:11]
	v_cmp_nlt_f32_e64 s[10:11], |v0|, s57
	s_nop 1
	v_cndmask_b32_e64 v0, v197, v168, s[10:11]
	v_add_f32_e32 v170, 1.0, v0
	v_add_f32_e32 v168, -1.0, v170
	v_sub_f32_e32 v169, v168, v170
	v_add_f32_e32 v169, 1.0, v169
	v_sub_f32_e32 v168, v0, v168
	v_add_f32_e32 v171, v168, v169
	v_frexp_mant_f32_e32 v168, v170
	v_cmp_gt_f32_e64 s[10:11], s59, v168
	v_cvt_f64_f32_e32 v[168:169], v170
	v_frexp_exp_i32_f64_e32 v168, v[168:169]
	v_subbrev_co_u32_e64 v168, s[10:11], 0, v168, s[10:11]
	v_sub_u32_e32 v169, 0, v168
	v_ldexp_f32 v170, v170, v169
	v_ldexp_f32 v169, v171, v169
	v_add_f32_e32 v171, -1.0, v170
	v_add_f32_e32 v172, 1.0, v171
	v_sub_f32_e32 v172, v170, v172
	v_add_f32_e32 v172, v169, v172
	v_add_f32_e32 v174, v171, v172
	v_sub_f32_e32 v171, v171, v174
	v_add_f32_e32 v171, v172, v171
	v_add_f32_e32 v172, 1.0, v170
	v_add_f32_e32 v175, -1.0, v172
	v_sub_f32_e32 v170, v170, v175
	v_add_f32_e32 v169, v169, v170
	v_add_f32_e32 v170, v172, v169
	v_sub_f32_e32 v172, v172, v170
	v_add_f32_e32 v169, v169, v172
	v_rcp_f32_e32 v172, v170
	v_cvt_f32_i32_e32 v168, v168
	v_cmp_neq_f32_e64 s[10:11], s58, v0
	v_mul_f32_e32 v175, v174, v172
	v_mul_f32_e32 v176, v170, v175
	v_fma_f32 v177, v175, v170, -v176
	v_fmac_f32_e32 v177, v175, v169
	v_add_f32_e32 v194, v176, v177
	v_sub_f32_e32 v195, v174, v194
	v_sub_f32_e32 v174, v174, v195
	v_sub_f32_e32 v176, v194, v176
	v_sub_f32_e32 v174, v174, v194
	v_add_f32_e32 v171, v171, v174
	v_sub_f32_e32 v174, v176, v177
	v_add_f32_e32 v171, v174, v171
	v_add_f32_e32 v174, v195, v171
	v_mul_f32_e32 v176, v172, v174
	v_mul_f32_e32 v177, v170, v176
	v_fma_f32 v170, v176, v170, -v177
	v_fmac_f32_e32 v170, v176, v169
	v_sub_f32_e32 v169, v195, v174
	v_add_f32_e32 v169, v171, v169
	v_add_f32_e32 v171, v177, v170
	v_sub_f32_e32 v194, v174, v171
	v_sub_f32_e32 v174, v174, v194
	v_sub_f32_e32 v177, v171, v177
	v_sub_f32_e32 v171, v174, v171
	v_add_f32_e32 v169, v169, v171
	v_sub_f32_e32 v170, v177, v170
	v_add_f32_e32 v169, v170, v169
	v_add_f32_e32 v170, v175, v176
	v_add_f32_e32 v169, v194, v169
	v_sub_f32_e32 v171, v170, v175
	v_mul_f32_e32 v169, v172, v169
	v_sub_f32_e32 v171, v176, v171
	v_add_f32_e32 v169, v171, v169
	v_mul_f32_e32 v175, 0x3f317218, v168
	v_add_f32_e32 v171, v170, v169
	v_fma_f32 v176, v168, s60, -v175
	v_mul_f32_e32 v172, v171, v171
	v_fmac_f32_e32 v176, 0xb102e308, v168
	v_sub_f32_e32 v168, v171, v170
	v_fmamk_f32 v174, v172, 0x3e9b6dac, v196
	v_sub_f32_e32 v168, v169, v168
	v_add_f32_e32 v169, v175, v176
	v_fmaak_f32 v174, v172, v174, 0x3f2aaada
	v_sub_f32_e32 v170, v169, v175
	v_ldexp_f32 v175, v171, 1
	v_mul_f32_e32 v171, v171, v172
	v_mul_f32_e32 v171, v171, v174
	v_add_f32_e32 v172, v175, v171
	v_sub_f32_e32 v174, v172, v175
	v_ldexp_f32 v168, v168, 1
	v_sub_f32_e32 v171, v171, v174
	v_add_f32_e32 v168, v168, v171
	v_add_f32_e32 v171, v172, v168
	v_sub_f32_e32 v172, v171, v172
	v_sub_f32_e32 v168, v168, v172
	v_add_f32_e32 v172, v169, v171
	v_sub_f32_e32 v174, v172, v169
	v_sub_f32_e32 v175, v172, v174
	v_sub_f32_e32 v170, v176, v170
	v_sub_f32_e32 v169, v169, v175
	v_sub_f32_e32 v171, v171, v174
	v_add_f32_e32 v169, v171, v169
	v_add_f32_e32 v171, v170, v168
	v_sub_f32_e32 v174, v171, v170
	v_sub_f32_e32 v175, v171, v174
	v_sub_f32_e32 v170, v170, v175
	v_sub_f32_e32 v168, v168, v174
	v_add_f32_e32 v169, v171, v169
	v_add_f32_e32 v168, v168, v170
	v_add_f32_e32 v170, v172, v169
	v_sub_f32_e32 v171, v170, v172
	v_sub_f32_e32 v169, v169, v171
	v_add_f32_e32 v168, v168, v169
	v_add_f32_e32 v168, v170, v168
	v_cndmask_b32_e64 v168, v197, v168, s[10:11]
	v_cmp_lt_f32_e64 s[10:11], |v0|, s61
	s_nop 1
	v_cndmask_b32_e64 v0, v168, v0, s[10:11]
	v_sub_f32_e32 v0, v165, v0
	v_lshl_add_u64 v[168:169], v[166:167], 0, s[2:3]
	global_store_dword v[168:169], v0, off
	global_load_dword v0, v1, s[18:19] offset:60
	s_or_b32 s2, s38, 15
	s_ashr_i32 s3, s2, 31
	s_lshl_b64 s[4:5], s[2:3], 16
	v_lshl_add_u64 v[166:167], v[166:167], 0, s[4:5]
	s_waitcnt vmcnt(0)
;   DI void operator()(int tok0, int feat0, f32x16 (&acc)[2][2], int r, int hh) const {
;     ...
;       } else if (feat0 == 4096) {
;         if (hh == 0) {
; #pragma unroll
;           for (int i = 0; i < 16; ++i) {
;             const float xv = acc[0][mt][i] + bf[i];
;             const float ls = fminf(xv, 0.f) - log1pf(expf(-fabsf(xv)));
;             lf[((size_t)(b * 16 + i)) * SEQ + s] = ls;
;           }
;         }
	v_add_f32_e32 v0, v129, v0
	v_mul_f32_e64 v168, |v0|, s54
	v_fma_f32 v169, |v0|, s54, -v168
	v_rndne_f32_e32 v170, v168
	v_fma_f32 v169, |v0|, s55, v169
	v_sub_f32_e32 v168, v168, v170
	v_add_f32_e32 v168, v168, v169
	v_exp_f32_e32 v168, v168
	v_cvt_i32_f32_e32 v169, v170
	v_cmp_ngt_f32_e64 s[10:11], |v0|, s56
	v_min_f32_e32 v165, 0, v0
	v_ldexp_f32 v168, v168, v169
	v_cndmask_b32_e64 v168, 0, v168, s[10:11]
	v_cmp_nlt_f32_e64 s[10:11], |v0|, s57
	s_nop 1
	v_cndmask_b32_e64 v0, v197, v168, s[10:11]
	v_add_f32_e32 v170, 1.0, v0
	v_add_f32_e32 v168, -1.0, v170
	v_sub_f32_e32 v169, v168, v170
	v_add_f32_e32 v169, 1.0, v169
	v_sub_f32_e32 v168, v0, v168
	v_add_f32_e32 v171, v168, v169
	v_frexp_mant_f32_e32 v168, v170
	v_cmp_gt_f32_e64 s[10:11], s59, v168
	v_cvt_f64_f32_e32 v[168:169], v170
	v_frexp_exp_i32_f64_e32 v168, v[168:169]
	v_subbrev_co_u32_e64 v168, s[10:11], 0, v168, s[10:11]
	v_sub_u32_e32 v169, 0, v168
	v_ldexp_f32 v170, v170, v169
	v_ldexp_f32 v169, v171, v169
	v_add_f32_e32 v171, -1.0, v170
	v_add_f32_e32 v172, 1.0, v171
	v_sub_f32_e32 v172, v170, v172
	v_add_f32_e32 v172, v169, v172
	v_add_f32_e32 v174, v171, v172
	v_sub_f32_e32 v171, v171, v174
	v_add_f32_e32 v171, v172, v171
	v_add_f32_e32 v172, 1.0, v170
	v_add_f32_e32 v175, -1.0, v172
	v_sub_f32_e32 v170, v170, v175
	v_add_f32_e32 v169, v169, v170
	v_add_f32_e32 v170, v172, v169
	v_sub_f32_e32 v172, v172, v170
	v_add_f32_e32 v169, v169, v172
	v_rcp_f32_e32 v172, v170
	v_cvt_f32_i32_e32 v168, v168
	v_cmp_neq_f32_e64 s[10:11], s58, v0
	v_mul_f32_e32 v175, v174, v172
	v_mul_f32_e32 v176, v170, v175
	v_fma_f32 v177, v175, v170, -v176
	v_fmac_f32_e32 v177, v175, v169
	v_add_f32_e32 v194, v176, v177
	v_sub_f32_e32 v195, v174, v194
	v_sub_f32_e32 v174, v174, v195
	v_sub_f32_e32 v176, v194, v176
	v_sub_f32_e32 v174, v174, v194
	v_add_f32_e32 v171, v171, v174
	v_sub_f32_e32 v174, v176, v177
	v_add_f32_e32 v171, v174, v171
	v_add_f32_e32 v174, v195, v171
	v_mul_f32_e32 v176, v172, v174
	v_mul_f32_e32 v177, v170, v176
	v_fma_f32 v170, v176, v170, -v177
	v_fmac_f32_e32 v170, v176, v169
	v_sub_f32_e32 v169, v195, v174
	v_add_f32_e32 v169, v171, v169
	v_add_f32_e32 v171, v177, v170
	v_sub_f32_e32 v194, v174, v171
	v_sub_f32_e32 v174, v174, v194
	v_sub_f32_e32 v177, v171, v177
	v_sub_f32_e32 v171, v174, v171
	v_add_f32_e32 v169, v169, v171
	v_sub_f32_e32 v170, v177, v170
	v_add_f32_e32 v169, v170, v169
	v_add_f32_e32 v170, v175, v176
	v_add_f32_e32 v169, v194, v169
	v_sub_f32_e32 v171, v170, v175
	v_mul_f32_e32 v169, v172, v169
	v_sub_f32_e32 v171, v176, v171
	v_add_f32_e32 v169, v171, v169
	v_mul_f32_e32 v175, 0x3f317218, v168
	v_add_f32_e32 v171, v170, v169
	v_fma_f32 v176, v168, s60, -v175
	v_mul_f32_e32 v172, v171, v171
	v_fmac_f32_e32 v176, 0xb102e308, v168
	v_sub_f32_e32 v168, v171, v170
	v_fmamk_f32 v174, v172, 0x3e9b6dac, v196
	v_sub_f32_e32 v168, v169, v168
	v_add_f32_e32 v169, v175, v176
	v_fmaak_f32 v174, v172, v174, 0x3f2aaada
	v_sub_f32_e32 v170, v169, v175
	v_ldexp_f32 v175, v171, 1
	v_mul_f32_e32 v171, v171, v172
	v_mul_f32_e32 v171, v171, v174
	v_add_f32_e32 v172, v175, v171
	v_sub_f32_e32 v174, v172, v175
	v_ldexp_f32 v168, v168, 1
	v_sub_f32_e32 v171, v171, v174
	v_add_f32_e32 v168, v168, v171
	v_add_f32_e32 v171, v172, v168
	v_sub_f32_e32 v172, v171, v172
	v_sub_f32_e32 v168, v168, v172
	v_add_f32_e32 v172, v169, v171
	v_sub_f32_e32 v174, v172, v169
	v_sub_f32_e32 v175, v172, v174
	v_sub_f32_e32 v170, v176, v170
	v_sub_f32_e32 v169, v169, v175
	v_sub_f32_e32 v171, v171, v174
	v_add_f32_e32 v169, v171, v169
	v_add_f32_e32 v171, v170, v168
	v_sub_f32_e32 v174, v171, v170
	v_sub_f32_e32 v175, v171, v174
	v_sub_f32_e32 v170, v170, v175
	v_sub_f32_e32 v168, v168, v174
	v_add_f32_e32 v169, v171, v169
	v_add_f32_e32 v168, v168, v170
	v_add_f32_e32 v170, v172, v169
	v_sub_f32_e32 v171, v170, v172
	v_sub_f32_e32 v169, v169, v171
	v_add_f32_e32 v168, v168, v169
	v_add_f32_e32 v168, v170, v168
	v_cndmask_b32_e64 v168, v197, v168, s[10:11]
	v_cmp_lt_f32_e64 s[10:11], |v0|, s61
	s_nop 1
	v_cndmask_b32_e64 v0, v168, v0, s[10:11]
	v_sub_f32_e32 v0, v165, v0
	global_store_dword v[166:167], v0, off

; DI float xmax32(float v) { const u32x2 r_ = __builtin_amdgcn_permlane32_swap(__float_as_uint(v), __float_as_uint(v), false, false); return fmaxf(__uint_as_float(r_[0]), __uint_as_float(r_[1])); }
; template <int DVT, bool FOX>
; DI void attn_step(const char* kb, const bf16x8 (&qf)[4], f32x16 (&o)[DVT], float& m, float& l, const bool diag, const int j, const int tq, const int r, const int hh) {
;     ...
;   float mx;
;   {
;     float a0 = fmaxf(fmaxf(st[0][0], st[0][1]), st[0][2]), a1 = fmaxf(fmaxf(st[1][0], st[1][1]), st[1][2]);
; #pragma unroll
;     for (int i = 3; i < 15; i += 2) { a0 = fmaxf(fmaxf(a0, st[0][i]), st[0][i + 1]); a1 = fmaxf(fmaxf(a1, st[1][i]), st[1][i + 1]); }
;     mx = fmaxf(fmaxf(a0, a1), fmaxf(st[0][15], st[1][15]));
;   }
;   mx = xmax32(mx);
;   if (__any(diag || mx > 8.f)) {
;     const float d = (diag || mx > 0.f) ? mx : 0.f;
;     const float alpha = diag ? 0.f : __builtin_amdgcn_exp2f(-d);
;     m += d;
;     l *= alpha;
; #pragma unroll
;     for (int dd = 0; dd < DVT; ++dd)
; #pragma unroll
;       for (int i = 0; i < 16; ++i) o[dd][i] *= alpha;
;     const f32x2 d2 = {d, d};
; #pragma unroll
;     for (int kt = 0; kt < 2; ++kt)
; #pragma unroll
;       for (int i = 0; i < 8; ++i) { f32x2 z = {st[kt][2 * i], st[kt][2 * i + 1]}; z = z - d2; st[kt][2 * i] = z[0]; st[kt][2 * i + 1] = z[1]; }
;   }
.LBB0_228:
	v_max3_f32 v42, v138, v139, v136
	v_max3_f32 v43, v56, v57, v54
	v_max3_f32 v42, v42, v137, v134
	v_max3_f32 v43, v43, v55, v52
	v_max3_f32 v42, v42, v135, v132
	v_max3_f32 v43, v43, v53, v50
	v_max3_f32 v42, v42, v133, v130
	v_max3_f32 v43, v43, v51, v40
	v_max3_f32 v42, v42, v131, v128
	v_max3_f32 v43, v43, v41, v38
	v_max3_f32 v42, v42, v129, v60
	v_max3_f32 v43, v43, v39, v36
	v_max_f32_e32 v44, v35, v35
	v_max_f32_e32 v45, v59, v59
	v_max3_f32 v42, v42, v61, v58
	v_max3_f32 v43, v43, v37, v34
	v_max_f32_e32 v44, v45, v44
	v_max3_f32 v42, v42, v43, v44
	v_mov_b32_e32 v43, v42
	s_nop 1
	v_permlane32_swap_b32_e32 v42, v43
	v_max_f32_e32 v42, v42, v43
	v_cmp_lt_f32_e32 vcc, s92, v42
	s_or_b64 vcc, s[88:89], vcc
	s_nop 0
	v_cndmask_b32_e64 v43, 0, 1, vcc
	v_cmp_ne_u32_e32 vcc, 0, v43
	s_cbranch_vccz .LBB0_230
	v_cmp_lt_f32_e32 vcc, 0, v42
	s_or_b64 vcc, s[88:89], vcc
	s_nop 0
	v_cndmask_b32_e32 v42, 0, v42, vcc
	v_exp_f32_e64 v43, -v42
	v_add_f32_e32 v126, v126, v42
	v_cndmask_b32_e64 v44, v43, 0, s[88:89]
	v_mul_f32_e32 v0, v0, v44
	v_pk_mul_f32 v[32:33], v[32:33], v[44:45] op_sel_hi:[1,0]
	v_pk_mul_f32 v[30:31], v[30:31], v[44:45] op_sel_hi:[1,0]
	v_pk_mul_f32 v[28:29], v[28:29], v[44:45] op_sel_hi:[1,0]
	v_pk_mul_f32 v[26:27], v[26:27], v[44:45] op_sel_hi:[1,0]
	v_pk_mul_f32 v[24:25], v[24:25], v[44:45] op_sel_hi:[1,0]
	v_pk_mul_f32 v[22:23], v[22:23], v[44:45] op_sel_hi:[1,0]
	v_pk_mul_f32 v[20:21], v[20:21], v[44:45] op_sel_hi:[1,0]
	v_pk_mul_f32 v[18:19], v[18:19], v[44:45] op_sel_hi:[1,0]
	v_pk_mul_f32 v[16:17], v[16:17], v[44:45] op_sel_hi:[1,0]
	v_pk_mul_f32 v[14:15], v[14:15], v[44:45] op_sel_hi:[1,0]
	v_pk_mul_f32 v[12:13], v[12:13], v[44:45] op_sel_hi:[1,0]
	v_pk_mul_f32 v[10:11], v[10:11], v[44:45] op_sel_hi:[1,0]
	v_pk_mul_f32 v[8:9], v[8:9], v[44:45] op_sel_hi:[1,0]
	v_pk_mul_f32 v[6:7], v[6:7], v[44:45] op_sel_hi:[1,0]
	v_pk_mul_f32 v[4:5], v[4:5], v[44:45] op_sel_hi:[1,0]
	v_pk_mul_f32 v[2:3], v[2:3], v[44:45] op_sel_hi:[1,0]
	v_pk_add_f32 v[138:139], v[138:139], v[42:43] op_sel_hi:[1,0] neg_lo:[0,1] neg_hi:[0,1]
	v_pk_add_f32 v[136:137], v[136:137], v[42:43] op_sel_hi:[1,0] neg_lo:[0,1] neg_hi:[0,1]
	v_pk_add_f32 v[134:135], v[134:135], v[42:43] op_sel_hi:[1,0] neg_lo:[0,1] neg_hi:[0,1]
	v_pk_add_f32 v[132:133], v[132:133], v[42:43] op_sel_hi:[1,0] neg_lo:[0,1] neg_hi:[0,1]
	v_pk_add_f32 v[130:131], v[130:131], v[42:43] op_sel_hi:[1,0] neg_lo:[0,1] neg_hi:[0,1]
	v_pk_add_f32 v[128:129], v[128:129], v[42:43] op_sel_hi:[1,0] neg_lo:[0,1] neg_hi:[0,1]
	v_pk_add_f32 v[60:61], v[60:61], v[42:43] op_sel_hi:[1,0] neg_lo:[0,1] neg_hi:[0,1]
	v_pk_add_f32 v[58:59], v[58:59], v[42:43] op_sel_hi:[1,0] neg_lo:[0,1] neg_hi:[0,1]
	v_pk_add_f32 v[56:57], v[56:57], v[42:43] op_sel_hi:[1,0] neg_lo:[0,1] neg_hi:[0,1]
	v_pk_add_f32 v[54:55], v[54:55], v[42:43] op_sel_hi:[1,0] neg_lo:[0,1] neg_hi:[0,1]
	v_pk_add_f32 v[52:53], v[52:53], v[42:43] op_sel_hi:[1,0] neg_lo:[0,1] neg_hi:[0,1]
	v_pk_add_f32 v[50:51], v[50:51], v[42:43] op_sel_hi:[1,0] neg_lo:[0,1] neg_hi:[0,1]
	v_pk_add_f32 v[40:41], v[40:41], v[42:43] op_sel_hi:[1,0] neg_lo:[0,1] neg_hi:[0,1]
	v_pk_add_f32 v[38:39], v[38:39], v[42:43] op_sel_hi:[1,0] neg_lo:[0,1] neg_hi:[0,1]
	v_pk_add_f32 v[36:37], v[36:37], v[42:43] op_sel_hi:[1,0] neg_lo:[0,1] neg_hi:[0,1]
	v_pk_add_f32 v[34:35], v[34:35], v[42:43] op_sel_hi:[1,0] neg_lo:[0,1] neg_hi:[0,1]

; #define G_GLOAD(XR, WR, KT) { _Pragma("unroll") for (int i_ = 0; i_ < 4; ++i_) XR[i_] = *(const u32x4*)(Xt + ((size_t)(64 * i_) * ldx + (KT) * 64) * 2 + xoff); \
;     _Pragma("unroll") for (int i_ = 0; i_ < 4; ++i_) WR[i_] = *(const u32x4*)(Wtb + ((size_t)(64 * i_) * K + (KT) * 64) * 2 + woff); }
; #define G_LSTORE(XR, WR, STG) { char* xs_ = lds + (STG) * G_STAGE; char* ws_ = xs_ + G_XB; \
;     _Pragma("unroll") for (int i_ = 0; i_ < 4; ++i_) *(u32x4*)(xs_ + (lrow + 64 * i_) * LROW + lch * 16) = XR[i_]; \
;     _Pragma("unroll") for (int i_ = 0; i_ < 4; ++i_) *(u32x4*)(ws_ + (lrow + 64 * i_) * LROW + lch * 16) = WR[i_]; }
; template <class Epi>
; DI void gemm_phase(const bf16_t* __restrict__ X, const int ldx, const bf16_t* __restrict__ Wt, const int N, const int K, const Epi& epi, char* lds) {
;     ...
;     if (Epi::kFull || chunk == xcd) {
;       G_GLOAD(xr0, wr0, 0);
;       G_LSTORE(xr0, wr0, 0);
;       __syncthreads();
;       G_GLOAD(xr0, wr0, 1);
;     }
; #pragma unroll
;     for (int c = 0; c < 2; ++c)
; #pragma unroll
;       for (int a = 0; a < 2; ++a)
; #pragma unroll
;         for (int b = 0; b < 2; ++b)
; #pragma unroll
;           for (int i = 0; i < 16; ++i) acc[c][a][b][i] = 0.f;
.LBB0_268:
	s_lshl_b32 s2, s34, 5
	v_readlane_b32 s3, v254, 3
	s_add_i32 s2, s2, s3
	s_lshr_b32 s2, s2, 2
	s_and_b32 s2, s2, 0xffffffc
	s_or_b32 s2, s2, s90
	s_lshl_b32 s4, s2, 8
	s_mov_b32 s5, s97
	s_lshl_b64 s[20:21], s[4:5], 11
	s_add_u32 s20, s12, s20
	s_addc_u32 s21, s13, s21
	v_lshl_add_u64 v[178:179], s[20:21], 0, v[162:163]
	s_waitcnt vmcnt(2)
	v_add_co_u32_e32 v48, vcc, s91, v178
	s_mov_b64 s[22:23], 0x40000
	s_nop 0
	v_addc_co_u32_e32 v49, vcc, 0, v179, vcc
	v_add_co_u32_e32 v74, vcc, s1, v178
	global_load_dwordx4 v[24:27], v[178:179], off
	global_load_dwordx4 v[28:31], v[48:49], off
	v_addc_co_u32_e32 v75, vcc, 0, v179, vcc
	v_add_co_u32_e32 v76, vcc, s76, v178
	global_load_dwordx4 v[32:35], v[164:165], off
	global_load_dwordx4 v[36:39], v[198:199], off
	global_load_dwordx4 v[40:43], v[206:207], off
	global_load_dwordx4 v[44:47], v[170:171], off
	v_addc_co_u32_e32 v77, vcc, 0, v179, vcc
	global_load_dwordx4 v[66:69], v[74:75], off
	global_load_dwordx4 v[70:73], v[76:77], off
	v_mov_b32_e32 v2, 0
	v_lshl_add_u64 v[180:181], v[178:179], 0, s[22:23]
	s_mov_b64 s[22:23], 0x60000
	s_mov_b32 s21, 0
	s_movk_i32 s3, 0x100
	v_mov_b32_e32 v3, v2
	v_mov_b64_e32 v[4:5], v[2:3]
	v_mov_b64_e32 v[6:7], v[2:3]
	v_mov_b64_e32 v[8:9], v[2:3]
	v_mov_b64_e32 v[10:11], v[2:3]
	v_mov_b64_e32 v[12:13], v[2:3]
	v_mov_b64_e32 v[14:15], v[2:3]
	v_mov_b64_e32 v[16:17], v[2:3]
	s_waitcnt vmcnt(9)
	v_mov_b64_e32 v[50:51], v[2:3]
	v_mov_b64_e32 v[52:53], v[2:3]
	s_waitcnt vmcnt(8)
	v_mov_b64_e32 v[54:55], v[2:3]
	v_mov_b64_e32 v[56:57], v[2:3]
	v_mov_b64_e32 v[58:59], v[2:3]
	v_mov_b64_e32 v[60:61], v[2:3]
	v_mov_b64_e32 v[62:63], v[2:3]
	v_mov_b64_e32 v[64:65], v[2:3]
	v_mov_b64_e32 v[18:19], v[2:3]
	v_mov_b64_e32 v[20:21], v[2:3]
	v_mov_b32_e32 v22, v2
	v_lshl_add_u64 v[182:183], v[178:179], 0, s[22:23]
	v_mov_b32_e32 v23, v2
	v_mov_b64_e32 v[82:83], v[2:3]
	v_mov_b64_e32 v[84:85], v[2:3]
	v_mov_b64_e32 v[86:87], v[2:3]
	v_mov_b64_e32 v[88:89], v[2:3]
	v_mov_b64_e32 v[90:91], v[2:3]
	v_mov_b64_e32 v[92:93], v[2:3]
	v_mov_b64_e32 v[94:95], v[2:3]
	v_mov_b64_e32 v[96:97], v[2:3]
	v_mov_b64_e32 v[98:99], v[2:3]
	v_mov_b64_e32 v[100:101], v[2:3]
	v_mov_b64_e32 v[102:103], v[2:3]
	v_mov_b32_e32 v104, v2
	s_waitcnt vmcnt(5)
	ds_write_b128 v222, v[32:35] offset:36864
	s_waitcnt vmcnt(4)
	ds_write_b128 v222, v[36:39] offset:46080
	s_waitcnt vmcnt(3)
	ds_write_b128 v222, v[40:43] offset:55296
	s_waitcnt vmcnt(2)
	ds_write_b128 v222, v[44:47] offset:64512
	ds_write_b128 v222, v[24:27]
	ds_write_b128 v222, v[28:31] offset:9216
	s_waitcnt vmcnt(1)
	ds_write_b128 v222, v[66:69] offset:18432
	s_waitcnt vmcnt(0)
	ds_write_b128 v222, v[70:73] offset:27648
	s_waitcnt lgkmcnt(0)
	s_barrier
	global_load_dwordx4 v[130:133], v[174:175], off
	global_load_dwordx4 v[150:153], v[176:177], off
	global_load_dwordx4 v[158:161], v[172:173], off
	global_load_dwordx4 v[138:141], v[164:165], off offset:128
	global_load_dwordx4 v[146:149], v[76:77], off offset:128
	global_load_dwordx4 v[134:137], v[74:75], off offset:128
	global_load_dwordx4 v[154:157], v[48:49], off offset:128
	global_load_dwordx4 v[142:145], v[178:179], off offset:128
	v_mov_b64_e32 v[24:25], v[2:3]
	v_mov_b64_e32 v[26:27], v[2:3]
	v_mov_b64_e32 v[28:29], v[2:3]
	v_mov_b64_e32 v[30:31], v[2:3]
	v_mov_b64_e32 v[32:33], v[2:3]
	v_mov_b64_e32 v[34:35], v[2:3]
	v_mov_b64_e32 v[36:37], v[2:3]
	v_mov_b64_e32 v[38:39], v[2:3]
	v_mov_b64_e32 v[40:41], v[2:3]
	v_mov_b64_e32 v[42:43], v[2:3]
	v_mov_b64_e32 v[44:45], v[2:3]
	v_mov_b64_e32 v[46:47], v[2:3]
	v_mov_b64_e32 v[48:49], v[2:3]
	v_mov_b32_e32 v105, v2
	v_mov_b64_e32 v[106:107], v[2:3]
	v_mov_b64_e32 v[108:109], v[2:3]
	v_mov_b64_e32 v[110:111], v[2:3]
	v_mov_b64_e32 v[112:113], v[2:3]
	v_mov_b64_e32 v[66:67], v[2:3]
	v_mov_b64_e32 v[68:69], v[2:3]
	v_mov_b64_e32 v[70:71], v[2:3]
	v_mov_b64_e32 v[72:73], v[2:3]
	v_mov_b64_e32 v[74:75], v[2:3]
	v_mov_b64_e32 v[76:77], v[2:3]
	v_mov_b64_e32 v[78:79], v[2:3]
	v_mov_b64_e32 v[80:81], v[2:3]
	v_mov_b64_e32 v[114:115], v[2:3]
	v_mov_b64_e32 v[116:117], v[2:3]
	v_mov_b32_e32 v118, v2
	v_mov_b32_e32 v119, v2
	v_mov_b32_e32 v120, v2
	v_mov_b32_e32 v121, v2
	v_mov_b32_e32 v122, v2
	v_mov_b32_e32 v123, v2
	v_mov_b32_e32 v124, v2
	v_mov_b32_e32 v125, v2
	v_mov_b32_e32 v126, v2
	v_mov_b32_e32 v127, v2
	v_mov_b32_e32 v128, v2
	v_mov_b32_e32 v129, v2

; #define G_GLOAD(XR, WR, KT) { _Pragma("unroll") for (int i_ = 0; i_ < 4; ++i_) XR[i_] = *(const u32x4*)(Xt + ((size_t)(64 * i_) * ldx + (KT) * 64) * 2 + xoff); \
;     _Pragma("unroll") for (int i_ = 0; i_ < 4; ++i_) WR[i_] = *(const u32x4*)(Wtb + ((size_t)(64 * i_) * K + (KT) * 64) * 2 + woff); }
; #define G_LSTORE(XR, WR, STG) { char* xs_ = lds + (STG) * G_STAGE; char* ws_ = xs_ + G_XB; \
;     _Pragma("unroll") for (int i_ = 0; i_ < 4; ++i_) *(u32x4*)(xs_ + (lrow + 64 * i_) * LROW + lch * 16) = XR[i_]; \
;     _Pragma("unroll") for (int i_ = 0; i_ < 4; ++i_) *(u32x4*)(ws_ + (lrow + 64 * i_) * LROW + lch * 16) = WR[i_]; }
; template <class Epi>
; DI void gemm_phase(const bf16_t* __restrict__ X, const int ldx, const bf16_t* __restrict__ Wt, const int N, const int K, const Epi& epi, char* lds) {
;     ...
;     const int L = chunk * 32 + slot, band = L / (4 * nNt), rem = L % (4 * nNt);
;     const int mt_ = band * 4 + (rem & 3), nt_ = rem >> 2;
;     const char* Xt = (const char*)(X + (size_t)(mt_ * 256) * ldx);
;     const char* Wtb = (const char*)(Wt + (size_t)(nt_ * 256) * K);
;     const unsigned xoff = (unsigned)(lrow * ldx + lch * 8) * 2u, woff = (unsigned)(lrow * K + lch * 8) * 2u;
;     const bool has_next = !Epi::kFull && (chunk + 8 < nchunks);
;     const int Ln = (has_next ? chunk + 8 : chunk) * 32 + slot, band_n = Ln / (4 * nNt), rem_n = Ln % (4 * nNt);
;     const char* Xt_n = (const char*)(X + (size_t)((band_n * 4 + (rem_n & 3)) * 256) * ldx);
;     const char* Wtb_n = (const char*)(Wt + (size_t)((rem_n >> 2) * 256) * K);
;     f32x16 acc[2][2][2];
;     ...
;     asm volatile("" ::: "memory");
;     if (Epi::kFull || chunk == xcd) {
;       G_GLOAD(xr0, wr0, 0);
;       G_LSTORE(xr0, wr0, 0);
;       __syncthreads();
;       G_GLOAD(xr0, wr0, 1);
;     }
; #pragma unroll
;     for (int c = 0; c < 2; ++c)
; #pragma unroll
;       for (int a = 0; a < 2; ++a)
; #pragma unroll
;         for (int b = 0; b < 2; ++b)
; #pragma unroll
;           for (int i = 0; i < 16; ++i) acc[c][a][b][i] = 0.f;
.LBB0_310:
	s_add_i32 s36, s10, 8
	s_cmp_gt_u32 s10, 47
	s_cselect_b64 s[24:25], -1, 0
	s_cmp_lt_u32 s10, 48
	s_cselect_b32 s10, s36, s10
	s_cselect_b32 s5, 0, 15
	s_cselect_b32 s12, 1, 15
	s_lshl_b32 s10, s10, 5
	v_readlane_b32 s11, v254, 3
	s_add_i32 s10, s10, s11
	s_lshr_b32 s11, s10, 3
	s_mul_hi_u32 s11, s11, 0x24924925
	s_mul_i32 s14, s11, 56
	s_sub_i32 s26, s10, s14
	s_lshl_b32 s10, s11, 10
	s_lshl_b32 s11, s26, 8
	s_and_b32 s11, s11, 0x300
	s_or_b32 s10, s11, s10
	s_ashr_i32 s11, s10, 31
	s_lshl_b64 s[10:11], s[10:11], 11
	s_add_u32 s14, s30, s10
	s_addc_u32 s15, s31, s11
	s_lshl_b32 s10, s26, 17
	s_and_b32 s10, s10, 0x780000
	s_add_u32 s26, s34, s10
	v_mov_b32_e32 v2, 0
	s_mov_b32 s13, 3
	s_addc_u32 s27, s35, 0
	v_mov_b32_e32 v3, v2
	v_mov_b64_e32 v[4:5], v[2:3]
	v_mov_b64_e32 v[6:7], v[2:3]
	v_mov_b64_e32 v[8:9], v[2:3]
	v_mov_b64_e32 v[10:11], v[2:3]
	v_mov_b64_e32 v[12:13], v[2:3]
	v_mov_b64_e32 v[14:15], v[2:3]
	v_mov_b64_e32 v[16:17], v[2:3]
	s_waitcnt vmcnt(5)
	v_mov_b64_e32 v[34:35], v[2:3]
	v_mov_b64_e32 v[36:37], v[2:3]
	s_waitcnt vmcnt(4)
	v_mov_b64_e32 v[38:39], v[2:3]
	v_mov_b64_e32 v[40:41], v[2:3]
	s_waitcnt vmcnt(3)
	v_mov_b64_e32 v[42:43], v[2:3]
	v_mov_b64_e32 v[44:45], v[2:3]
	s_waitcnt vmcnt(2)
	v_mov_b64_e32 v[46:47], v[2:3]
	v_mov_b64_e32 v[48:49], v[2:3]
	v_mov_b64_e32 v[18:19], v[2:3]
	v_mov_b64_e32 v[20:21], v[2:3]
	v_mov_b64_e32 v[22:23], v[2:3]
	v_mov_b64_e32 v[24:25], v[2:3]
	v_mov_b64_e32 v[26:27], v[2:3]
	v_mov_b64_e32 v[28:29], v[2:3]
	v_mov_b64_e32 v[30:31], v[2:3]
	v_mov_b64_e32 v[32:33], v[2:3]
	s_waitcnt vmcnt(1)
	v_mov_b64_e32 v[50:51], v[2:3]
	v_mov_b64_e32 v[52:53], v[2:3]
	s_waitcnt vmcnt(0)
	v_mov_b64_e32 v[54:55], v[2:3]
	v_mov_b64_e32 v[56:57], v[2:3]
	v_mov_b64_e32 v[58:59], v[2:3]
	v_mov_b64_e32 v[60:61], v[2:3]
	v_mov_b64_e32 v[62:63], v[2:3]
	v_mov_b64_e32 v[64:65], v[2:3]
	v_mov_b64_e32 v[66:67], v[2:3]
	v_mov_b64_e32 v[68:69], v[2:3]
	v_mov_b64_e32 v[70:71], v[2:3]
	v_mov_b64_e32 v[72:73], v[2:3]
	v_mov_b64_e32 v[74:75], v[2:3]
	v_mov_b64_e32 v[76:77], v[2:3]
	v_mov_b64_e32 v[78:79], v[2:3]
	v_mov_b64_e32 v[80:81], v[2:3]
	v_mov_b64_e32 v[98:99], v[2:3]
	v_mov_b64_e32 v[100:101], v[2:3]
	v_mov_b64_e32 v[102:103], v[2:3]
	v_mov_b64_e32 v[104:105], v[2:3]
	v_mov_b64_e32 v[106:107], v[2:3]
	v_mov_b64_e32 v[108:109], v[2:3]
	v_mov_b64_e32 v[110:111], v[2:3]
	v_mov_b64_e32 v[112:113], v[2:3]
	v_mov_b64_e32 v[82:83], v[2:3]
	v_mov_b64_e32 v[84:85], v[2:3]
	v_mov_b64_e32 v[86:87], v[2:3]
	v_mov_b64_e32 v[88:89], v[2:3]
	v_mov_b64_e32 v[90:91], v[2:3]
	v_mov_b64_e32 v[92:93], v[2:3]
	v_mov_b64_e32 v[94:95], v[2:3]
	v_mov_b64_e32 v[96:97], v[2:3]
	v_mov_b64_e32 v[114:115], v[2:3]
	v_mov_b64_e32 v[116:117], v[2:3]
	v_mov_b64_e32 v[118:119], v[2:3]
	v_mov_b64_e32 v[120:121], v[2:3]
	v_mov_b64_e32 v[122:123], v[2:3]
	v_mov_b64_e32 v[124:125], v[2:3]
	v_mov_b64_e32 v[126:127], v[2:3]
	v_mov_b64_e32 v[128:129], v[2:3]
	v_add_u32_e32 v232, s91, v170
	v_add_u32_e32 v233, s1, v170
	v_add_u32_e32 v234, s76, v170
	v_add_u32_e32 v235, v184, v185
	v_add_u32_e32 v236, v184, v186
	v_add_u32_e32 v237, v187, v175
.LBB0_311:
	ds_read_b128 v[162:165], v235
	ds_read_b128 v[166:169], v235 offset:4608
	ds_read_b128 v[176:179], v236 offset:36864
	ds_read_b128 v[180:183], v236 offset:41472
	ds_read_b128 v[216:219], v236 offset:46080
	ds_read_b128 v[220:223], v236 offset:50688
	ds_read_b128 v[224:227], v189 offset:32
	ds_read_b128 v[228:231], v189 offset:4640
	s_add_i32 s28, s13, -3
	s_cmp_lt_u32 s28, 14
	s_cselect_b64 s[38:39], -1, 0
	s_and_b64 s[10:11], s[38:39], exec
	s_cselect_b32 s11, s9, s27
	s_cselect_b32 s10, s8, s26
	s_cselect_b32 s41, s7, s15
	s_cselect_b32 s40, s6, s14
	s_add_i32 s29, s13, -1
	s_waitcnt lgkmcnt(5)
	v_mfma_f32_32x32x16_bf16 v[114:129], v[176:179], v[162:165], v[114:129]
	v_mfma_f32_32x32x16_bf16 v[82:97], v[176:179], v[166:169], v[82:97]
	s_waitcnt lgkmcnt(4)
	v_mfma_f32_32x32x16_bf16 v[98:113], v[180:183], v[162:165], v[98:113]
	v_mfma_f32_32x32x16_bf16 v[66:81], v[180:183], v[166:169], v[66:81]
	s_waitcnt lgkmcnt(3)
	v_mfma_f32_32x32x16_bf16 v[50:65], v[216:219], v[162:165], v[50:65]
	s_and_b64 s[38:39], s[38:39], exec
	s_cselect_b32 s29, s29, s5
	v_mfma_f32_32x32x16_bf16 v[18:33], v[216:219], v[166:169], v[18:33]
	s_waitcnt lgkmcnt(2)
	v_mfma_f32_32x32x16_bf16 v[34:49], v[220:223], v[162:165], v[34:49]
	ds_read_b128 v[162:165], v190 offset:36896
	ds_read_b128 v[176:179], v190 offset:41504
	v_mfma_f32_32x32x16_bf16 v[2:17], v[220:223], v[166:169], v[2:17]
	s_lshl_b32 s96, s29, 7
	s_add_u32 s100, s40, s96
	s_addc_u32 s101, s41, 0
	s_waitcnt vmcnt(3)
	ds_write_b128 v191, v[138:141] offset:9216
	ds_write_b128 v191, v[134:137]
	global_load_dwordx4 v[134:137], v170, s[100:101]
	global_load_dwordx4 v[138:141], v232, s[100:101]
	ds_write_b128 v191, v[130:133] offset:18432
	ds_write_b128 v191, v[142:145] offset:27648
	global_load_dwordx4 v[130:133], v233, s[100:101]
	global_load_dwordx4 v[142:145], v234, s[100:101]
	ds_read_b128 v[166:169], v190 offset:46112
	ds_read_b128 v[180:183], v190 offset:50720
	ds_read_b128 v[216:219], v189 offset:64
	ds_read_b128 v[220:223], v189 offset:4672
	s_waitcnt lgkmcnt(9)
	v_mfma_f32_32x32x16_bf16 v[114:129], v[162:165], v[224:227], v[114:129]
	v_mfma_f32_32x32x16_bf16 v[82:97], v[162:165], v[228:231], v[82:97]
	s_waitcnt lgkmcnt(8)
	v_mfma_f32_32x32x16_bf16 v[98:113], v[176:179], v[224:227], v[98:113]
	v_mfma_f32_32x32x16_bf16 v[66:81], v[176:179], v[228:231], v[66:81]
	s_waitcnt lgkmcnt(3)
	v_mfma_f32_32x32x16_bf16 v[50:65], v[166:169], v[224:227], v[50:65]
	v_mfma_f32_32x32x16_bf16 v[18:33], v[166:169], v[228:231], v[18:33]
	ds_read_b128 v[162:165], v190 offset:36928
	ds_read_b128 v[166:169], v190 offset:41536
	s_waitcnt lgkmcnt(4)
	v_mfma_f32_32x32x16_bf16 v[34:49], v[180:183], v[224:227], v[34:49]
	v_mfma_f32_32x32x16_bf16 v[2:17], v[180:183], v[228:231], v[2:17]
	s_add_u32 s100, s10, s96
	s_addc_u32 s101, s11, 0
	s_waitcnt vmcnt(6)
	ds_write_b128 v208, v[154:157] offset:9216
	s_waitcnt vmcnt(5)
	ds_write_b128 v208, v[146:149]
	global_load_dwordx4 v[146:149], v170, s[100:101]
	global_load_dwordx4 v[154:157], v232, s[100:101]
	ds_read_b128 v[176:179], v190 offset:46144
	ds_read_b128 v[180:183], v190 offset:50752
	ds_read_b128 v[224:227], v189 offset:96
	ds_read_b128 v[228:231], v189 offset:4704
	s_waitcnt lgkmcnt(7)
	v_mfma_f32_32x32x16_bf16 v[114:129], v[162:165], v[216:219], v[114:129]
	v_mfma_f32_32x32x16_bf16 v[82:97], v[162:165], v[220:223], v[82:97]
	s_waitcnt lgkmcnt(6)
	v_mfma_f32_32x32x16_bf16 v[98:113], v[166:169], v[216:219], v[98:113]
	v_mfma_f32_32x32x16_bf16 v[66:81], v[166:169], v[220:223], v[66:81]
	s_waitcnt lgkmcnt(3)
	v_mfma_f32_32x32x16_bf16 v[50:65], v[176:179], v[216:219], v[50:65]
	ds_read_b128 v[162:165], v190 offset:36960
	ds_read_b128 v[166:169], v190 offset:41568
	v_mfma_f32_32x32x16_bf16 v[18:33], v[176:179], v[220:223], v[18:33]
	s_waitcnt lgkmcnt(4)
	v_mfma_f32_32x32x16_bf16 v[34:49], v[180:183], v[216:219], v[34:49]
	v_mfma_f32_32x32x16_bf16 v[2:17], v[180:183], v[220:223], v[2:17]
	ds_write_b128 v208, v[150:153] offset:18432
	s_waitcnt vmcnt(6)
	ds_write_b128 v208, v[158:161] offset:27648
	global_load_dwordx4 v[150:153], v233, s[100:101]
	global_load_dwordx4 v[158:161], v234, s[100:101]
	ds_read_b128 v[176:179], v190 offset:46176
	ds_read_b128 v[180:183], v190 offset:50784
	s_waitcnt lgkmcnt(5)
	v_mfma_f32_32x32x16_bf16 v[114:129], v[162:165], v[224:227], v[114:129]
	v_mfma_f32_32x32x16_bf16 v[82:97], v[162:165], v[228:231], v[82:97]
	s_waitcnt lgkmcnt(4)
	v_mfma_f32_32x32x16_bf16 v[98:113], v[166:169], v[224:227], v[98:113]
	v_mfma_f32_32x32x16_bf16 v[66:81], v[166:169], v[228:231], v[66:81]
	s_waitcnt lgkmcnt(1)
	v_mfma_f32_32x32x16_bf16 v[50:65], v[176:179], v[224:227], v[50:65]
	v_mfma_f32_32x32x16_bf16 v[18:33], v[176:179], v[228:231], v[18:33]
	s_waitcnt lgkmcnt(0)
	v_mfma_f32_32x32x16_bf16 v[34:49], v[180:183], v[224:227], v[34:49]
	v_mfma_f32_32x32x16_bf16 v[2:17], v[180:183], v[228:231], v[2:17]
	s_barrier
	ds_read_b128 v[162:165], v209
	ds_read_b128 v[166:169], v209 offset:4608
	ds_read_b128 v[176:179], v210
	ds_read_b128 v[180:183], v210 offset:4608
	ds_read_b128 v[216:219], v210 offset:9216
	ds_read_b128 v[220:223], v210 offset:13824
	ds_read_b128 v[224:227], v237 offset:32
	ds_read_b128 v[228:231], v211 offset:32
	s_cmp_lt_u32 s28, 13
	s_cselect_b64 s[10:11], -1, 0
	s_and_b64 s[10:11], s[10:11], exec
	s_cselect_b32 s39, s7, s15
	s_cselect_b32 s38, s6, s14
	s_cselect_b32 s11, s9, s27
	s_cselect_b32 s10, s8, s26
	s_waitcnt lgkmcnt(5)
	v_mfma_f32_32x32x16_bf16 v[114:129], v[176:179], v[162:165], v[114:129]
	v_mfma_f32_32x32x16_bf16 v[82:97], v[176:179], v[166:169], v[82:97]
	s_waitcnt lgkmcnt(4)
	v_mfma_f32_32x32x16_bf16 v[98:113], v[180:183], v[162:165], v[98:113]
	v_mfma_f32_32x32x16_bf16 v[66:81], v[180:183], v[166:169], v[66:81]
	s_waitcnt lgkmcnt(3)
	v_mfma_f32_32x32x16_bf16 v[50:65], v[216:219], v[162:165], v[50:65]
	v_add_u32_e32 v174, v188, v175
	s_cselect_b32 s29, s13, s12
	v_mfma_f32_32x32x16_bf16 v[18:33], v[216:219], v[166:169], v[18:33]
	s_waitcnt lgkmcnt(2)
	v_mfma_f32_32x32x16_bf16 v[34:49], v[220:223], v[162:165], v[34:49]
	ds_read_b128 v[162:165], v174 offset:32
	ds_read_b128 v[176:179], v212 offset:32
	v_mfma_f32_32x32x16_bf16 v[2:17], v[220:223], v[166:169], v[2:17]
	s_lshl_b32 s96, s29, 7
	s_add_u32 s100, s38, s96
	s_addc_u32 s101, s39, 0
	s_waitcnt vmcnt(6)
	ds_write_b128 v215, v[138:141] offset:9216
	ds_write_b128 v215, v[134:137]
	global_load_dwordx4 v[134:137], v170, s[100:101]
	global_load_dwordx4 v[138:141], v232, s[100:101]
	s_waitcnt vmcnt(7)
	ds_write_b128 v215, v[130:133] offset:18432
	s_waitcnt vmcnt(6)
	ds_write_b128 v215, v[142:145] offset:27648
	global_load_dwordx4 v[130:133], v233, s[100:101]
	global_load_dwordx4 v[142:145], v234, s[100:101]
	ds_read_b128 v[166:169], v213 offset:32
	ds_read_b128 v[180:183], v214 offset:32
	ds_read_b128 v[216:219], v237 offset:64
	ds_read_b128 v[220:223], v211 offset:64
	s_waitcnt lgkmcnt(9)
	v_mfma_f32_32x32x16_bf16 v[114:129], v[162:165], v[224:227], v[114:129]
	v_mfma_f32_32x32x16_bf16 v[82:97], v[162:165], v[228:231], v[82:97]
	s_waitcnt lgkmcnt(8)
	v_mfma_f32_32x32x16_bf16 v[98:113], v[176:179], v[224:227], v[98:113]
	v_mfma_f32_32x32x16_bf16 v[66:81], v[176:179], v[228:231], v[66:81]
	s_waitcnt lgkmcnt(3)
	v_mfma_f32_32x32x16_bf16 v[50:65], v[166:169], v[224:227], v[50:65]
	v_mfma_f32_32x32x16_bf16 v[18:33], v[166:169], v[228:231], v[18:33]
	ds_read_b128 v[162:165], v174 offset:64
	ds_read_b128 v[166:169], v212 offset:64
	s_waitcnt lgkmcnt(4)
	v_mfma_f32_32x32x16_bf16 v[34:49], v[180:183], v[224:227], v[34:49]
	v_mfma_f32_32x32x16_bf16 v[2:17], v[180:183], v[228:231], v[2:17]
	s_add_u32 s100, s10, s96
	s_addc_u32 s101, s11, 0
	s_waitcnt vmcnt(6)
	ds_write_b128 v215, v[154:157] offset:46080
	ds_write_b128 v215, v[146:149] offset:36864
	global_load_dwordx4 v[146:149], v170, s[100:101]
	global_load_dwordx4 v[154:157], v232, s[100:101]
	ds_read_b128 v[176:179], v213 offset:64
	ds_read_b128 v[180:183], v214 offset:64
	ds_read_b128 v[224:227], v237 offset:96
	ds_read_b128 v[228:231], v211 offset:96
	s_waitcnt lgkmcnt(7)
; DI unsigned pk2(float lo, float hi) { f32x2 v = {lo, hi}; bf16x2v b = __builtin_convertvector(v, bf16x2v); return __builtin_bit_cast(unsigned, b); }
; DI bf16_t f2bf(float x) { return (bf16_t)(pk2(x, 0.f) & 0xffffu); }
; DI float sigmoidf_(float x) { return __builtin_amdgcn_rcpf(1.f + __builtin_amdgcn_exp2f(-LOG2E * x)); }
; DI float siluf_(float x) { return x * __builtin_amdgcn_rcpf(1.f + __builtin_amdgcn_exp2f(-LOG2E * x)); }
; DI int swz32(int s) { return (s & ~12) | ((s & 4) << 1) | ((s & 8) >> 1); }
;   DI void operator()(int tok0, int feat0, f32x16 (&acc)[2][2], int r, int hh) const {
;     const int seg = feat0 >> 9, c0 = feat0 & 511;
; #pragma unroll
;     for (int mt = 0; mt < 2; ++mt) {
;       const int tok = tok0 + mt * 32 + r, b = tok >> 14, s = tok & (SEQ - 1);
; #pragma unroll
;       for (int nt = 0; nt < 2; ++nt)
; #pragma unroll
;         for (int gp = 0; gp < 2; ++gp) {
;           const int c = c0 + nt * 32 + 16 * hh + 8 * gp;
;           float v[8];
; #pragma unroll
;           for (int e = 0; e < 8; ++e) v[e] = acc[nt][mt][8 * gp + e];
;           if (seg == 0 || seg == 3) {
;             u32x4 o = {pk2(siluf_(v[0]), siluf_(v[1])), pk2(siluf_(v[2]), siluf_(v[3])), pk2(siluf_(v[4]), siluf_(v[5])), pk2(siluf_(v[6]), siluf_(v[7]))};
;             *(u32x4*)((seg == 0 ? aq : ag) + (size_t)tok * 512 + c) = o;
;           } else if (seg == 1) {
; #pragma unroll
;             for (int h2 = 0; h2 < 2; ++h2) {
;               f32x4 lbv = *(const f32x4*)(lb + c + 4 * h2), o;
; #pragma unroll
;               for (int e = 0; e < 4; ++e) o[e] = __logf(lbv[e] + (1.f - lbv[e]) * sigmoidf_(v[4 * h2 + e]));
;               *(f32x4*)(alf + (size_t)tok * 512 + c + 4 * h2) = o;
;             }
;           } else if (seg == 4 || seg == 5) {
;             const float sc = seg == 4 ? 0.125f * LOG2E : 1.f;
;             u32x4 o = {pk2(v[0] * sc, v[1] * sc), pk2(v[2] * sc, v[3] * sc), pk2(v[4] * sc, v[5] * sc), pk2(v[6] * sc, v[7] * sc)};
;             *(u32x4*)((seg == 4 ? bq : bk) + (size_t)tok * 512 + c) = o;
;           } else {
;             bf16_t* dst = (seg == 2 ? aiT : bvT) + ((size_t)((b * 4 + (c >> 7)) * 128 + (c & 127))) * SEQ + (seg == 2 ? s : swz32(s));
; #pragma unroll
;             for (int e = 0; e < 8; ++e) dst[(size_t)e * SEQ] = f2bf(v[e]);
	v_mfma_f32_32x32x16_bf16 v[114:129], v[162:165], v[216:219], v[114:129]
	v_mfma_f32_32x32x16_bf16 v[82:97], v[162:165], v[220:223], v[82:97]
	s_waitcnt lgkmcnt(6)
	v_mfma_f32_32x32x16_bf16 v[98:113], v[166:169], v[216:219], v[98:113]
	v_mfma_f32_32x32x16_bf16 v[66:81], v[166:169], v[220:223], v[66:81]
	s_waitcnt lgkmcnt(3)
	v_mfma_f32_32x32x16_bf16 v[50:65], v[176:179], v[216:219], v[50:65]
	ds_read_b128 v[162:165], v174 offset:96
	ds_read_b128 v[166:169], v212 offset:96
	v_mfma_f32_32x32x16_bf16 v[18:33], v[176:179], v[220:223], v[18:33]
	s_waitcnt lgkmcnt(4)
	v_mfma_f32_32x32x16_bf16 v[34:49], v[180:183], v[216:219], v[34:49]
	v_mfma_f32_32x32x16_bf16 v[2:17], v[180:183], v[220:223], v[2:17]
	s_waitcnt vmcnt(7)
	ds_write_b128 v215, v[150:153] offset:55296
	s_waitcnt vmcnt(6)
	ds_write_b128 v215, v[158:161] offset:64512
	global_load_dwordx4 v[150:153], v233, s[100:101]
	global_load_dwordx4 v[158:161], v234, s[100:101]
	ds_read_b128 v[176:179], v213 offset:96
	ds_read_b128 v[180:183], v214 offset:96
	s_waitcnt lgkmcnt(5)
	v_mfma_f32_32x32x16_bf16 v[114:129], v[162:165], v[224:227], v[114:129]
	v_mfma_f32_32x32x16_bf16 v[82:97], v[162:165], v[228:231], v[82:97]
	s_waitcnt lgkmcnt(4)
	v_mfma_f32_32x32x16_bf16 v[98:113], v[166:169], v[224:227], v[98:113]
	v_mfma_f32_32x32x16_bf16 v[66:81], v[166:169], v[228:231], v[66:81]
	s_waitcnt lgkmcnt(1)
	v_mfma_f32_32x32x16_bf16 v[50:65], v[176:179], v[224:227], v[50:65]
	v_mfma_f32_32x32x16_bf16 v[18:33], v[176:179], v[228:231], v[18:33]
	s_waitcnt lgkmcnt(0)
	v_mfma_f32_32x32x16_bf16 v[34:49], v[180:183], v[224:227], v[34:49]
	v_mfma_f32_32x32x16_bf16 v[2:17], v[180:183], v[228:231], v[2:17]
	s_add_i32 s13, s13, 2
	s_cmp_gt_u32 s28, 13
	s_barrier
	s_cbranch_scc0 .LBB0_311
	v_mov_b32_e32 v0, v192
	s_ashr_i32 s2, s2, 5
	v_ashrrev_i32_e32 v162, 1, v0
	v_and_b32_e32 v162, 0xffffff80, v162
	v_lshrrev_b32_e32 v165, 1, v0
	v_add_u32_e32 v162, s3, v162
	v_and_b32_e32 v164, 0xdf, v0
	v_and_b32_e32 v0, 16, v165
	s_movk_i32 s3, 0x180
	v_and_or_b32 v216, v162, s3, v0
	s_movk_i32 s3, 0x200
	v_ashrrev_i32_e32 v163, 9, v162
	v_cmp_gt_u32_e64 s[12:13], s3, v162
	s_movk_i32 s3, 0x1ff
	v_cmp_lt_u32_e32 vcc, s3, v162
	v_cmp_ne_u32_e64 s[6:7], 3, v163
	s_and_b64 s[26:27], vcc, s[6:7]
	v_and_b32_e32 v0, 0xfffffc00, v162
	v_cmp_eq_u32_e32 vcc, 4, v163
	v_mov_b32_e32 v162, 0x3e38aa3b
	v_cmp_ne_u32_e64 s[8:9], 1, v163
	v_cmp_eq_u32_e64 s[10:11], 2, v163
	v_cndmask_b32_e32 v174, 1.0, v162, vcc
	v_bfrev_b32_e32 v162, 48
	v_mov_b32_e32 v163, 0xa000000
	v_or_b32_e32 v180, s4, v164
	v_cndmask_b32_e32 v172, v162, v163, vcc
	v_mov_b32_e32 v162, s4
	s_and_b32 s37, s2, 0xfffffe00
	s_movk_i32 s2, 0x3fd3
	v_bitop3_b32 v163, v164, s53, v162 bitop3:0xc8
	v_bitop3_b32 v162, v164, s2, v162 bitop3:0xc8
	v_lshlrev_b32_e32 v164, 1, v180
	s_movk_i32 s3, 0x800
	v_and_b32_e32 v218, 8, v164
	v_and_b32_e32 v219, 4, v165
	v_cmp_ne_u32_e64 s[6:7], s3, v0
	v_mov_b32_e32 v0, 0x6000000
	v_or3_b32 v162, v162, v218, v219
	v_ashrrev_i32_e32 v181, 31, v180
	v_cndmask_b32_e64 v0, v207, v0, s[10:11]
	v_mov_b32_e32 v173, v1
	v_cndmask_b32_e64 v217, v162, v163, s[10:11]
	v_lshlrev_b64 v[178:179], 10, v[180:181]
	v_lshlrev_b64 v[176:177], 11, v[180:181]
	s_and_saveexec_b64 s[2:3], s[26:27]
	s_xor_b64 s[4:5], exec, s[2:3]
	s_cbranch_execz .LBB0_322
	s_and_saveexec_b64 s[2:3], s[8:9]
	s_xor_b64 s[14:15], exec, s[2:3]
	s_cbranch_execz .LBB0_319
	s_and_saveexec_b64 s[2:3], s[6:7]
	s_xor_b64 s[28:29], exec, s[2:3]
	s_cbranch_execz .LBB0_316
	v_or_b32_e32 v164, s37, v216
	v_ashrrev_i32_e32 v165, 31, v164
	v_lshl_add_u64 v[162:163], s[16:17], 0, v[0:1]
	v_lshlrev_b64 v[164:165], 15, v[164:165]
	v_lshl_add_u64 v[162:163], v[162:163], 0, v[164:165]
	v_lshlrev_b32_e32 v164, 1, v217
	v_mov_b32_e32 v165, v1
	v_lshl_add_u64 v[162:163], v[162:163], 0, v[164:165]
	v_cvt_pk_bf16_f32 v164, v114, s0
	global_store_short v[162:163], v164, off
	v_add_co_u32_e32 v164, vcc, 0x8000, v162
	v_cvt_pk_bf16_f32 v166, v115, s0
	s_nop 0
	v_addc_co_u32_e32 v165, vcc, 0, v163, vcc
	global_store_short v[164:165], v166, off
	v_add_co_u32_e32 v164, vcc, s65, v162
	v_cvt_pk_bf16_f32 v166, v116, s0
	s_nop 0
	v_addc_co_u32_e32 v165, vcc, 0, v163, vcc
	global_store_short v[164:165], v166, off
	v_add_co_u32_e32 v164, vcc, 0x18000, v162
	v_cvt_pk_bf16_f32 v166, v117, s0
	s_nop 0
	v_addc_co_u32_e32 v165, vcc, 0, v163, vcc
	global_store_short v[164:165], v166, off
	v_add_co_u32_e32 v164, vcc, s91, v162
	v_cvt_pk_bf16_f32 v166, v118, s0
	s_nop 0
	v_addc_co_u32_e32 v165, vcc, 0, v163, vcc
	global_store_short v[164:165], v166, off
	v_add_co_u32_e32 v164, vcc, 0x28000, v162
	v_cvt_pk_bf16_f32 v166, v119, s0
	s_nop 0
	v_addc_co_u32_e32 v165, vcc, 0, v163, vcc
	global_store_short v[164:165], v166, off
	v_add_co_u32_e32 v164, vcc, 0x30000, v162
	v_cvt_pk_bf16_f32 v166, v120, s0
	s_nop 0
	v_addc_co_u32_e32 v165, vcc, 0, v163, vcc
	v_add_co_u32_e32 v162, vcc, 0x38000, v162
	global_store_short v[164:165], v166, off
	v_cvt_pk_bf16_f32 v164, v121, s0
	v_addc_co_u32_e32 v163, vcc, 0, v163, vcc
	global_store_short v[162:163], v164, off

; #define MFMA32(a, b, c) __builtin_amdgcn_mfma_f32_32x32x16_bf16((a), (b), (c), 0, 0, 0)
; DI float xmax32(float v) { const u32x2 r_ = __builtin_amdgcn_permlane32_swap(__float_as_uint(v), __float_as_uint(v), false, false); return fmaxf(__uint_as_float(r_[0]), __uint_as_float(r_[1])); }
; template <int DVT, bool FOX>
; DI void attn_step(const char* kb, const bf16x8 (&qf)[4], f32x16 (&o)[DVT], float& m, float& l, const bool diag, const int j, const int tq, const int r, const int hh) {
;     ...
; #pragma unroll
;   for (int ks = 0; ks < 4; ++ks)
; #pragma unroll
;     for (int kt = 0; kt < 2; ++kt) st[kt] = MFMA32(kf[ks * 2 + kt], qf[ks], st[kt]);
;   bf16x8 va[DVT], vn[DVT];
; #pragma unroll
;   for (int d = 0; d < DVT; ++d) va[d] = *(const bf16x8*)(vb + (d * 32 + r) * LROW + (8 * hh) * 2);
;   __builtin_amdgcn_sched_barrier(0);
;   {
;     const f32x2 mm = {m, m};
; #pragma unroll
;     for (int kt = 0; kt < 2; ++kt)
; #pragma unroll
;       for (int i = 0; i < 8; ++i) { f32x2 z = {st[kt][2 * i], st[kt][2 * i + 1]}; z = z - mm; st[kt][2 * i] = z[0]; st[kt][2 * i + 1] = z[1]; }
;   }
;   if (FOX) {
;     if (diag) {
; #pragma unroll
;       for (int kt = 0; kt < 2; ++kt)
; #pragma unroll
;         for (int i = 0; i < 16; ++i) {
;           const int key = j * 64 + kt * 32 + (i & 3) + 8 * (i >> 2) + 4 * hh;
;           if (key > tq) st[kt][i] = -INFINITY;
;         }
;     }
;   }
;   float mx;
;   {
;     float a0 = fmaxf(fmaxf(st[0][0], st[0][1]), st[0][2]), a1 = fmaxf(fmaxf(st[1][0], st[1][1]), st[1][2]);
; #pragma unroll
;     for (int i = 3; i < 15; i += 2) { a0 = fmaxf(fmaxf(a0, st[0][i]), st[0][i + 1]); a1 = fmaxf(fmaxf(a1, st[1][i]), st[1][i + 1]); }
;     mx = fmaxf(fmaxf(a0, a1), fmaxf(st[0][15], st[1][15]));
;   }
;   mx = xmax32(mx);
;   if (__any(diag || mx > 8.f)) {
;     const float d = (diag || mx > 0.f) ? mx : 0.f;
;     const float alpha = diag ? 0.f : __builtin_amdgcn_exp2f(-d);
;     m += d;
;     l *= alpha;
; #pragma unroll
;     for (int dd = 0; dd < DVT; ++dd)
; #pragma unroll
;       for (int i = 0; i < 16; ++i) o[dd][i] *= alpha;
;     const f32x2 d2 = {d, d};
; #pragma unroll
;     for (int kt = 0; kt < 2; ++kt)
; #pragma unroll
;       for (int i = 0; i < 8; ++i) { f32x2 z = {st[kt][2 * i], st[kt][2 * i + 1]}; z = z - d2; st[kt][2 * i] = z[0]; st[kt][2 * i + 1] = z[1]; }
;   }
.LBB0_642:
	s_cmp_gt_i32 s3, s25
	s_cbranch_scc1 .LBB0_646
	ds_read_b128 v[2:5], v184
	ds_read_b128 v[6:9], v184 offset:32
	ds_read_b128 v[10:13], v184 offset:4608
	ds_read_b128 v[152:155], v184 offset:4640
	ds_read_b128 v[170:173], v184 offset:64
	ds_read_b128 v[174:177], v184 offset:96
	ds_read_b128 v[186:189], v184 offset:4672
	ds_read_b128 v[208:211], v184 offset:4704
	s_add_i32 s15, s26, s2
	s_cmp_eq_u32 s15, -1
	s_cselect_b64 s[22:23], -1, 0
	s_waitcnt lgkmcnt(7)
	v_mfma_f32_32x32x16_bf16 v[96:111], v[2:5], v[112:115], 0
	s_waitcnt lgkmcnt(5)
	v_mfma_f32_32x32x16_bf16 v[80:95], v[10:13], v[112:115], 0
	v_mfma_f32_32x32x16_bf16 v[96:111], v[6:9], v[116:119], v[96:111]
	s_waitcnt lgkmcnt(4)
	v_mfma_f32_32x32x16_bf16 v[80:95], v[152:155], v[116:119], v[80:95]
	ds_read_b128 v[152:155], v184 offset:9216
	ds_read_b128 v[10:13], v184 offset:13824
	ds_read_b128 v[6:9], v184 offset:18432
	ds_read_b128 v[2:5], v184 offset:23040
	s_waitcnt lgkmcnt(7)
	v_mfma_f32_32x32x16_bf16 v[96:111], v[170:173], v[120:123], v[96:111]
	s_waitcnt lgkmcnt(5)
	v_mfma_f32_32x32x16_bf16 v[80:95], v[186:189], v[120:123], v[80:95]
	v_mfma_f32_32x32x16_bf16 v[96:111], v[174:177], v[124:127], v[96:111]
	s_waitcnt lgkmcnt(4)
	v_mfma_f32_32x32x16_bf16 v[80:95], v[208:211], v[124:127], v[80:95]
	s_nop 9
	v_add_f32_e64 v170, v96, -v168
	v_add_f32_e64 v171, v97, -v168
	v_add_f32_e64 v172, v98, -v168
	v_add_f32_e64 v173, v99, -v168
	v_pk_add_f32 v[96:97], v[80:81], v[168:169] op_sel_hi:[1,0] neg_lo:[0,1] neg_hi:[0,1]
	v_pk_add_f32 v[98:99], v[82:83], v[168:169] op_sel_hi:[1,0] neg_lo:[0,1] neg_hi:[0,1]
	v_pk_add_f32 v[174:175], v[100:101], v[168:169] op_sel_hi:[1,0] neg_lo:[0,1] neg_hi:[0,1]
	v_pk_add_f32 v[100:101], v[84:85], v[168:169] op_sel_hi:[1,0] neg_lo:[0,1] neg_hi:[0,1]
	v_pk_add_f32 v[80:81], v[88:89], v[168:169] op_sel_hi:[1,0] neg_lo:[0,1] neg_hi:[0,1]
	v_max3_f32 v88, v170, v171, v172
	v_max3_f32 v89, v96, v97, v98
	v_pk_add_f32 v[176:177], v[102:103], v[168:169] op_sel_hi:[1,0] neg_lo:[0,1] neg_hi:[0,1]
	v_pk_add_f32 v[86:87], v[86:87], v[168:169] op_sel_hi:[1,0] neg_lo:[0,1] neg_hi:[0,1]
	v_max3_f32 v88, v88, v173, v174
	v_max3_f32 v89, v89, v99, v100
	v_pk_add_f32 v[102:103], v[104:105], v[168:169] op_sel_hi:[1,0] neg_lo:[0,1] neg_hi:[0,1]
	v_max3_f32 v88, v88, v175, v176
	v_max3_f32 v89, v89, v101, v86
	v_pk_add_f32 v[104:105], v[106:107], v[168:169] op_sel_hi:[1,0] neg_lo:[0,1] neg_hi:[0,1]
	v_pk_add_f32 v[82:83], v[90:91], v[168:169] op_sel_hi:[1,0] neg_lo:[0,1] neg_hi:[0,1]
	v_max3_f32 v88, v88, v177, v102
	v_max3_f32 v89, v89, v87, v80
	v_pk_add_f32 v[106:107], v[108:109], v[168:169] op_sel_hi:[1,0] neg_lo:[0,1] neg_hi:[0,1]
	v_pk_add_f32 v[84:85], v[92:93], v[168:169] op_sel_hi:[1,0] neg_lo:[0,1] neg_hi:[0,1]
	v_max3_f32 v88, v88, v103, v104
	v_max3_f32 v89, v89, v81, v82
	v_pk_add_f32 v[108:109], v[110:111], v[168:169] op_sel_hi:[1,0] neg_lo:[0,1] neg_hi:[0,1]
	v_pk_add_f32 v[14:15], v[94:95], v[168:169] op_sel_hi:[1,0] neg_lo:[0,1] neg_hi:[0,1]
	v_max3_f32 v88, v88, v105, v106
	v_max3_f32 v89, v89, v83, v84
	v_max3_f32 v88, v88, v107, v108
	v_max3_f32 v89, v89, v85, v14
	v_max_f32_e32 v90, v109, v15
	v_max3_f32 v88, v88, v89, v90
	v_mov_b32_e32 v89, v88
	s_nop 1
	v_permlane32_swap_b32_e32 v88, v89
	v_max_f32_e32 v88, v88, v89
	v_cmp_lt_f32_e32 vcc, s92, v88
	s_or_b64 vcc, s[22:23], vcc
	s_cbranch_vccz .LBB0_645
	v_cmp_lt_f32_e32 vcc, 0, v88
	s_or_b64 vcc, s[22:23], vcc
	s_nop 0
	v_cndmask_b32_e32 v89, 0, v88, vcc
	v_exp_f32_e64 v88, -v89
	v_add_f32_e32 v168, v168, v89
	v_sub_f32_e32 v170, v170, v89
	v_sub_f32_e32 v171, v171, v89
	v_cndmask_b32_e64 v88, v88, 0, s[22:23]
	v_mul_f32_e32 v0, v0, v88
	v_pk_mul_f32 v[78:79], v[78:79], v[88:89] op_sel_hi:[1,0]
	v_pk_mul_f32 v[76:77], v[76:77], v[88:89] op_sel_hi:[1,0]
	v_pk_mul_f32 v[74:75], v[74:75], v[88:89] op_sel_hi:[1,0]
	v_pk_mul_f32 v[72:73], v[72:73], v[88:89] op_sel_hi:[1,0]
	v_pk_mul_f32 v[70:71], v[70:71], v[88:89] op_sel_hi:[1,0]
	v_pk_mul_f32 v[68:69], v[68:69], v[88:89] op_sel_hi:[1,0]
	v_pk_mul_f32 v[66:67], v[66:67], v[88:89] op_sel_hi:[1,0]
	v_pk_mul_f32 v[64:65], v[64:65], v[88:89] op_sel_hi:[1,0]
	v_pk_mul_f32 v[62:63], v[62:63], v[88:89] op_sel_hi:[1,0]
	v_pk_mul_f32 v[60:61], v[60:61], v[88:89] op_sel_hi:[1,0]
	v_pk_mul_f32 v[58:59], v[58:59], v[88:89] op_sel_hi:[1,0]
	v_pk_mul_f32 v[56:57], v[56:57], v[88:89] op_sel_hi:[1,0]
	v_pk_mul_f32 v[54:55], v[54:55], v[88:89] op_sel_hi:[1,0]
	v_pk_mul_f32 v[52:53], v[52:53], v[88:89] op_sel_hi:[1,0]
	v_pk_mul_f32 v[50:51], v[50:51], v[88:89] op_sel_hi:[1,0]
	v_pk_mul_f32 v[48:49], v[48:49], v[88:89] op_sel_hi:[1,0]
	v_pk_mul_f32 v[46:47], v[46:47], v[88:89] op_sel_hi:[1,0]
	v_pk_mul_f32 v[44:45], v[44:45], v[88:89] op_sel_hi:[1,0]
	v_pk_mul_f32 v[42:43], v[42:43], v[88:89] op_sel_hi:[1,0]
	v_pk_mul_f32 v[40:41], v[40:41], v[88:89] op_sel_hi:[1,0]
	v_pk_mul_f32 v[38:39], v[38:39], v[88:89] op_sel_hi:[1,0]
	v_pk_mul_f32 v[36:37], v[36:37], v[88:89] op_sel_hi:[1,0]
	v_pk_mul_f32 v[34:35], v[34:35], v[88:89] op_sel_hi:[1,0]
	v_pk_mul_f32 v[32:33], v[32:33], v[88:89] op_sel_hi:[1,0]
	v_pk_mul_f32 v[30:31], v[30:31], v[88:89] op_sel_hi:[1,0]
	v_pk_mul_f32 v[28:29], v[28:29], v[88:89] op_sel_hi:[1,0]
	v_pk_mul_f32 v[26:27], v[26:27], v[88:89] op_sel_hi:[1,0]
	v_pk_mul_f32 v[24:25], v[24:25], v[88:89] op_sel_hi:[1,0]
	v_pk_mul_f32 v[22:23], v[22:23], v[88:89] op_sel_hi:[1,0]
	v_pk_mul_f32 v[20:21], v[20:21], v[88:89] op_sel_hi:[1,0]
	v_pk_mul_f32 v[18:19], v[18:19], v[88:89] op_sel_hi:[1,0]
	v_pk_mul_f32 v[16:17], v[16:17], v[88:89] op_sel_hi:[1,0]
	v_sub_f32_e32 v172, v172, v89
	v_sub_f32_e32 v173, v173, v89
	v_sub_f32_e32 v174, v174, v89
	v_sub_f32_e32 v175, v175, v89
	v_sub_f32_e32 v176, v176, v89
	v_sub_f32_e32 v177, v177, v89
	v_sub_f32_e32 v102, v102, v89
	v_sub_f32_e32 v103, v103, v89
	v_sub_f32_e32 v104, v104, v89
	v_sub_f32_e32 v105, v105, v89
	v_sub_f32_e32 v106, v106, v89
	v_sub_f32_e32 v107, v107, v89
	v_sub_f32_e32 v108, v108, v89
	v_sub_f32_e32 v109, v109, v89
	v_sub_f32_e32 v96, v96, v89
	v_sub_f32_e32 v97, v97, v89
	v_sub_f32_e32 v98, v98, v89
	v_sub_f32_e32 v99, v99, v89
	v_sub_f32_e32 v100, v100, v89
	v_sub_f32_e32 v101, v101, v89
	v_sub_f32_e32 v86, v86, v89
	v_sub_f32_e32 v87, v87, v89
	v_sub_f32_e32 v80, v80, v89
	v_sub_f32_e32 v81, v81, v89
	v_sub_f32_e32 v82, v82, v89
	v_sub_f32_e32 v83, v83, v89
	v_sub_f32_e32 v84, v84, v89
	v_sub_f32_e32 v85, v85, v89
	v_sub_f32_e32 v14, v14, v89
	v_sub_f32_e32 v15, v15, v89

; #define MFMA32(a, b, c) __builtin_amdgcn_mfma_f32_32x32x16_bf16((a), (b), (c), 0, 0, 0)
; DI float xmax32(float v) { const u32x2 r_ = __builtin_amdgcn_permlane32_swap(__float_as_uint(v), __float_as_uint(v), false, false); return fmaxf(__uint_as_float(r_[0]), __uint_as_float(r_[1])); }
; template <int DVT, bool FOX>
; DI void attn_step(const char* kb, const bf16x8 (&qf)[4], f32x16 (&o)[DVT], float& m, float& l, const bool diag, const int j, const int tq, const int r, const int hh) {
;     ...
; #pragma unroll
;   for (int ks = 0; ks < 4; ++ks)
; #pragma unroll
;     for (int kt = 0; kt < 2; ++kt) st[kt] = MFMA32(kf[ks * 2 + kt], qf[ks], st[kt]);
;   bf16x8 va[DVT], vn[DVT];
; #pragma unroll
;   for (int d = 0; d < DVT; ++d) va[d] = *(const bf16x8*)(vb + (d * 32 + r) * LROW + (8 * hh) * 2);
;   __builtin_amdgcn_sched_barrier(0);
;   {
;     const f32x2 mm = {m, m};
; #pragma unroll
;     for (int kt = 0; kt < 2; ++kt)
; #pragma unroll
;       for (int i = 0; i < 8; ++i) { f32x2 z = {st[kt][2 * i], st[kt][2 * i + 1]}; z = z - mm; st[kt][2 * i] = z[0]; st[kt][2 * i + 1] = z[1]; }
;   }
;   if (FOX) {
;     if (diag) {
; #pragma unroll
;       for (int kt = 0; kt < 2; ++kt)
; #pragma unroll
;         for (int i = 0; i < 16; ++i) {
;           const int key = j * 64 + kt * 32 + (i & 3) + 8 * (i >> 2) + 4 * hh;
;           if (key > tq) st[kt][i] = -INFINITY;
;         }
;     }
;   }
;   float mx;
;   {
;     float a0 = fmaxf(fmaxf(st[0][0], st[0][1]), st[0][2]), a1 = fmaxf(fmaxf(st[1][0], st[1][1]), st[1][2]);
; #pragma unroll
;     for (int i = 3; i < 15; i += 2) { a0 = fmaxf(fmaxf(a0, st[0][i]), st[0][i + 1]); a1 = fmaxf(fmaxf(a1, st[1][i]), st[1][i + 1]); }
;     mx = fmaxf(fmaxf(a0, a1), fmaxf(st[0][15], st[1][15]));
;   }
;   mx = xmax32(mx);
;   if (__any(diag || mx > 8.f)) {
;     const float d = (diag || mx > 0.f) ? mx : 0.f;
;     const float alpha = diag ? 0.f : __builtin_amdgcn_exp2f(-d);
;     m += d;
;     l *= alpha;
; #pragma unroll
;     for (int dd = 0; dd < DVT; ++dd)
; #pragma unroll
;       for (int i = 0; i < 16; ++i) o[dd][i] *= alpha;
;     const f32x2 d2 = {d, d};
; #pragma unroll
;     for (int kt = 0; kt < 2; ++kt)
; #pragma unroll
;       for (int i = 0; i < 8; ++i) { f32x2 z = {st[kt][2 * i], st[kt][2 * i + 1]}; z = z - d2; st[kt][2 * i] = z[0]; st[kt][2 * i + 1] = z[1]; }
;   }
.LBB0_650:
	ds_read_b128 v[2:5], v184 offset:27904
	ds_read_b128 v[6:9], v184 offset:27936
	ds_read_b128 v[10:13], v184 offset:32512
	ds_read_b128 v[152:155], v184 offset:32544
	ds_read_b128 v[170:173], v184 offset:27968
	ds_read_b128 v[174:177], v184 offset:28000
	ds_read_b128 v[186:189], v184 offset:32576
	ds_read_b128 v[208:211], v184 offset:32608
	s_cmp_eq_u32 s25, s2
	s_cselect_b64 s[22:23], -1, 0
	s_waitcnt lgkmcnt(7)
	v_mfma_f32_32x32x16_bf16 v[96:111], v[2:5], v[112:115], 0
	s_waitcnt lgkmcnt(5)
	v_mfma_f32_32x32x16_bf16 v[80:95], v[10:13], v[112:115], 0
	v_mfma_f32_32x32x16_bf16 v[96:111], v[6:9], v[116:119], v[96:111]
	s_waitcnt lgkmcnt(4)
	v_mfma_f32_32x32x16_bf16 v[80:95], v[152:155], v[116:119], v[80:95]
	ds_read_b128 v[152:155], v184 offset:37120
	ds_read_b128 v[10:13], v184 offset:41728
	ds_read_b128 v[6:9], v184 offset:46336
	ds_read_b128 v[2:5], v184 offset:50944
	s_waitcnt lgkmcnt(7)
	v_mfma_f32_32x32x16_bf16 v[96:111], v[170:173], v[120:123], v[96:111]
	s_waitcnt lgkmcnt(5)
	v_mfma_f32_32x32x16_bf16 v[80:95], v[186:189], v[120:123], v[80:95]
	v_mfma_f32_32x32x16_bf16 v[96:111], v[174:177], v[124:127], v[96:111]
	s_waitcnt lgkmcnt(4)
	v_mfma_f32_32x32x16_bf16 v[80:95], v[208:211], v[124:127], v[80:95]
	s_nop 9
	v_add_f32_e64 v170, v96, -v168
	v_add_f32_e64 v171, v97, -v168
	v_add_f32_e64 v172, v98, -v168
	v_add_f32_e64 v173, v99, -v168
	v_pk_add_f32 v[96:97], v[80:81], v[168:169] op_sel_hi:[1,0] neg_lo:[0,1] neg_hi:[0,1]
	v_pk_add_f32 v[98:99], v[82:83], v[168:169] op_sel_hi:[1,0] neg_lo:[0,1] neg_hi:[0,1]
	v_pk_add_f32 v[174:175], v[100:101], v[168:169] op_sel_hi:[1,0] neg_lo:[0,1] neg_hi:[0,1]
	v_pk_add_f32 v[100:101], v[84:85], v[168:169] op_sel_hi:[1,0] neg_lo:[0,1] neg_hi:[0,1]
	v_pk_add_f32 v[80:81], v[88:89], v[168:169] op_sel_hi:[1,0] neg_lo:[0,1] neg_hi:[0,1]
	v_max3_f32 v88, v170, v171, v172
	v_max3_f32 v89, v96, v97, v98
	v_pk_add_f32 v[176:177], v[102:103], v[168:169] op_sel_hi:[1,0] neg_lo:[0,1] neg_hi:[0,1]
	v_pk_add_f32 v[86:87], v[86:87], v[168:169] op_sel_hi:[1,0] neg_lo:[0,1] neg_hi:[0,1]
	v_max3_f32 v88, v88, v173, v174
	v_max3_f32 v89, v89, v99, v100
	v_pk_add_f32 v[102:103], v[104:105], v[168:169] op_sel_hi:[1,0] neg_lo:[0,1] neg_hi:[0,1]
	v_max3_f32 v88, v88, v175, v176
	v_max3_f32 v89, v89, v101, v86
	v_pk_add_f32 v[104:105], v[106:107], v[168:169] op_sel_hi:[1,0] neg_lo:[0,1] neg_hi:[0,1]
	v_pk_add_f32 v[82:83], v[90:91], v[168:169] op_sel_hi:[1,0] neg_lo:[0,1] neg_hi:[0,1]
	v_max3_f32 v88, v88, v177, v102
	v_max3_f32 v89, v89, v87, v80
	v_pk_add_f32 v[106:107], v[108:109], v[168:169] op_sel_hi:[1,0] neg_lo:[0,1] neg_hi:[0,1]
	v_pk_add_f32 v[84:85], v[92:93], v[168:169] op_sel_hi:[1,0] neg_lo:[0,1] neg_hi:[0,1]
	v_max3_f32 v88, v88, v103, v104
	v_max3_f32 v89, v89, v81, v82
	v_pk_add_f32 v[108:109], v[110:111], v[168:169] op_sel_hi:[1,0] neg_lo:[0,1] neg_hi:[0,1]
	v_pk_add_f32 v[14:15], v[94:95], v[168:169] op_sel_hi:[1,0] neg_lo:[0,1] neg_hi:[0,1]
	v_max3_f32 v88, v88, v105, v106
	v_max3_f32 v89, v89, v83, v84
	v_max3_f32 v88, v88, v107, v108
	v_max3_f32 v89, v89, v85, v14
	v_max_f32_e32 v90, v109, v15
	v_max3_f32 v88, v88, v89, v90
	v_mov_b32_e32 v89, v88
	s_nop 1
	v_permlane32_swap_b32_e32 v88, v89
	v_max_f32_e32 v88, v88, v89
	v_cmp_lt_f32_e32 vcc, s92, v88
	s_or_b64 vcc, s[22:23], vcc
	s_cbranch_vccz .LBB0_652
	v_cmp_lt_f32_e32 vcc, 0, v88
	s_or_b64 vcc, s[22:23], vcc
	s_nop 0
	v_cndmask_b32_e32 v89, 0, v88, vcc
	v_exp_f32_e64 v88, -v89
	v_add_f32_e32 v168, v168, v89
	v_sub_f32_e32 v170, v170, v89
	v_sub_f32_e32 v171, v171, v89
	v_cndmask_b32_e64 v88, v88, 0, s[22:23]
	v_mul_f32_e32 v0, v0, v88
	v_pk_mul_f32 v[78:79], v[78:79], v[88:89] op_sel_hi:[1,0]
	v_pk_mul_f32 v[76:77], v[76:77], v[88:89] op_sel_hi:[1,0]
	v_pk_mul_f32 v[74:75], v[74:75], v[88:89] op_sel_hi:[1,0]
	v_pk_mul_f32 v[72:73], v[72:73], v[88:89] op_sel_hi:[1,0]
	v_pk_mul_f32 v[70:71], v[70:71], v[88:89] op_sel_hi:[1,0]
	v_pk_mul_f32 v[68:69], v[68:69], v[88:89] op_sel_hi:[1,0]
	v_pk_mul_f32 v[66:67], v[66:67], v[88:89] op_sel_hi:[1,0]
	v_pk_mul_f32 v[64:65], v[64:65], v[88:89] op_sel_hi:[1,0]
	v_pk_mul_f32 v[62:63], v[62:63], v[88:89] op_sel_hi:[1,0]
	v_pk_mul_f32 v[60:61], v[60:61], v[88:89] op_sel_hi:[1,0]
	v_pk_mul_f32 v[58:59], v[58:59], v[88:89] op_sel_hi:[1,0]
	v_pk_mul_f32 v[56:57], v[56:57], v[88:89] op_sel_hi:[1,0]
	v_pk_mul_f32 v[54:55], v[54:55], v[88:89] op_sel_hi:[1,0]
	v_pk_mul_f32 v[52:53], v[52:53], v[88:89] op_sel_hi:[1,0]
	v_pk_mul_f32 v[50:51], v[50:51], v[88:89] op_sel_hi:[1,0]
	v_pk_mul_f32 v[48:49], v[48:49], v[88:89] op_sel_hi:[1,0]
	v_pk_mul_f32 v[46:47], v[46:47], v[88:89] op_sel_hi:[1,0]
	v_pk_mul_f32 v[44:45], v[44:45], v[88:89] op_sel_hi:[1,0]
	v_pk_mul_f32 v[42:43], v[42:43], v[88:89] op_sel_hi:[1,0]
	v_pk_mul_f32 v[40:41], v[40:41], v[88:89] op_sel_hi:[1,0]
	v_pk_mul_f32 v[38:39], v[38:39], v[88:89] op_sel_hi:[1,0]
	v_pk_mul_f32 v[36:37], v[36:37], v[88:89] op_sel_hi:[1,0]
	v_pk_mul_f32 v[34:35], v[34:35], v[88:89] op_sel_hi:[1,0]
	v_pk_mul_f32 v[32:33], v[32:33], v[88:89] op_sel_hi:[1,0]
	v_pk_mul_f32 v[30:31], v[30:31], v[88:89] op_sel_hi:[1,0]
	v_pk_mul_f32 v[28:29], v[28:29], v[88:89] op_sel_hi:[1,0]
	v_pk_mul_f32 v[26:27], v[26:27], v[88:89] op_sel_hi:[1,0]
	v_pk_mul_f32 v[24:25], v[24:25], v[88:89] op_sel_hi:[1,0]
	v_pk_mul_f32 v[22:23], v[22:23], v[88:89] op_sel_hi:[1,0]
	v_pk_mul_f32 v[20:21], v[20:21], v[88:89] op_sel_hi:[1,0]
	v_pk_mul_f32 v[18:19], v[18:19], v[88:89] op_sel_hi:[1,0]
	v_pk_mul_f32 v[16:17], v[16:17], v[88:89] op_sel_hi:[1,0]
	v_sub_f32_e32 v172, v172, v89
	v_sub_f32_e32 v173, v173, v89
	v_sub_f32_e32 v174, v174, v89
	v_sub_f32_e32 v175, v175, v89
	v_sub_f32_e32 v176, v176, v89
	v_sub_f32_e32 v177, v177, v89
	v_sub_f32_e32 v102, v102, v89
	v_sub_f32_e32 v103, v103, v89
	v_sub_f32_e32 v104, v104, v89
	v_sub_f32_e32 v105, v105, v89
	v_sub_f32_e32 v106, v106, v89
	v_sub_f32_e32 v107, v107, v89
	v_sub_f32_e32 v108, v108, v89
	v_sub_f32_e32 v109, v109, v89
	v_sub_f32_e32 v96, v96, v89
	v_sub_f32_e32 v97, v97, v89
	v_sub_f32_e32 v98, v98, v89
	v_sub_f32_e32 v99, v99, v89
	v_sub_f32_e32 v100, v100, v89
	v_sub_f32_e32 v101, v101, v89
	v_sub_f32_e32 v86, v86, v89
	v_sub_f32_e32 v87, v87, v89
	v_sub_f32_e32 v80, v80, v89
	v_sub_f32_e32 v81, v81, v89
	v_sub_f32_e32 v82, v82, v89
	v_sub_f32_e32 v83, v83, v89
	v_sub_f32_e32 v84, v84, v89
	v_sub_f32_e32 v85, v85, v89
	v_sub_f32_e32 v14, v14, v89
	v_sub_f32_e32 v15, v15, v89

; #define MFMA32(a, b, c) __builtin_amdgcn_mfma_f32_32x32x16_bf16((a), (b), (c), 0, 0, 0)
; DI float xmax32(float v) { const u32x2 r_ = __builtin_amdgcn_permlane32_swap(__float_as_uint(v), __float_as_uint(v), false, false); return fmaxf(__uint_as_float(r_[0]), __uint_as_float(r_[1])); }
; template <int DVT, bool FOX>
; DI void attn_step(const char* kb, const bf16x8 (&qf)[4], f32x16 (&o)[DVT], float& m, float& l, const bool diag, const int j, const int tq, const int r, const int hh) {
;     ...
; #pragma unroll
;   for (int ks = 0; ks < 4; ++ks)
; #pragma unroll
;     for (int kt = 0; kt < 2; ++kt) st[kt] = MFMA32(kf[ks * 2 + kt], qf[ks], st[kt]);
;   bf16x8 va[DVT], vn[DVT];
; #pragma unroll
;   for (int d = 0; d < DVT; ++d) va[d] = *(const bf16x8*)(vb + (d * 32 + r) * LROW + (8 * hh) * 2);
;   __builtin_amdgcn_sched_barrier(0);
;   {
;     const f32x2 mm = {m, m};
; #pragma unroll
;     for (int kt = 0; kt < 2; ++kt)
; #pragma unroll
;       for (int i = 0; i < 8; ++i) { f32x2 z = {st[kt][2 * i], st[kt][2 * i + 1]}; z = z - mm; st[kt][2 * i] = z[0]; st[kt][2 * i + 1] = z[1]; }
;   }
;   if (FOX) {
;     if (diag) {
; #pragma unroll
;       for (int kt = 0; kt < 2; ++kt)
; #pragma unroll
;         for (int i = 0; i < 16; ++i) {
;           const int key = j * 64 + kt * 32 + (i & 3) + 8 * (i >> 2) + 4 * hh;
;           if (key > tq) st[kt][i] = -INFINITY;
;         }
;     }
;   }
;   float mx;
;   {
;     float a0 = fmaxf(fmaxf(st[0][0], st[0][1]), st[0][2]), a1 = fmaxf(fmaxf(st[1][0], st[1][1]), st[1][2]);
; #pragma unroll
;     for (int i = 3; i < 15; i += 2) { a0 = fmaxf(fmaxf(a0, st[0][i]), st[0][i + 1]); a1 = fmaxf(fmaxf(a1, st[1][i]), st[1][i + 1]); }
;     mx = fmaxf(fmaxf(a0, a1), fmaxf(st[0][15], st[1][15]));
;   }
;   mx = xmax32(mx);
;   if (__any(diag || mx > 8.f)) {
;     const float d = (diag || mx > 0.f) ? mx : 0.f;
;     const float alpha = diag ? 0.f : __builtin_amdgcn_exp2f(-d);
;     m += d;
;     l *= alpha;
; #pragma unroll
;     for (int dd = 0; dd < DVT; ++dd)
; #pragma unroll
;       for (int i = 0; i < 16; ++i) o[dd][i] *= alpha;
;     const f32x2 d2 = {d, d};
; #pragma unroll
;     for (int kt = 0; kt < 2; ++kt)
; #pragma unroll
;       for (int i = 0; i < 8; ++i) { f32x2 z = {st[kt][2 * i], st[kt][2 * i + 1]}; z = z - d2; st[kt][2 * i] = z[0]; st[kt][2 * i + 1] = z[1]; }
;   }
.LBB0_660:
	s_add_i32 s3, s26, s27
	s_cmp_gt_i32 s2, s25
	s_cbranch_scc1 .LBB0_664
	ds_read_b128 v[2:5], v177
	ds_read_b128 v[6:9], v177 offset:32
	ds_read_b128 v[10:13], v177 offset:4608
	ds_read_b128 v[152:155], v177 offset:4640
	ds_read_b128 v[168:171], v177 offset:64
	ds_read_b128 v[172:175], v177 offset:96
	ds_read_b128 v[184:187], v177 offset:4672
	ds_read_b128 v[188:191], v177 offset:4704
	s_cmp_eq_u32 s3, -1
	s_cselect_b64 s[4:5], -1, 0
	s_waitcnt lgkmcnt(7)
	v_mfma_f32_32x32x16_bf16 v[96:111], v[2:5], v[112:115], 0
	s_waitcnt lgkmcnt(5)
	v_mfma_f32_32x32x16_bf16 v[80:95], v[10:13], v[112:115], 0
	v_mfma_f32_32x32x16_bf16 v[96:111], v[6:9], v[116:119], v[96:111]
	s_waitcnt lgkmcnt(4)
	v_mfma_f32_32x32x16_bf16 v[80:95], v[152:155], v[116:119], v[80:95]
	ds_read_b128 v[152:155], v177 offset:9216
	ds_read_b128 v[10:13], v177 offset:13824
	ds_read_b128 v[6:9], v177 offset:18432
	ds_read_b128 v[2:5], v177 offset:23040
	s_waitcnt lgkmcnt(7)
	v_mfma_f32_32x32x16_bf16 v[96:111], v[168:171], v[120:123], v[96:111]
	s_waitcnt lgkmcnt(5)
	v_mfma_f32_32x32x16_bf16 v[80:95], v[184:187], v[120:123], v[80:95]
	v_mfma_f32_32x32x16_bf16 v[96:111], v[172:175], v[124:127], v[96:111]
	s_waitcnt lgkmcnt(4)
	v_mfma_f32_32x32x16_bf16 v[80:95], v[188:191], v[124:127], v[80:95]
	s_nop 9
	v_add_f32_e64 v168, v96, -v166
	v_add_f32_e64 v169, v97, -v166
	v_add_f32_e64 v170, v98, -v166
	v_add_f32_e64 v171, v99, -v166
	v_pk_add_f32 v[96:97], v[80:81], v[166:167] op_sel_hi:[1,0] neg_lo:[0,1] neg_hi:[0,1]
	v_pk_add_f32 v[98:99], v[82:83], v[166:167] op_sel_hi:[1,0] neg_lo:[0,1] neg_hi:[0,1]
	v_pk_add_f32 v[172:173], v[100:101], v[166:167] op_sel_hi:[1,0] neg_lo:[0,1] neg_hi:[0,1]
	v_pk_add_f32 v[100:101], v[84:85], v[166:167] op_sel_hi:[1,0] neg_lo:[0,1] neg_hi:[0,1]
	v_pk_add_f32 v[80:81], v[88:89], v[166:167] op_sel_hi:[1,0] neg_lo:[0,1] neg_hi:[0,1]
	v_max3_f32 v88, v168, v169, v170
	v_max3_f32 v89, v96, v97, v98
	v_pk_add_f32 v[174:175], v[102:103], v[166:167] op_sel_hi:[1,0] neg_lo:[0,1] neg_hi:[0,1]
	v_pk_add_f32 v[86:87], v[86:87], v[166:167] op_sel_hi:[1,0] neg_lo:[0,1] neg_hi:[0,1]
	v_max3_f32 v88, v88, v171, v172
	v_max3_f32 v89, v89, v99, v100
	v_pk_add_f32 v[102:103], v[104:105], v[166:167] op_sel_hi:[1,0] neg_lo:[0,1] neg_hi:[0,1]
	v_max3_f32 v88, v88, v173, v174
	v_max3_f32 v89, v89, v101, v86
	v_pk_add_f32 v[104:105], v[106:107], v[166:167] op_sel_hi:[1,0] neg_lo:[0,1] neg_hi:[0,1]
	v_pk_add_f32 v[82:83], v[90:91], v[166:167] op_sel_hi:[1,0] neg_lo:[0,1] neg_hi:[0,1]
	v_max3_f32 v88, v88, v175, v102
	v_max3_f32 v89, v89, v87, v80
	v_pk_add_f32 v[106:107], v[108:109], v[166:167] op_sel_hi:[1,0] neg_lo:[0,1] neg_hi:[0,1]
	v_pk_add_f32 v[84:85], v[92:93], v[166:167] op_sel_hi:[1,0] neg_lo:[0,1] neg_hi:[0,1]
	v_max3_f32 v88, v88, v103, v104
	v_max3_f32 v89, v89, v81, v82
	v_pk_add_f32 v[108:109], v[110:111], v[166:167] op_sel_hi:[1,0] neg_lo:[0,1] neg_hi:[0,1]
	v_pk_add_f32 v[14:15], v[94:95], v[166:167] op_sel_hi:[1,0] neg_lo:[0,1] neg_hi:[0,1]
	v_max3_f32 v88, v88, v105, v106
	v_max3_f32 v89, v89, v83, v84
	v_max3_f32 v88, v88, v107, v108
	v_max3_f32 v89, v89, v85, v14
	v_max_f32_e32 v90, v109, v15
	v_max3_f32 v88, v88, v89, v90
	v_mov_b32_e32 v89, v88
	s_nop 1
	v_permlane32_swap_b32_e32 v88, v89
	v_max_f32_e32 v88, v88, v89
	v_cmp_lt_f32_e32 vcc, s92, v88
	s_or_b64 vcc, s[4:5], vcc
	s_cbranch_vccz .LBB0_663
	v_cmp_lt_f32_e32 vcc, 0, v88
	s_or_b64 vcc, s[4:5], vcc
	s_nop 0
	v_cndmask_b32_e32 v89, 0, v88, vcc
	v_exp_f32_e64 v88, -v89
	v_add_f32_e32 v166, v166, v89
	v_sub_f32_e32 v168, v168, v89
	v_sub_f32_e32 v169, v169, v89
	v_cndmask_b32_e64 v88, v88, 0, s[4:5]
	v_mul_f32_e32 v0, v0, v88
	v_pk_mul_f32 v[78:79], v[78:79], v[88:89] op_sel_hi:[1,0]
	v_pk_mul_f32 v[76:77], v[76:77], v[88:89] op_sel_hi:[1,0]
	v_pk_mul_f32 v[74:75], v[74:75], v[88:89] op_sel_hi:[1,0]
	v_pk_mul_f32 v[72:73], v[72:73], v[88:89] op_sel_hi:[1,0]
	v_pk_mul_f32 v[70:71], v[70:71], v[88:89] op_sel_hi:[1,0]
	v_pk_mul_f32 v[68:69], v[68:69], v[88:89] op_sel_hi:[1,0]
	v_pk_mul_f32 v[66:67], v[66:67], v[88:89] op_sel_hi:[1,0]
	v_pk_mul_f32 v[64:65], v[64:65], v[88:89] op_sel_hi:[1,0]
	v_pk_mul_f32 v[62:63], v[62:63], v[88:89] op_sel_hi:[1,0]
	v_pk_mul_f32 v[60:61], v[60:61], v[88:89] op_sel_hi:[1,0]
	v_pk_mul_f32 v[58:59], v[58:59], v[88:89] op_sel_hi:[1,0]
	v_pk_mul_f32 v[56:57], v[56:57], v[88:89] op_sel_hi:[1,0]
	v_pk_mul_f32 v[54:55], v[54:55], v[88:89] op_sel_hi:[1,0]
	v_pk_mul_f32 v[52:53], v[52:53], v[88:89] op_sel_hi:[1,0]
	v_pk_mul_f32 v[50:51], v[50:51], v[88:89] op_sel_hi:[1,0]
	v_pk_mul_f32 v[48:49], v[48:49], v[88:89] op_sel_hi:[1,0]
	v_pk_mul_f32 v[46:47], v[46:47], v[88:89] op_sel_hi:[1,0]
	v_pk_mul_f32 v[44:45], v[44:45], v[88:89] op_sel_hi:[1,0]
	v_pk_mul_f32 v[42:43], v[42:43], v[88:89] op_sel_hi:[1,0]
	v_pk_mul_f32 v[40:41], v[40:41], v[88:89] op_sel_hi:[1,0]
	v_pk_mul_f32 v[38:39], v[38:39], v[88:89] op_sel_hi:[1,0]
	v_pk_mul_f32 v[36:37], v[36:37], v[88:89] op_sel_hi:[1,0]
	v_pk_mul_f32 v[34:35], v[34:35], v[88:89] op_sel_hi:[1,0]
	v_pk_mul_f32 v[32:33], v[32:33], v[88:89] op_sel_hi:[1,0]
	v_pk_mul_f32 v[30:31], v[30:31], v[88:89] op_sel_hi:[1,0]
	v_pk_mul_f32 v[28:29], v[28:29], v[88:89] op_sel_hi:[1,0]
	v_pk_mul_f32 v[26:27], v[26:27], v[88:89] op_sel_hi:[1,0]
	v_pk_mul_f32 v[24:25], v[24:25], v[88:89] op_sel_hi:[1,0]
	v_pk_mul_f32 v[22:23], v[22:23], v[88:89] op_sel_hi:[1,0]
	v_pk_mul_f32 v[20:21], v[20:21], v[88:89] op_sel_hi:[1,0]
	v_pk_mul_f32 v[18:19], v[18:19], v[88:89] op_sel_hi:[1,0]
	v_pk_mul_f32 v[16:17], v[16:17], v[88:89] op_sel_hi:[1,0]
	v_sub_f32_e32 v170, v170, v89
	v_sub_f32_e32 v171, v171, v89
	v_sub_f32_e32 v172, v172, v89
	v_sub_f32_e32 v173, v173, v89
	v_sub_f32_e32 v174, v174, v89
	v_sub_f32_e32 v175, v175, v89
	v_sub_f32_e32 v102, v102, v89
	v_sub_f32_e32 v103, v103, v89
	v_sub_f32_e32 v104, v104, v89
	v_sub_f32_e32 v105, v105, v89
	v_sub_f32_e32 v106, v106, v89
	v_sub_f32_e32 v107, v107, v89
	v_sub_f32_e32 v108, v108, v89
	v_sub_f32_e32 v109, v109, v89
	v_sub_f32_e32 v96, v96, v89
	v_sub_f32_e32 v97, v97, v89
	v_sub_f32_e32 v98, v98, v89
	v_sub_f32_e32 v99, v99, v89
	v_sub_f32_e32 v100, v100, v89
	v_sub_f32_e32 v101, v101, v89
	v_sub_f32_e32 v86, v86, v89
	v_sub_f32_e32 v87, v87, v89
	v_sub_f32_e32 v80, v80, v89
	v_sub_f32_e32 v81, v81, v89
	v_sub_f32_e32 v82, v82, v89
	v_sub_f32_e32 v83, v83, v89
	v_sub_f32_e32 v84, v84, v89
	v_sub_f32_e32 v85, v85, v89
	v_sub_f32_e32 v14, v14, v89
	v_sub_f32_e32 v15, v15, v89

; #define MFMA32(a, b, c) __builtin_amdgcn_mfma_f32_32x32x16_bf16((a), (b), (c), 0, 0, 0)
; DI float xmax32(float v) { const u32x2 r_ = __builtin_amdgcn_permlane32_swap(__float_as_uint(v), __float_as_uint(v), false, false); return fmaxf(__uint_as_float(r_[0]), __uint_as_float(r_[1])); }
; template <int DVT, bool FOX>
; DI void attn_step(const char* kb, const bf16x8 (&qf)[4], f32x16 (&o)[DVT], float& m, float& l, const bool diag, const int j, const int tq, const int r, const int hh) {
;     ...
; #pragma unroll
;   for (int ks = 0; ks < 4; ++ks)
; #pragma unroll
;     for (int kt = 0; kt < 2; ++kt) st[kt] = MFMA32(kf[ks * 2 + kt], qf[ks], st[kt]);
;   bf16x8 va[DVT], vn[DVT];
; #pragma unroll
;   for (int d = 0; d < DVT; ++d) va[d] = *(const bf16x8*)(vb + (d * 32 + r) * LROW + (8 * hh) * 2);
;   __builtin_amdgcn_sched_barrier(0);
;   {
;     const f32x2 mm = {m, m};
; #pragma unroll
;     for (int kt = 0; kt < 2; ++kt)
; #pragma unroll
;       for (int i = 0; i < 8; ++i) { f32x2 z = {st[kt][2 * i], st[kt][2 * i + 1]}; z = z - mm; st[kt][2 * i] = z[0]; st[kt][2 * i + 1] = z[1]; }
;   }
;   if (FOX) {
;     if (diag) {
; #pragma unroll
;       for (int kt = 0; kt < 2; ++kt)
; #pragma unroll
;         for (int i = 0; i < 16; ++i) {
;           const int key = j * 64 + kt * 32 + (i & 3) + 8 * (i >> 2) + 4 * hh;
;           if (key > tq) st[kt][i] = -INFINITY;
;         }
;     }
;   }
;   float mx;
;   {
;     float a0 = fmaxf(fmaxf(st[0][0], st[0][1]), st[0][2]), a1 = fmaxf(fmaxf(st[1][0], st[1][1]), st[1][2]);
; #pragma unroll
;     for (int i = 3; i < 15; i += 2) { a0 = fmaxf(fmaxf(a0, st[0][i]), st[0][i + 1]); a1 = fmaxf(fmaxf(a1, st[1][i]), st[1][i + 1]); }
;     mx = fmaxf(fmaxf(a0, a1), fmaxf(st[0][15], st[1][15]));
;   }
;   mx = xmax32(mx);
;   if (__any(diag || mx > 8.f)) {
;     const float d = (diag || mx > 0.f) ? mx : 0.f;
;     const float alpha = diag ? 0.f : __builtin_amdgcn_exp2f(-d);
;     m += d;
;     l *= alpha;
; #pragma unroll
;     for (int dd = 0; dd < DVT; ++dd)
; #pragma unroll
;       for (int i = 0; i < 16; ++i) o[dd][i] *= alpha;
;     const f32x2 d2 = {d, d};
; #pragma unroll
;     for (int kt = 0; kt < 2; ++kt)
; #pragma unroll
;       for (int i = 0; i < 8; ++i) { f32x2 z = {st[kt][2 * i], st[kt][2 * i + 1]}; z = z - d2; st[kt][2 * i] = z[0]; st[kt][2 * i + 1] = z[1]; }
;   }
.LBB0_668:
	ds_read_b128 v[2:5], v177 offset:27904
	ds_read_b128 v[6:9], v177 offset:27936
	ds_read_b128 v[10:13], v177 offset:32512
	ds_read_b128 v[152:155], v177 offset:32544
	ds_read_b128 v[168:171], v177 offset:27968
	ds_read_b128 v[172:175], v177 offset:28000
	ds_read_b128 v[184:187], v177 offset:32576
	ds_read_b128 v[188:191], v177 offset:32608
	s_cmp_eq_u32 s3, 0
	s_cselect_b64 s[4:5], -1, 0
	s_waitcnt lgkmcnt(7)
	v_mfma_f32_32x32x16_bf16 v[96:111], v[2:5], v[112:115], 0
	s_waitcnt lgkmcnt(5)
	v_mfma_f32_32x32x16_bf16 v[80:95], v[10:13], v[112:115], 0
	v_mfma_f32_32x32x16_bf16 v[96:111], v[6:9], v[116:119], v[96:111]
	s_waitcnt lgkmcnt(4)
	v_mfma_f32_32x32x16_bf16 v[80:95], v[152:155], v[116:119], v[80:95]
	ds_read_b128 v[152:155], v177 offset:37120
	ds_read_b128 v[10:13], v177 offset:41728
	ds_read_b128 v[6:9], v177 offset:46336
	ds_read_b128 v[2:5], v177 offset:50944
	s_waitcnt lgkmcnt(7)
	v_mfma_f32_32x32x16_bf16 v[96:111], v[168:171], v[120:123], v[96:111]
	s_waitcnt lgkmcnt(5)
	v_mfma_f32_32x32x16_bf16 v[80:95], v[184:187], v[120:123], v[80:95]
	v_mfma_f32_32x32x16_bf16 v[96:111], v[172:175], v[124:127], v[96:111]
	s_waitcnt lgkmcnt(4)
	v_mfma_f32_32x32x16_bf16 v[80:95], v[188:191], v[124:127], v[80:95]
	s_nop 9
	v_add_f32_e64 v168, v96, -v166
	v_add_f32_e64 v169, v97, -v166
	v_add_f32_e64 v170, v98, -v166
	v_add_f32_e64 v171, v99, -v166
	v_pk_add_f32 v[96:97], v[80:81], v[166:167] op_sel_hi:[1,0] neg_lo:[0,1] neg_hi:[0,1]
	v_pk_add_f32 v[98:99], v[82:83], v[166:167] op_sel_hi:[1,0] neg_lo:[0,1] neg_hi:[0,1]
	v_pk_add_f32 v[172:173], v[100:101], v[166:167] op_sel_hi:[1,0] neg_lo:[0,1] neg_hi:[0,1]
	v_pk_add_f32 v[100:101], v[84:85], v[166:167] op_sel_hi:[1,0] neg_lo:[0,1] neg_hi:[0,1]
	v_pk_add_f32 v[80:81], v[88:89], v[166:167] op_sel_hi:[1,0] neg_lo:[0,1] neg_hi:[0,1]
	v_max3_f32 v88, v168, v169, v170
	v_max3_f32 v89, v96, v97, v98
	v_pk_add_f32 v[174:175], v[102:103], v[166:167] op_sel_hi:[1,0] neg_lo:[0,1] neg_hi:[0,1]
	v_pk_add_f32 v[86:87], v[86:87], v[166:167] op_sel_hi:[1,0] neg_lo:[0,1] neg_hi:[0,1]
	v_max3_f32 v88, v88, v171, v172
	v_max3_f32 v89, v89, v99, v100
	v_pk_add_f32 v[102:103], v[104:105], v[166:167] op_sel_hi:[1,0] neg_lo:[0,1] neg_hi:[0,1]
	v_max3_f32 v88, v88, v173, v174
	v_max3_f32 v89, v89, v101, v86
	v_pk_add_f32 v[104:105], v[106:107], v[166:167] op_sel_hi:[1,0] neg_lo:[0,1] neg_hi:[0,1]
	v_pk_add_f32 v[82:83], v[90:91], v[166:167] op_sel_hi:[1,0] neg_lo:[0,1] neg_hi:[0,1]
	v_max3_f32 v88, v88, v175, v102
	v_max3_f32 v89, v89, v87, v80
	v_pk_add_f32 v[106:107], v[108:109], v[166:167] op_sel_hi:[1,0] neg_lo:[0,1] neg_hi:[0,1]
	v_pk_add_f32 v[84:85], v[92:93], v[166:167] op_sel_hi:[1,0] neg_lo:[0,1] neg_hi:[0,1]
	v_max3_f32 v88, v88, v103, v104
	v_max3_f32 v89, v89, v81, v82
	v_pk_add_f32 v[108:109], v[110:111], v[166:167] op_sel_hi:[1,0] neg_lo:[0,1] neg_hi:[0,1]
	v_pk_add_f32 v[14:15], v[94:95], v[166:167] op_sel_hi:[1,0] neg_lo:[0,1] neg_hi:[0,1]
	v_max3_f32 v88, v88, v105, v106
	v_max3_f32 v89, v89, v83, v84
	v_max3_f32 v88, v88, v107, v108
	v_max3_f32 v89, v89, v85, v14
	v_max_f32_e32 v90, v109, v15
	v_max3_f32 v88, v88, v89, v90
	v_mov_b32_e32 v89, v88
	s_nop 1
	v_permlane32_swap_b32_e32 v88, v89
	v_max_f32_e32 v88, v88, v89
	v_cmp_lt_f32_e32 vcc, s92, v88
	s_or_b64 vcc, s[4:5], vcc
	s_cbranch_vccz .LBB0_670
	v_cmp_lt_f32_e32 vcc, 0, v88
	s_or_b64 vcc, s[4:5], vcc
	s_nop 0
	v_cndmask_b32_e32 v89, 0, v88, vcc
	v_exp_f32_e64 v88, -v89
	v_add_f32_e32 v166, v166, v89
	v_sub_f32_e32 v168, v168, v89
	v_sub_f32_e32 v169, v169, v89
	v_cndmask_b32_e64 v88, v88, 0, s[4:5]
	v_mul_f32_e32 v0, v0, v88
	v_pk_mul_f32 v[78:79], v[78:79], v[88:89] op_sel_hi:[1,0]
	v_pk_mul_f32 v[76:77], v[76:77], v[88:89] op_sel_hi:[1,0]
	v_pk_mul_f32 v[74:75], v[74:75], v[88:89] op_sel_hi:[1,0]
	v_pk_mul_f32 v[72:73], v[72:73], v[88:89] op_sel_hi:[1,0]
	v_pk_mul_f32 v[70:71], v[70:71], v[88:89] op_sel_hi:[1,0]
	v_pk_mul_f32 v[68:69], v[68:69], v[88:89] op_sel_hi:[1,0]
	v_pk_mul_f32 v[66:67], v[66:67], v[88:89] op_sel_hi:[1,0]
	v_pk_mul_f32 v[64:65], v[64:65], v[88:89] op_sel_hi:[1,0]
	v_pk_mul_f32 v[62:63], v[62:63], v[88:89] op_sel_hi:[1,0]
	v_pk_mul_f32 v[60:61], v[60:61], v[88:89] op_sel_hi:[1,0]
	v_pk_mul_f32 v[58:59], v[58:59], v[88:89] op_sel_hi:[1,0]
	v_pk_mul_f32 v[56:57], v[56:57], v[88:89] op_sel_hi:[1,0]
	v_pk_mul_f32 v[54:55], v[54:55], v[88:89] op_sel_hi:[1,0]
	v_pk_mul_f32 v[52:53], v[52:53], v[88:89] op_sel_hi:[1,0]
	v_pk_mul_f32 v[50:51], v[50:51], v[88:89] op_sel_hi:[1,0]
	v_pk_mul_f32 v[48:49], v[48:49], v[88:89] op_sel_hi:[1,0]
	v_pk_mul_f32 v[46:47], v[46:47], v[88:89] op_sel_hi:[1,0]
	v_pk_mul_f32 v[44:45], v[44:45], v[88:89] op_sel_hi:[1,0]
	v_pk_mul_f32 v[42:43], v[42:43], v[88:89] op_sel_hi:[1,0]
	v_pk_mul_f32 v[40:41], v[40:41], v[88:89] op_sel_hi:[1,0]
	v_pk_mul_f32 v[38:39], v[38:39], v[88:89] op_sel_hi:[1,0]
	v_pk_mul_f32 v[36:37], v[36:37], v[88:89] op_sel_hi:[1,0]
	v_pk_mul_f32 v[34:35], v[34:35], v[88:89] op_sel_hi:[1,0]
	v_pk_mul_f32 v[32:33], v[32:33], v[88:89] op_sel_hi:[1,0]
	v_pk_mul_f32 v[30:31], v[30:31], v[88:89] op_sel_hi:[1,0]
	v_pk_mul_f32 v[28:29], v[28:29], v[88:89] op_sel_hi:[1,0]
	v_pk_mul_f32 v[26:27], v[26:27], v[88:89] op_sel_hi:[1,0]
	v_pk_mul_f32 v[24:25], v[24:25], v[88:89] op_sel_hi:[1,0]
	v_pk_mul_f32 v[22:23], v[22:23], v[88:89] op_sel_hi:[1,0]
	v_pk_mul_f32 v[20:21], v[20:21], v[88:89] op_sel_hi:[1,0]
	v_pk_mul_f32 v[18:19], v[18:19], v[88:89] op_sel_hi:[1,0]
	v_pk_mul_f32 v[16:17], v[16:17], v[88:89] op_sel_hi:[1,0]
	v_sub_f32_e32 v170, v170, v89
	v_sub_f32_e32 v171, v171, v89
	v_sub_f32_e32 v172, v172, v89
	v_sub_f32_e32 v173, v173, v89
	v_sub_f32_e32 v174, v174, v89
	v_sub_f32_e32 v175, v175, v89
	v_sub_f32_e32 v102, v102, v89
	v_sub_f32_e32 v103, v103, v89
	v_sub_f32_e32 v104, v104, v89
	v_sub_f32_e32 v105, v105, v89
	v_sub_f32_e32 v106, v106, v89
	v_sub_f32_e32 v107, v107, v89
	v_sub_f32_e32 v108, v108, v89
	v_sub_f32_e32 v109, v109, v89
	v_sub_f32_e32 v96, v96, v89
	v_sub_f32_e32 v97, v97, v89
	v_sub_f32_e32 v98, v98, v89
	v_sub_f32_e32 v99, v99, v89
	v_sub_f32_e32 v100, v100, v89
	v_sub_f32_e32 v101, v101, v89
	v_sub_f32_e32 v86, v86, v89
	v_sub_f32_e32 v87, v87, v89
	v_sub_f32_e32 v80, v80, v89
	v_sub_f32_e32 v81, v81, v89
	v_sub_f32_e32 v82, v82, v89
	v_sub_f32_e32 v83, v83, v89
	v_sub_f32_e32 v84, v84, v89
	v_sub_f32_e32 v85, v85, v89
	v_sub_f32_e32 v14, v14, v89
	v_sub_f32_e32 v15, v15, v89

; #define G_GLOAD(XR, WR, KT) { _Pragma("unroll") for (int i_ = 0; i_ < 4; ++i_) XR[i_] = *(const u32x4*)(Xt + ((size_t)(64 * i_) * ldx + (KT) * 64) * 2 + xoff); \
;     _Pragma("unroll") for (int i_ = 0; i_ < 4; ++i_) WR[i_] = *(const u32x4*)(Wtb + ((size_t)(64 * i_) * K + (KT) * 64) * 2 + woff); }
; #define G_LSTORE(XR, WR, STG) { char* xs_ = lds + (STG) * G_STAGE; char* ws_ = xs_ + G_XB; \
;     _Pragma("unroll") for (int i_ = 0; i_ < 4; ++i_) *(u32x4*)(xs_ + (lrow + 64 * i_) * LROW + lch * 16) = XR[i_]; \
;     _Pragma("unroll") for (int i_ = 0; i_ < 4; ++i_) *(u32x4*)(ws_ + (lrow + 64 * i_) * LROW + lch * 16) = WR[i_]; }
; template <class Epi>
; DI void gemm_phase(const bf16_t* __restrict__ X, const int ldx, const bf16_t* __restrict__ Wt, const int N, const int K, const Epi& epi, char* lds) {
;     ...
;     if (Epi::kFull || chunk == xcd) {
;       G_GLOAD(xr0, wr0, 0);
;       G_LSTORE(xr0, wr0, 0);
;       __syncthreads();
;       G_GLOAD(xr0, wr0, 1);
;     }
; #pragma unroll
;     for (int c = 0; c < 2; ++c)
; #pragma unroll
;       for (int a = 0; a < 2; ++a)
; #pragma unroll
;         for (int b = 0; b < 2; ++b)
; #pragma unroll
;           for (int i = 0; i < 16; ++i) acc[c][a][b][i] = 0.f;
.LBB0_700:
	s_lshl_b32 s2, s34, 5
	v_readlane_b32 s3, v254, 3
	s_add_i32 s2, s2, s3
	s_lshr_b32 s2, s2, 2
	s_and_b32 s2, s2, 0xffffffc
	s_or_b32 s2, s2, s90
	s_lshl_b32 s4, s2, 8
	s_mov_b32 s5, s97
	s_lshl_b64 s[18:19], s[4:5], 11
	s_add_u32 s18, s6, s18
	s_addc_u32 s19, s7, s19
	v_lshl_add_u64 v[178:179], s[18:19], 0, v[162:163]
	s_waitcnt vmcnt(2)
	v_add_co_u32_e32 v48, vcc, s91, v178
	s_mov_b64 s[20:21], 0x40000
	s_nop 0
	v_addc_co_u32_e32 v49, vcc, 0, v179, vcc
	v_add_co_u32_e32 v74, vcc, s1, v178
	global_load_dwordx4 v[24:27], v[178:179], off
	global_load_dwordx4 v[28:31], v[48:49], off
	v_addc_co_u32_e32 v75, vcc, 0, v179, vcc
	v_add_co_u32_e32 v76, vcc, s76, v178
	global_load_dwordx4 v[32:35], v[164:165], off
	global_load_dwordx4 v[36:39], v[198:199], off
	global_load_dwordx4 v[40:43], v[206:207], off
	global_load_dwordx4 v[44:47], v[170:171], off
	v_addc_co_u32_e32 v77, vcc, 0, v179, vcc
	global_load_dwordx4 v[66:69], v[74:75], off
	global_load_dwordx4 v[70:73], v[76:77], off
	v_mov_b32_e32 v2, 0
	v_lshl_add_u64 v[180:181], v[178:179], 0, s[20:21]
	s_mov_b64 s[20:21], 0x60000
	s_mov_b32 s19, 0
	s_movk_i32 s3, 0x100
	v_mov_b32_e32 v3, v2
	v_mov_b64_e32 v[4:5], v[2:3]
	v_mov_b64_e32 v[6:7], v[2:3]
	v_mov_b64_e32 v[8:9], v[2:3]
	v_mov_b64_e32 v[10:11], v[2:3]
	v_mov_b64_e32 v[12:13], v[2:3]
	v_mov_b64_e32 v[14:15], v[2:3]
	v_mov_b64_e32 v[16:17], v[2:3]
	s_waitcnt vmcnt(9)
	v_mov_b64_e32 v[50:51], v[2:3]
	v_mov_b64_e32 v[52:53], v[2:3]
	s_waitcnt vmcnt(8)
	v_mov_b64_e32 v[54:55], v[2:3]
	v_mov_b64_e32 v[56:57], v[2:3]
	v_mov_b64_e32 v[58:59], v[2:3]
	v_mov_b64_e32 v[60:61], v[2:3]
	v_mov_b64_e32 v[62:63], v[2:3]
	v_mov_b64_e32 v[64:65], v[2:3]
	v_mov_b64_e32 v[18:19], v[2:3]
	v_mov_b64_e32 v[20:21], v[2:3]
	v_mov_b32_e32 v22, v2
	v_lshl_add_u64 v[182:183], v[178:179], 0, s[20:21]
	v_mov_b32_e32 v23, v2
	v_mov_b64_e32 v[82:83], v[2:3]
	v_mov_b64_e32 v[84:85], v[2:3]
	v_mov_b64_e32 v[86:87], v[2:3]
	v_mov_b64_e32 v[88:89], v[2:3]
	v_mov_b64_e32 v[90:91], v[2:3]
	v_mov_b64_e32 v[92:93], v[2:3]
	v_mov_b64_e32 v[94:95], v[2:3]
	v_mov_b64_e32 v[96:97], v[2:3]
	v_mov_b64_e32 v[98:99], v[2:3]
	v_mov_b64_e32 v[100:101], v[2:3]
	v_mov_b64_e32 v[102:103], v[2:3]
	v_mov_b32_e32 v104, v2
	s_waitcnt vmcnt(5)
	ds_write_b128 v222, v[32:35] offset:36864
	s_waitcnt vmcnt(4)
	ds_write_b128 v222, v[36:39] offset:46080
	s_waitcnt vmcnt(3)
	ds_write_b128 v222, v[40:43] offset:55296
	s_waitcnt vmcnt(2)
	ds_write_b128 v222, v[44:47] offset:64512
	ds_write_b128 v222, v[24:27]
	ds_write_b128 v222, v[28:31] offset:9216
	s_waitcnt vmcnt(1)
	ds_write_b128 v222, v[66:69] offset:18432
	s_waitcnt vmcnt(0)
	ds_write_b128 v222, v[70:73] offset:27648
	s_waitcnt lgkmcnt(0)
	s_barrier
	global_load_dwordx4 v[130:133], v[174:175], off
	global_load_dwordx4 v[150:153], v[176:177], off
	global_load_dwordx4 v[158:161], v[172:173], off
	global_load_dwordx4 v[138:141], v[164:165], off offset:128
	global_load_dwordx4 v[146:149], v[76:77], off offset:128
	global_load_dwordx4 v[134:137], v[74:75], off offset:128
	global_load_dwordx4 v[154:157], v[48:49], off offset:128
	global_load_dwordx4 v[142:145], v[178:179], off offset:128
	v_mov_b64_e32 v[24:25], v[2:3]
	v_mov_b64_e32 v[26:27], v[2:3]
	v_mov_b64_e32 v[28:29], v[2:3]
	v_mov_b64_e32 v[30:31], v[2:3]
	v_mov_b64_e32 v[32:33], v[2:3]
	v_mov_b64_e32 v[34:35], v[2:3]
	v_mov_b64_e32 v[36:37], v[2:3]
	v_mov_b64_e32 v[38:39], v[2:3]
	v_mov_b64_e32 v[40:41], v[2:3]
	v_mov_b64_e32 v[42:43], v[2:3]
	v_mov_b64_e32 v[44:45], v[2:3]
	v_mov_b64_e32 v[46:47], v[2:3]
	v_mov_b64_e32 v[48:49], v[2:3]
	v_mov_b32_e32 v105, v2
	v_mov_b64_e32 v[106:107], v[2:3]
	v_mov_b64_e32 v[108:109], v[2:3]
	v_mov_b64_e32 v[110:111], v[2:3]
	v_mov_b64_e32 v[112:113], v[2:3]
	v_mov_b64_e32 v[66:67], v[2:3]
	v_mov_b64_e32 v[68:69], v[2:3]
	v_mov_b64_e32 v[70:71], v[2:3]
	v_mov_b64_e32 v[72:73], v[2:3]
	v_mov_b64_e32 v[74:75], v[2:3]
	v_mov_b64_e32 v[76:77], v[2:3]
	v_mov_b64_e32 v[78:79], v[2:3]
	v_mov_b64_e32 v[80:81], v[2:3]
	v_mov_b64_e32 v[114:115], v[2:3]
	v_mov_b64_e32 v[116:117], v[2:3]
	v_mov_b32_e32 v118, v2
	v_mov_b32_e32 v119, v2
	v_mov_b32_e32 v120, v2
	v_mov_b32_e32 v121, v2
	v_mov_b32_e32 v122, v2
	v_mov_b32_e32 v123, v2
	v_mov_b32_e32 v124, v2
	v_mov_b32_e32 v125, v2
	v_mov_b32_e32 v126, v2
	v_mov_b32_e32 v127, v2
	v_mov_b32_e32 v128, v2
	v_mov_b32_e32 v129, v2

; #define G_GLOAD(XR, WR, KT) { _Pragma("unroll") for (int i_ = 0; i_ < 4; ++i_) XR[i_] = *(const u32x4*)(Xt + ((size_t)(64 * i_) * ldx + (KT) * 64) * 2 + xoff); \
;     _Pragma("unroll") for (int i_ = 0; i_ < 4; ++i_) WR[i_] = *(const u32x4*)(Wtb + ((size_t)(64 * i_) * K + (KT) * 64) * 2 + woff); }
; #define G_LSTORE(XR, WR, STG) { char* xs_ = lds + (STG) * G_STAGE; char* ws_ = xs_ + G_XB; \
;     _Pragma("unroll") for (int i_ = 0; i_ < 4; ++i_) *(u32x4*)(xs_ + (lrow + 64 * i_) * LROW + lch * 16) = XR[i_]; \
;     _Pragma("unroll") for (int i_ = 0; i_ < 4; ++i_) *(u32x4*)(ws_ + (lrow + 64 * i_) * LROW + lch * 16) = WR[i_]; }
; template <class Epi>
; DI void gemm_phase(const bf16_t* __restrict__ X, const int ldx, const bf16_t* __restrict__ Wt, const int N, const int K, const Epi& epi, char* lds) {
;     ...
;     const int L = chunk * 32 + slot, band = L / (4 * nNt), rem = L % (4 * nNt);
;     const int mt_ = band * 4 + (rem & 3), nt_ = rem >> 2;
;     const char* Xt = (const char*)(X + (size_t)(mt_ * 256) * ldx);
;     const char* Wtb = (const char*)(Wt + (size_t)(nt_ * 256) * K);
;     const unsigned xoff = (unsigned)(lrow * ldx + lch * 8) * 2u, woff = (unsigned)(lrow * K + lch * 8) * 2u;
;     const bool has_next = !Epi::kFull && (chunk + 8 < nchunks);
;     const int Ln = (has_next ? chunk + 8 : chunk) * 32 + slot, band_n = Ln / (4 * nNt), rem_n = Ln % (4 * nNt);
;     const char* Xt_n = (const char*)(X + (size_t)((band_n * 4 + (rem_n & 3)) * 256) * ldx);
;     const char* Wtb_n = (const char*)(Wt + (size_t)((rem_n >> 2) * 256) * K);
;     f32x16 acc[2][2][2];
;     ...
;     asm volatile("" ::: "memory");
;     if (Epi::kFull || chunk == xcd) {
;       G_GLOAD(xr0, wr0, 0);
;       G_LSTORE(xr0, wr0, 0);
;       __syncthreads();
;       G_GLOAD(xr0, wr0, 1);
;     }
; #pragma unroll
;     for (int c = 0; c < 2; ++c)
; #pragma unroll
;       for (int a = 0; a < 2; ++a)
; #pragma unroll
;         for (int b = 0; b < 2; ++b)
; #pragma unroll
;           for (int i = 0; i < 16; ++i) acc[c][a][b][i] = 0.f;
.LBB0_738:
	s_add_i32 s9, s16, 8
	s_cmpk_gt_u32 s16, 0x4f
	s_cselect_b64 s[4:5], -1, 0
	s_cmpk_lt_u32 s16, 0x50
	s_cselect_b32 s16, s9, s16
	s_cselect_b32 s21, 0, 15
	s_cselect_b32 s22, 1, 15
	s_lshl_b32 s16, s16, 5
	v_readlane_b32 s17, v254, 3
	s_add_i32 s16, s16, s17
	s_mul_hi_u32 s17, s16, 0xba2e8ba3
	s_lshr_b32 s17, s17, 6
	s_mul_i32 s23, s17, 0x58
	s_sub_i32 s26, s16, s23
	s_lshl_b32 s16, s17, 10
	s_lshl_b32 s17, s26, 8
	s_and_b32 s17, s17, 0x300
	s_or_b32 s16, s17, s16
	s_ashr_i32 s17, s16, 31
	s_lshl_b64 s[16:17], s[16:17], 11
	s_add_u32 s23, s2, s16
	s_addc_u32 s25, s18, s17
	s_lshl_b32 s16, s26, 17
	s_and_b32 s16, s16, 0xf80000
	s_add_u32 s26, s19, s16
	v_mov_b32_e32 v2, 0
	s_addc_u32 s27, s20, 0
	s_mov_b32 s28, 3
	v_mov_b32_e32 v3, v2
	v_mov_b64_e32 v[4:5], v[2:3]
	v_mov_b64_e32 v[6:7], v[2:3]
	v_mov_b64_e32 v[8:9], v[2:3]
	v_mov_b64_e32 v[10:11], v[2:3]
	v_mov_b64_e32 v[12:13], v[2:3]
	v_mov_b64_e32 v[14:15], v[2:3]
	v_mov_b64_e32 v[16:17], v[2:3]
	s_waitcnt vmcnt(5)
	v_mov_b64_e32 v[34:35], v[2:3]
	v_mov_b64_e32 v[36:37], v[2:3]
	s_waitcnt vmcnt(4)
	v_mov_b64_e32 v[38:39], v[2:3]
	v_mov_b64_e32 v[40:41], v[2:3]
	s_waitcnt vmcnt(3)
	v_mov_b64_e32 v[42:43], v[2:3]
	v_mov_b64_e32 v[44:45], v[2:3]
	s_waitcnt vmcnt(2)
	v_mov_b64_e32 v[46:47], v[2:3]
	v_mov_b64_e32 v[48:49], v[2:3]
	v_mov_b64_e32 v[18:19], v[2:3]
	v_mov_b64_e32 v[20:21], v[2:3]
	v_mov_b64_e32 v[22:23], v[2:3]
	v_mov_b64_e32 v[24:25], v[2:3]
	v_mov_b64_e32 v[26:27], v[2:3]
	v_mov_b64_e32 v[28:29], v[2:3]
	v_mov_b64_e32 v[30:31], v[2:3]
	v_mov_b64_e32 v[32:33], v[2:3]
	s_waitcnt vmcnt(1)
	v_mov_b64_e32 v[50:51], v[2:3]
	v_mov_b64_e32 v[52:53], v[2:3]
	s_waitcnt vmcnt(0)
	v_mov_b64_e32 v[54:55], v[2:3]
	v_mov_b64_e32 v[56:57], v[2:3]
	v_mov_b64_e32 v[58:59], v[2:3]
	v_mov_b64_e32 v[60:61], v[2:3]
	v_mov_b64_e32 v[62:63], v[2:3]
	v_mov_b64_e32 v[64:65], v[2:3]
	v_mov_b64_e32 v[66:67], v[2:3]
	v_mov_b64_e32 v[68:69], v[2:3]
	v_mov_b64_e32 v[70:71], v[2:3]
	v_mov_b64_e32 v[72:73], v[2:3]
	v_mov_b64_e32 v[74:75], v[2:3]
	v_mov_b64_e32 v[76:77], v[2:3]
	v_mov_b64_e32 v[78:79], v[2:3]
	v_mov_b64_e32 v[80:81], v[2:3]
	v_mov_b64_e32 v[98:99], v[2:3]
	v_mov_b64_e32 v[100:101], v[2:3]
	v_mov_b64_e32 v[102:103], v[2:3]
	v_mov_b64_e32 v[104:105], v[2:3]
	v_mov_b64_e32 v[106:107], v[2:3]
	v_mov_b64_e32 v[108:109], v[2:3]
	v_mov_b64_e32 v[110:111], v[2:3]
	v_mov_b64_e32 v[112:113], v[2:3]
	v_mov_b64_e32 v[82:83], v[2:3]
	v_mov_b64_e32 v[84:85], v[2:3]
	v_mov_b64_e32 v[86:87], v[2:3]
	v_mov_b64_e32 v[88:89], v[2:3]
	v_mov_b64_e32 v[90:91], v[2:3]
	v_mov_b64_e32 v[92:93], v[2:3]
	v_mov_b64_e32 v[94:95], v[2:3]
	v_mov_b64_e32 v[96:97], v[2:3]
	v_mov_b64_e32 v[114:115], v[2:3]
	v_mov_b64_e32 v[116:117], v[2:3]
	v_mov_b64_e32 v[118:119], v[2:3]
	v_mov_b64_e32 v[120:121], v[2:3]
	v_mov_b64_e32 v[122:123], v[2:3]
	v_mov_b64_e32 v[124:125], v[2:3]
	v_mov_b64_e32 v[126:127], v[2:3]
	v_mov_b64_e32 v[128:129], v[2:3]
	v_add_u32_e32 v232, s91, v162
	v_add_u32_e32 v233, s1, v162
	v_add_u32_e32 v234, s76, v162
	v_add_u32_e32 v235, v171, v172
	v_add_u32_e32 v236, v171, v173
	v_add_u32_e32 v237, v174, v170
.LBB0_739:
	ds_read_b128 v[164:167], v235
	ds_read_b128 v[188:191], v235 offset:4608
	ds_read_b128 v[194:197], v236 offset:36864
	ds_read_b128 v[202:205], v236 offset:41472
	ds_read_b128 v[206:209], v236 offset:46080
	ds_read_b128 v[210:213], v236 offset:50688
	ds_read_b128 v[214:217], v176 offset:32
	ds_read_b128 v[218:221], v176 offset:4640
	s_add_i32 s29, s28, -3
	s_cmp_lt_u32 s29, 14
	s_cselect_b64 s[30:31], -1, 0
	s_and_b64 s[16:17], s[30:31], exec
	s_cselect_b32 s17, s15, s27
	s_cselect_b32 s16, s14, s26
	s_cselect_b32 s35, s13, s25
	s_cselect_b32 s34, s12, s23
	s_add_i32 s33, s28, -1
	s_waitcnt lgkmcnt(5)
	v_mfma_f32_32x32x16_bf16 v[114:129], v[194:197], v[164:167], v[114:129]
	v_mfma_f32_32x32x16_bf16 v[82:97], v[194:197], v[188:191], v[82:97]
	s_waitcnt lgkmcnt(4)
	v_mfma_f32_32x32x16_bf16 v[98:113], v[202:205], v[164:167], v[98:113]
	v_mfma_f32_32x32x16_bf16 v[66:81], v[202:205], v[188:191], v[66:81]
	s_waitcnt lgkmcnt(3)
	v_mfma_f32_32x32x16_bf16 v[50:65], v[206:209], v[164:167], v[50:65]
	s_and_b64 s[30:31], s[30:31], exec
	s_cselect_b32 s30, s33, s21
	v_mfma_f32_32x32x16_bf16 v[18:33], v[206:209], v[188:191], v[18:33]
	s_waitcnt lgkmcnt(2)
	v_mfma_f32_32x32x16_bf16 v[34:49], v[210:213], v[164:167], v[34:49]
	ds_read_b128 v[164:167], v177 offset:36896
	ds_read_b128 v[194:197], v177 offset:41504
	v_mfma_f32_32x32x16_bf16 v[2:17], v[210:213], v[188:191], v[2:17]
	s_lshl_b32 s96, s30, 7
	s_add_u32 s100, s34, s96
	s_addc_u32 s101, s35, 0
	s_waitcnt vmcnt(6)
	ds_write_b128 v178, v[142:145] offset:9216
	ds_write_b128 v178, v[134:137]
	global_load_dwordx4 v[134:137], v162, s[100:101]
	global_load_dwordx4 v[142:145], v232, s[100:101]
	s_waitcnt vmcnt(7)
	ds_write_b128 v178, v[130:133] offset:18432
	s_waitcnt vmcnt(6)
	ds_write_b128 v178, v[150:153] offset:27648
	global_load_dwordx4 v[130:133], v233, s[100:101]
	global_load_dwordx4 v[150:153], v234, s[100:101]
	ds_read_b128 v[188:191], v177 offset:46112
	ds_read_b128 v[202:205], v177 offset:50720
	ds_read_b128 v[206:209], v176 offset:64
	ds_read_b128 v[210:213], v176 offset:4672
	s_waitcnt lgkmcnt(9)
	v_mfma_f32_32x32x16_bf16 v[114:129], v[164:167], v[214:217], v[114:129]
	v_mfma_f32_32x32x16_bf16 v[82:97], v[164:167], v[218:221], v[82:97]
	s_waitcnt lgkmcnt(8)
	v_mfma_f32_32x32x16_bf16 v[98:113], v[194:197], v[214:217], v[98:113]
	v_mfma_f32_32x32x16_bf16 v[66:81], v[194:197], v[218:221], v[66:81]
	s_waitcnt lgkmcnt(3)
	v_mfma_f32_32x32x16_bf16 v[50:65], v[188:191], v[214:217], v[50:65]
	v_mfma_f32_32x32x16_bf16 v[18:33], v[188:191], v[218:221], v[18:33]
	ds_read_b128 v[164:167], v177 offset:36928
	ds_read_b128 v[188:191], v177 offset:41536
	s_waitcnt lgkmcnt(4)
	v_mfma_f32_32x32x16_bf16 v[34:49], v[202:205], v[214:217], v[34:49]
	v_mfma_f32_32x32x16_bf16 v[2:17], v[202:205], v[218:221], v[2:17]
	s_add_u32 s100, s16, s96
	s_addc_u32 s101, s17, 0
	s_waitcnt vmcnt(6)
	ds_write_b128 v179, v[154:157] offset:9216
	ds_write_b128 v179, v[138:141]
	global_load_dwordx4 v[138:141], v162, s[100:101]
	global_load_dwordx4 v[154:157], v232, s[100:101]
	ds_read_b128 v[194:197], v177 offset:46144
	ds_read_b128 v[202:205], v177 offset:50752
	ds_read_b128 v[214:217], v176 offset:96
	ds_read_b128 v[218:221], v176 offset:4704
	s_waitcnt lgkmcnt(7)
	v_mfma_f32_32x32x16_bf16 v[114:129], v[164:167], v[206:209], v[114:129]
	v_mfma_f32_32x32x16_bf16 v[82:97], v[164:167], v[210:213], v[82:97]
	s_waitcnt lgkmcnt(6)
	v_mfma_f32_32x32x16_bf16 v[98:113], v[188:191], v[206:209], v[98:113]
	v_mfma_f32_32x32x16_bf16 v[66:81], v[188:191], v[210:213], v[66:81]
	s_waitcnt lgkmcnt(3)
	v_mfma_f32_32x32x16_bf16 v[50:65], v[194:197], v[206:209], v[50:65]
	ds_read_b128 v[164:167], v177 offset:36960
	ds_read_b128 v[188:191], v177 offset:41568
	v_mfma_f32_32x32x16_bf16 v[18:33], v[194:197], v[210:213], v[18:33]
	s_waitcnt lgkmcnt(4)
	v_mfma_f32_32x32x16_bf16 v[34:49], v[202:205], v[206:209], v[34:49]
	v_mfma_f32_32x32x16_bf16 v[2:17], v[202:205], v[210:213], v[2:17]
	s_waitcnt vmcnt(7)
	ds_write_b128 v179, v[146:149] offset:18432
	s_waitcnt vmcnt(6)
	ds_write_b128 v179, v[158:161] offset:27648
	global_load_dwordx4 v[146:149], v233, s[100:101]
	global_load_dwordx4 v[158:161], v234, s[100:101]
	ds_read_b128 v[194:197], v177 offset:46176
	ds_read_b128 v[202:205], v177 offset:50784
	s_waitcnt lgkmcnt(5)
	v_mfma_f32_32x32x16_bf16 v[114:129], v[164:167], v[214:217], v[114:129]
	v_mfma_f32_32x32x16_bf16 v[82:97], v[164:167], v[218:221], v[82:97]
	s_waitcnt lgkmcnt(4)
	v_mfma_f32_32x32x16_bf16 v[98:113], v[188:191], v[214:217], v[98:113]
	v_mfma_f32_32x32x16_bf16 v[66:81], v[188:191], v[218:221], v[66:81]
	s_waitcnt lgkmcnt(1)
	v_mfma_f32_32x32x16_bf16 v[50:65], v[194:197], v[214:217], v[50:65]
	v_mfma_f32_32x32x16_bf16 v[18:33], v[194:197], v[218:221], v[18:33]
	s_waitcnt lgkmcnt(0)
	v_mfma_f32_32x32x16_bf16 v[34:49], v[202:205], v[214:217], v[34:49]
	v_mfma_f32_32x32x16_bf16 v[2:17], v[202:205], v[218:221], v[2:17]
	s_barrier
	ds_read_b128 v[164:167], v180
	ds_read_b128 v[188:191], v180 offset:4608
	ds_read_b128 v[194:197], v181
	ds_read_b128 v[202:205], v181 offset:4608
	ds_read_b128 v[206:209], v181 offset:9216
	ds_read_b128 v[210:213], v181 offset:13824
	ds_read_b128 v[214:217], v237 offset:32
	ds_read_b128 v[218:221], v182 offset:32
	s_cmp_lt_u32 s29, 13
	s_cselect_b64 s[16:17], -1, 0
	s_and_b64 s[16:17], s[16:17], exec
	s_cselect_b32 s31, s13, s25
	s_cselect_b32 s30, s12, s23
	s_cselect_b32 s17, s15, s27
	s_cselect_b32 s16, s14, s26
	s_waitcnt lgkmcnt(5)
	v_mfma_f32_32x32x16_bf16 v[114:129], v[194:197], v[164:167], v[114:129]
	v_mfma_f32_32x32x16_bf16 v[82:97], v[194:197], v[188:191], v[82:97]
	s_waitcnt lgkmcnt(4)
	v_mfma_f32_32x32x16_bf16 v[98:113], v[202:205], v[164:167], v[98:113]
	v_mfma_f32_32x32x16_bf16 v[66:81], v[202:205], v[188:191], v[66:81]
	s_waitcnt lgkmcnt(3)
	v_mfma_f32_32x32x16_bf16 v[50:65], v[206:209], v[164:167], v[50:65]
	v_add_u32_e32 v187, v175, v170
	s_cselect_b32 s33, s28, s22
	v_mfma_f32_32x32x16_bf16 v[18:33], v[206:209], v[188:191], v[18:33]
	s_waitcnt lgkmcnt(2)
	v_mfma_f32_32x32x16_bf16 v[34:49], v[210:213], v[164:167], v[34:49]
	ds_read_b128 v[164:167], v187 offset:32
	ds_read_b128 v[194:197], v183 offset:32
	v_mfma_f32_32x32x16_bf16 v[2:17], v[210:213], v[188:191], v[2:17]
	s_lshl_b32 s96, s33, 7
	s_add_u32 s100, s30, s96
	s_addc_u32 s101, s31, 0
	s_waitcnt vmcnt(6)
	ds_write_b128 v186, v[142:145] offset:9216
	ds_write_b128 v186, v[134:137]
	global_load_dwordx4 v[134:137], v162, s[100:101]
	global_load_dwordx4 v[142:145], v232, s[100:101]
	s_waitcnt vmcnt(7)
	ds_write_b128 v186, v[130:133] offset:18432
	s_waitcnt vmcnt(6)
	ds_write_b128 v186, v[150:153] offset:27648
	global_load_dwordx4 v[130:133], v233, s[100:101]
	global_load_dwordx4 v[150:153], v234, s[100:101]
	ds_read_b128 v[188:191], v184 offset:32
	ds_read_b128 v[202:205], v185 offset:32
	ds_read_b128 v[206:209], v237 offset:64
	ds_read_b128 v[210:213], v182 offset:64
	s_waitcnt lgkmcnt(9)
	v_mfma_f32_32x32x16_bf16 v[114:129], v[164:167], v[214:217], v[114:129]
	v_mfma_f32_32x32x16_bf16 v[82:97], v[164:167], v[218:221], v[82:97]
	s_waitcnt lgkmcnt(8)
	v_mfma_f32_32x32x16_bf16 v[98:113], v[194:197], v[214:217], v[98:113]
	v_mfma_f32_32x32x16_bf16 v[66:81], v[194:197], v[218:221], v[66:81]
	s_waitcnt lgkmcnt(3)
	v_mfma_f32_32x32x16_bf16 v[50:65], v[188:191], v[214:217], v[50:65]
	v_mfma_f32_32x32x16_bf16 v[18:33], v[188:191], v[218:221], v[18:33]
	ds_read_b128 v[164:167], v187 offset:64
	ds_read_b128 v[188:191], v183 offset:64
	s_waitcnt lgkmcnt(4)
	v_mfma_f32_32x32x16_bf16 v[34:49], v[202:205], v[214:217], v[34:49]
	v_mfma_f32_32x32x16_bf16 v[2:17], v[202:205], v[218:221], v[2:17]
	s_add_u32 s100, s16, s96
	s_addc_u32 s101, s17, 0
	s_waitcnt vmcnt(6)
	ds_write_b128 v186, v[154:157] offset:46080
	ds_write_b128 v186, v[138:141] offset:36864
	global_load_dwordx4 v[138:141], v162, s[100:101]
	global_load_dwordx4 v[154:157], v232, s[100:101]
	ds_read_b128 v[194:197], v184 offset:64
	ds_read_b128 v[202:205], v185 offset:64
	ds_read_b128 v[214:217], v237 offset:96
	ds_read_b128 v[218:221], v182 offset:96
	s_waitcnt lgkmcnt(7)
; DI unsigned pk2(float lo, float hi) { f32x2 v = {lo, hi}; bf16x2v b = __builtin_convertvector(v, bf16x2v); return __builtin_bit_cast(unsigned, b); }
; DI float siluf_(float x) { return x * __builtin_amdgcn_rcpf(1.f + __builtin_amdgcn_exp2f(-LOG2E * x)); }
;   DI void operator()(int tok0, int feat0, f32x16 (&acc)[2][2], int r, int hh) const {
;     const int u0 = (feat0 >> 6) * 32;
; #pragma unroll
;     for (int mt = 0; mt < 2; ++mt) {
;       bf16_t* dst = act + (size_t)(tok0 + mt * 32 + r) * DFF + u0 + 16 * hh;
; #pragma unroll
;       for (int gp = 0; gp < 2; ++gp) {
;         u32x4 o;
; #pragma unroll
;         for (int q = 0; q < 4; ++q) { const int i = 8 * gp + 2 * q; o[q] = pk2(siluf_(acc[0][mt][i]) * acc[1][mt][i], siluf_(acc[0][mt][i + 1]) * acc[1][mt][i + 1]); }
;         *(u32x4*)(dst + 8 * gp) = o;
;       }
	v_mfma_f32_32x32x16_bf16 v[114:129], v[164:167], v[206:209], v[114:129]
	v_mfma_f32_32x32x16_bf16 v[82:97], v[164:167], v[210:213], v[82:97]
	s_waitcnt lgkmcnt(6)
	v_mfma_f32_32x32x16_bf16 v[98:113], v[188:191], v[206:209], v[98:113]
	v_mfma_f32_32x32x16_bf16 v[66:81], v[188:191], v[210:213], v[66:81]
	s_waitcnt lgkmcnt(3)
	v_mfma_f32_32x32x16_bf16 v[50:65], v[194:197], v[206:209], v[50:65]
	ds_read_b128 v[164:167], v187 offset:96
	ds_read_b128 v[188:191], v183 offset:96
	v_mfma_f32_32x32x16_bf16 v[18:33], v[194:197], v[210:213], v[18:33]
	s_waitcnt lgkmcnt(4)
	v_mfma_f32_32x32x16_bf16 v[34:49], v[202:205], v[206:209], v[34:49]
	v_mfma_f32_32x32x16_bf16 v[2:17], v[202:205], v[210:213], v[2:17]
	s_waitcnt vmcnt(7)
	ds_write_b128 v186, v[146:149] offset:55296
	s_waitcnt vmcnt(6)
	ds_write_b128 v186, v[158:161] offset:64512
	global_load_dwordx4 v[146:149], v233, s[100:101]
	global_load_dwordx4 v[158:161], v234, s[100:101]
	ds_read_b128 v[194:197], v184 offset:96
	ds_read_b128 v[202:205], v185 offset:96
	s_waitcnt lgkmcnt(5)
	v_mfma_f32_32x32x16_bf16 v[114:129], v[164:167], v[214:217], v[114:129]
	v_mfma_f32_32x32x16_bf16 v[82:97], v[164:167], v[218:221], v[82:97]
	s_waitcnt lgkmcnt(4)
	v_mfma_f32_32x32x16_bf16 v[98:113], v[188:191], v[214:217], v[98:113]
	v_mfma_f32_32x32x16_bf16 v[66:81], v[188:191], v[218:221], v[66:81]
	s_waitcnt lgkmcnt(1)
	v_mfma_f32_32x32x16_bf16 v[50:65], v[194:197], v[214:217], v[50:65]
	v_mfma_f32_32x32x16_bf16 v[18:33], v[194:197], v[218:221], v[18:33]
	s_waitcnt lgkmcnt(0)
	v_mfma_f32_32x32x16_bf16 v[34:49], v[202:205], v[214:217], v[34:49]
	v_mfma_f32_32x32x16_bf16 v[2:17], v[202:205], v[218:221], v[2:17]
	s_add_i32 s28, s28, 2
	s_cmp_gt_u32 s29, 13
	s_barrier
	s_cbranch_scc0 .LBB0_739
	v_mov_b32_e32 v0, v192
	v_mov_b64_e32 v[166:167], s[6:7]
	v_ashrrev_i32_e32 v164, 1, v0
	v_and_b32_e32 v164, 0xffffff80, v164
	v_add_u32_e32 v164, s3, v164
	v_ashrrev_i32_e32 v164, 1, v164
	v_and_b32_e32 v165, 0xdf, v0
	v_or_b32_e32 v187, s8, v165
	v_ashrrev_i32_e32 v165, 31, v164
	v_mad_i64_i32 v[188:189], s[12:13], v187, s69, v[166:167]
	v_lshlrev_b64 v[168:169], 1, v[164:165]
	v_lshl_add_u64 v[164:165], v[188:189], 0, v[168:169]
	v_mul_f32_e32 v188, 0xbfb8aa3b, v114
	v_mul_f32_e32 v189, 0xbfb8aa3b, v115
	v_exp_f32_e32 v188, v188
	v_exp_f32_e32 v189, v189
	v_and_b32_e32 v0, 32, v0
	v_lshl_add_u64 v[164:165], v[164:165], 0, v[0:1]
	v_add_f32_e32 v188, 1.0, v188
	v_add_f32_e32 v189, 1.0, v189
	v_rcp_f32_e32 v188, v188
	v_rcp_f32_e32 v189, v189
	s_nop 0
	v_pk_mul_f32 v[114:115], v[114:115], v[188:189]
	s_nop 0
	v_pk_mul_f32 v[98:99], v[98:99], v[114:115]
	s_nop 0
	v_cvt_pk_bf16_f32 v98, v98, v99
	v_mul_f32_e32 v99, 0xbfb8aa3b, v116
	v_exp_f32_e32 v99, v99
	s_nop 0
	v_add_f32_e32 v99, 1.0, v99
	v_rcp_f32_e32 v114, v99
	v_mul_f32_e32 v99, 0xbfb8aa3b, v117
	v_exp_f32_e32 v99, v99
	s_nop 0
	v_add_f32_e32 v99, 1.0, v99
	v_rcp_f32_e32 v115, v99
	s_nop 0
	v_pk_mul_f32 v[114:115], v[116:117], v[114:115]
	s_nop 0
	v_pk_mul_f32 v[100:101], v[100:101], v[114:115]
	s_nop 0
	v_cvt_pk_bf16_f32 v99, v100, v101
	v_mul_f32_e32 v100, 0xbfb8aa3b, v118
	v_mul_f32_e32 v101, 0xbfb8aa3b, v119
	v_exp_f32_e32 v100, v100
	v_exp_f32_e32 v101, v101
	v_add_f32_e32 v100, 1.0, v100
	v_add_f32_e32 v101, 1.0, v101
	v_rcp_f32_e32 v100, v100
	v_rcp_f32_e32 v101, v101
	s_nop 0
	v_pk_mul_f32 v[100:101], v[118:119], v[100:101]
	s_nop 0
	v_pk_mul_f32 v[100:101], v[102:103], v[100:101]
	s_nop 0
	v_cvt_pk_bf16_f32 v100, v100, v101
	v_mul_f32_e32 v101, 0xbfb8aa3b, v120
	v_exp_f32_e32 v101, v101
	s_nop 0
	v_add_f32_e32 v101, 1.0, v101
	v_rcp_f32_e32 v102, v101
	v_mul_f32_e32 v101, 0xbfb8aa3b, v121
	v_exp_f32_e32 v101, v101
	s_nop 0
	v_add_f32_e32 v101, 1.0, v101
	v_rcp_f32_e32 v103, v101
	s_nop 0
	v_pk_mul_f32 v[102:103], v[120:121], v[102:103]
	s_nop 0
	v_pk_mul_f32 v[102:103], v[104:105], v[102:103]
	s_nop 0
	v_cvt_pk_bf16_f32 v101, v102, v103
	global_store_dwordx4 v[164:165], v[98:101], off
	s_nop 1
	v_mul_f32_e32 v98, 0xbfb8aa3b, v122
	v_mul_f32_e32 v99, 0xbfb8aa3b, v123
	v_exp_f32_e32 v98, v98
	v_exp_f32_e32 v99, v99
	v_add_f32_e32 v98, 1.0, v98
	v_add_f32_e32 v99, 1.0, v99
	v_rcp_f32_e32 v98, v98
	v_rcp_f32_e32 v99, v99
	s_nop 0
	v_pk_mul_f32 v[98:99], v[122:123], v[98:99]
	s_nop 0
	v_pk_mul_f32 v[98:99], v[106:107], v[98:99]
	s_nop 0
	v_cvt_pk_bf16_f32 v98, v98, v99
	v_mul_f32_e32 v99, 0xbfb8aa3b, v124
	v_exp_f32_e32 v99, v99
	s_nop 0
	v_add_f32_e32 v99, 1.0, v99
	v_rcp_f32_e32 v100, v99
	v_mul_f32_e32 v99, 0xbfb8aa3b, v125
	v_exp_f32_e32 v99, v99
	s_nop 0
	v_add_f32_e32 v99, 1.0, v99
	v_rcp_f32_e32 v101, v99
	s_nop 0
	v_pk_mul_f32 v[100:101], v[124:125], v[100:101]
	s_nop 0
	v_pk_mul_f32 v[100:101], v[108:109], v[100:101]
	s_nop 0
	v_cvt_pk_bf16_f32 v99, v100, v101
	v_mul_f32_e32 v100, 0xbfb8aa3b, v126
	v_mul_f32_e32 v101, 0xbfb8aa3b, v127
	v_exp_f32_e32 v100, v100
	v_exp_f32_e32 v101, v101
	v_add_f32_e32 v100, 1.0, v100
	v_add_f32_e32 v101, 1.0, v101
	v_rcp_f32_e32 v100, v100
	v_rcp_f32_e32 v101, v101
	s_nop 0
	v_pk_mul_f32 v[100:101], v[126:127], v[100:101]
	s_nop 0
	v_pk_mul_f32 v[100:101], v[110:111], v[100:101]
	s_nop 0
	v_cvt_pk_bf16_f32 v100, v100, v101
	v_mul_f32_e32 v101, 0xbfb8aa3b, v128
	v_exp_f32_e32 v101, v101
	s_nop 0
	v_add_f32_e32 v101, 1.0, v101
	v_rcp_f32_e32 v102, v101
	v_mul_f32_e32 v101, 0xbfb8aa3b, v129
	v_exp_f32_e32 v101, v101
	s_nop 0
	v_add_f32_e32 v101, 1.0, v101
	v_rcp_f32_e32 v103, v101
	s_nop 0
	v_pk_mul_f32 v[102:103], v[128:129], v[102:103]
	s_nop 0
	v_pk_mul_f32 v[102:103], v[112:113], v[102:103]
	s_nop 0
	v_cvt_pk_bf16_f32 v101, v102, v103
	global_store_dwordx4 v[164:165], v[98:101], off offset:16
	s_nop 1
	v_or_b32_e32 v98, 32, v187
; DI unsigned pk2(float lo, float hi) { f32x2 v = {lo, hi}; bf16x2v b = __builtin_convertvector(v, bf16x2v); return __builtin_bit_cast(unsigned, b); }
; DI float siluf_(float x) { return x * __builtin_amdgcn_rcpf(1.f + __builtin_amdgcn_exp2f(-LOG2E * x)); }
;   DI void operator()(int tok0, int feat0, f32x16 (&acc)[2][2], int r, int hh) const {
;     const int u0 = (feat0 >> 6) * 32;
; #pragma unroll
;     for (int mt = 0; mt < 2; ++mt) {
;       bf16_t* dst = act + (size_t)(tok0 + mt * 32 + r) * DFF + u0 + 16 * hh;
; #pragma unroll
;       for (int gp = 0; gp < 2; ++gp) {
;         u32x4 o;
; #pragma unroll
;         for (int q = 0; q < 4; ++q) { const int i = 8 * gp + 2 * q; o[q] = pk2(siluf_(acc[0][mt][i]) * acc[1][mt][i], siluf_(acc[0][mt][i + 1]) * acc[1][mt][i + 1]); }
;         *(u32x4*)(dst + 8 * gp) = o;
;       }
	v_mad_i64_i32 v[98:99], s[12:13], v98, s69, v[166:167]
	v_lshl_add_u64 v[98:99], v[98:99], 0, v[168:169]
	v_lshl_add_u64 v[98:99], v[98:99], 0, v[0:1]
	v_mul_f32_e32 v0, 0xbfb8aa3b, v82
	v_exp_f32_e32 v0, v0
	s_nop 0
	v_add_f32_e32 v0, 1.0, v0
	v_rcp_f32_e32 v100, v0
	v_mul_f32_e32 v0, 0xbfb8aa3b, v83
	v_exp_f32_e32 v0, v0
	s_nop 0
	v_add_f32_e32 v0, 1.0, v0
	v_rcp_f32_e32 v101, v0
	v_mul_f32_e32 v0, 0xbfb8aa3b, v84
	v_exp_f32_e32 v0, v0
	v_pk_mul_f32 v[82:83], v[82:83], v[100:101]
	s_nop 0
	v_pk_mul_f32 v[66:67], v[66:67], v[82:83]
	v_add_f32_e32 v0, 1.0, v0
	v_rcp_f32_e32 v82, v0
	v_mul_f32_e32 v0, 0xbfb8aa3b, v85
	v_exp_f32_e32 v0, v0
	v_cvt_pk_bf16_f32 v66, v66, v67
	v_add_f32_e32 v0, 1.0, v0
	v_rcp_f32_e32 v83, v0
	v_mul_f32_e32 v0, 0xbfb8aa3b, v86
	v_exp_f32_e32 v0, v0
	v_pk_mul_f32 v[82:83], v[84:85], v[82:83]
	s_nop 0
	v_pk_mul_f32 v[68:69], v[68:69], v[82:83]
	v_add_f32_e32 v0, 1.0, v0
	v_cvt_pk_bf16_f32 v67, v68, v69
	v_rcp_f32_e32 v68, v0
	v_mul_f32_e32 v0, 0xbfb8aa3b, v87
	v_exp_f32_e32 v0, v0
	s_nop 0
	v_add_f32_e32 v0, 1.0, v0
	v_rcp_f32_e32 v69, v0
	v_mul_f32_e32 v0, 0xbfb8aa3b, v88
	v_exp_f32_e32 v0, v0
	v_pk_mul_f32 v[68:69], v[86:87], v[68:69]
	s_nop 0
	v_pk_mul_f32 v[68:69], v[70:71], v[68:69]
	v_add_f32_e32 v0, 1.0, v0
	v_rcp_f32_e32 v70, v0
	v_mul_f32_e32 v0, 0xbfb8aa3b, v89
	v_exp_f32_e32 v0, v0
	v_cvt_pk_bf16_f32 v68, v68, v69
	v_add_f32_e32 v0, 1.0, v0
	v_rcp_f32_e32 v71, v0
	v_mul_f32_e32 v0, 0xbfb8aa3b, v90
	v_exp_f32_e32 v0, v0
	v_pk_mul_f32 v[70:71], v[88:89], v[70:71]
	s_nop 0
	v_pk_mul_f32 v[70:71], v[72:73], v[70:71]
	v_add_f32_e32 v0, 1.0, v0
	v_cvt_pk_bf16_f32 v69, v70, v71
	global_store_dwordx4 v[98:99], v[66:69], off
	s_nop 1
	v_rcp_f32_e32 v66, v0
	v_mul_f32_e32 v0, 0xbfb8aa3b, v91
	v_exp_f32_e32 v0, v0
	s_nop 0
	v_add_f32_e32 v0, 1.0, v0
	v_rcp_f32_e32 v67, v0
	v_mul_f32_e32 v0, 0xbfb8aa3b, v92
	v_exp_f32_e32 v0, v0
	v_pk_mul_f32 v[66:67], v[90:91], v[66:67]
	s_nop 0
	v_pk_mul_f32 v[66:67], v[74:75], v[66:67]
	v_add_f32_e32 v0, 1.0, v0
	v_rcp_f32_e32 v68, v0
	v_mul_f32_e32 v0, 0xbfb8aa3b, v93
	v_exp_f32_e32 v0, v0
	v_cvt_pk_bf16_f32 v66, v66, v67
	v_add_f32_e32 v0, 1.0, v0
	v_rcp_f32_e32 v69, v0
	v_mul_f32_e32 v0, 0xbfb8aa3b, v94
	v_exp_f32_e32 v0, v0
	v_pk_mul_f32 v[68:69], v[92:93], v[68:69]
	s_nop 0
	v_pk_mul_f32 v[68:69], v[76:77], v[68:69]
	v_add_f32_e32 v0, 1.0, v0
	v_cvt_pk_bf16_f32 v67, v68, v69
	v_rcp_f32_e32 v68, v0
	v_mul_f32_e32 v0, 0xbfb8aa3b, v95
	v_exp_f32_e32 v0, v0
	s_nop 0
	v_add_f32_e32 v0, 1.0, v0
	v_rcp_f32_e32 v69, v0
	v_mul_f32_e32 v0, 0xbfb8aa3b, v96
	v_exp_f32_e32 v0, v0
	v_pk_mul_f32 v[68:69], v[94:95], v[68:69]
	s_nop 0
	v_pk_mul_f32 v[68:69], v[78:79], v[68:69]
	v_add_f32_e32 v0, 1.0, v0
	v_rcp_f32_e32 v70, v0
	v_mul_f32_e32 v0, 0xbfb8aa3b, v97
	v_exp_f32_e32 v0, v0
	v_cvt_pk_bf16_f32 v68, v68, v69
	v_add_f32_e32 v0, 1.0, v0
	v_rcp_f32_e32 v71, v0
	s_nop 0
	v_pk_mul_f32 v[70:71], v[96:97], v[70:71]
	s_nop 0
	v_pk_mul_f32 v[70:71], v[80:81], v[70:71]
	s_nop 0
	v_cvt_pk_bf16_f32 v69, v70, v71
	global_store_dwordx4 v[98:99], v[66:69], off offset:16
	v_mul_f32_e32 v0, 0xbfb8aa3b, v50
	v_exp_f32_e32 v0, v0
	s_nop 0
	v_add_f32_e32 v0, 1.0, v0
	v_rcp_f32_e32 v66, v0
	v_mul_f32_e32 v0, 0xbfb8aa3b, v51
	v_exp_f32_e32 v0, v0
	s_nop 0
	v_add_f32_e32 v0, 1.0, v0
	v_rcp_f32_e32 v67, v0
	v_mul_f32_e32 v0, 0xbfb8aa3b, v52
	v_exp_f32_e32 v0, v0
	v_pk_mul_f32 v[50:51], v[50:51], v[66:67]
	s_nop 0
	v_pk_mul_f32 v[34:35], v[34:35], v[50:51]
	v_add_f32_e32 v0, 1.0, v0
	v_rcp_f32_e32 v50, v0
	v_mul_f32_e32 v0, 0xbfb8aa3b, v53
	v_exp_f32_e32 v0, v0
	v_cvt_pk_bf16_f32 v34, v34, v35
	v_add_f32_e32 v0, 1.0, v0
	v_rcp_f32_e32 v51, v0
	v_mul_f32_e32 v0, 0xbfb8aa3b, v54
	v_exp_f32_e32 v0, v0
	v_pk_mul_f32 v[50:51], v[52:53], v[50:51]
	s_nop 0
	v_pk_mul_f32 v[36:37], v[36:37], v[50:51]
	v_add_f32_e32 v0, 1.0, v0
	v_cvt_pk_bf16_f32 v35, v36, v37
	v_rcp_f32_e32 v36, v0
	v_mul_f32_e32 v0, 0xbfb8aa3b, v55
	v_exp_f32_e32 v0, v0
	s_nop 0
	v_add_f32_e32 v0, 1.0, v0
	v_rcp_f32_e32 v37, v0
	v_mul_f32_e32 v0, 0xbfb8aa3b, v56
	v_exp_f32_e32 v0, v0
	v_pk_mul_f32 v[36:37], v[54:55], v[36:37]
	s_nop 0
	v_pk_mul_f32 v[36:37], v[38:39], v[36:37]
	v_add_f32_e32 v0, 1.0, v0
	v_rcp_f32_e32 v38, v0
	v_mul_f32_e32 v0, 0xbfb8aa3b, v57
	v_exp_f32_e32 v0, v0
	v_cvt_pk_bf16_f32 v36, v36, v37
	v_add_f32_e32 v0, 1.0, v0
	v_rcp_f32_e32 v39, v0
	v_mul_f32_e32 v0, 0xbfb8aa3b, v58
	v_exp_f32_e32 v0, v0
	v_pk_mul_f32 v[38:39], v[56:57], v[38:39]
	s_nop 0
	v_pk_mul_f32 v[38:39], v[40:41], v[38:39]
	v_add_f32_e32 v0, 1.0, v0
	v_cvt_pk_bf16_f32 v37, v38, v39
	global_store_dwordx4 v[164:165], v[34:37], off offset:64
	s_nop 1
	v_rcp_f32_e32 v34, v0
	v_mul_f32_e32 v0, 0xbfb8aa3b, v59
	v_exp_f32_e32 v0, v0
	s_nop 0
	v_add_f32_e32 v0, 1.0, v0
	v_rcp_f32_e32 v35, v0
	v_mul_f32_e32 v0, 0xbfb8aa3b, v60
	v_exp_f32_e32 v0, v0
	v_pk_mul_f32 v[34:35], v[58:59], v[34:35]
; #define GAS __attribute__((address_space(1)))
; DI unsigned pk2(float lo, float hi) { f32x2 v = {lo, hi}; bf16x2v b = __builtin_convertvector(v, bf16x2v); return __builtin_bit_cast(unsigned, b); }
; DI float siluf_(float x) { return x * __builtin_amdgcn_rcpf(1.f + __builtin_amdgcn_exp2f(-LOG2E * x)); }
;   DI void operator()(int tok0, int feat0, f32x16 (&acc)[2][2], int r, int hh) const {
;     const int u0 = (feat0 >> 6) * 32;
; #pragma unroll
;     for (int mt = 0; mt < 2; ++mt) {
;       bf16_t* dst = act + (size_t)(tok0 + mt * 32 + r) * DFF + u0 + 16 * hh;
; #pragma unroll
;       for (int gp = 0; gp < 2; ++gp) {
;         u32x4 o;
; #pragma unroll
;         for (int q = 0; q < 4; ++q) { const int i = 8 * gp + 2 * q; o[q] = pk2(siluf_(acc[0][mt][i]) * acc[1][mt][i], siluf_(acc[0][mt][i + 1]) * acc[1][mt][i + 1]); }
;         *(u32x4*)(dst + 8 * gp) = o;
;       }
; DI void grid_barrier(unsigned* ctr, const unsigned target) {
;   asm volatile("s_waitcnt vmcnt(0)" ::: "memory");
;   __syncthreads();
;   if (threadIdx.x == 0) {
;     __builtin_amdgcn_fence(__ATOMIC_RELEASE, "agent");
;     asm volatile("s_waitcnt vmcnt(0)" ::: "memory");
;     __hip_atomic_fetch_add((GAS unsigned*)ctr, 1u, __ATOMIC_RELAXED, __HIP_MEMORY_SCOPE_AGENT);
;     while (__hip_atomic_load((GAS unsigned*)ctr, __ATOMIC_RELAXED, __HIP_MEMORY_SCOPE_AGENT) < target) __builtin_amdgcn_s_sleep(1);
	s_nop 0
	v_pk_mul_f32 v[34:35], v[42:43], v[34:35]
	v_add_f32_e32 v0, 1.0, v0
	v_rcp_f32_e32 v36, v0
	v_mul_f32_e32 v0, 0xbfb8aa3b, v61
	v_exp_f32_e32 v0, v0
	v_cvt_pk_bf16_f32 v34, v34, v35
	v_add_f32_e32 v0, 1.0, v0
	v_rcp_f32_e32 v37, v0
	v_mul_f32_e32 v0, 0xbfb8aa3b, v62
	v_exp_f32_e32 v0, v0
	v_pk_mul_f32 v[36:37], v[60:61], v[36:37]
	s_nop 0
	v_pk_mul_f32 v[36:37], v[44:45], v[36:37]
	v_add_f32_e32 v0, 1.0, v0
	v_cvt_pk_bf16_f32 v35, v36, v37
	v_rcp_f32_e32 v36, v0
	v_mul_f32_e32 v0, 0xbfb8aa3b, v63
	v_exp_f32_e32 v0, v0
	s_nop 0
	v_add_f32_e32 v0, 1.0, v0
	v_rcp_f32_e32 v37, v0
	v_mul_f32_e32 v0, 0xbfb8aa3b, v64
	v_exp_f32_e32 v0, v0
	v_pk_mul_f32 v[36:37], v[62:63], v[36:37]
	s_nop 0
	v_pk_mul_f32 v[36:37], v[46:47], v[36:37]
	v_add_f32_e32 v0, 1.0, v0
	v_rcp_f32_e32 v38, v0
	v_mul_f32_e32 v0, 0xbfb8aa3b, v65
	v_exp_f32_e32 v0, v0
	v_cvt_pk_bf16_f32 v36, v36, v37
	v_add_f32_e32 v0, 1.0, v0
	v_rcp_f32_e32 v39, v0
	v_mul_f32_e32 v0, 0xbfb8aa3b, v18
	v_exp_f32_e32 v0, v0
	v_pk_mul_f32 v[38:39], v[64:65], v[38:39]
	s_nop 0
	v_pk_mul_f32 v[38:39], v[48:49], v[38:39]
	v_add_f32_e32 v0, 1.0, v0
	v_cvt_pk_bf16_f32 v37, v38, v39
	global_store_dwordx4 v[164:165], v[34:37], off offset:80
	s_nop 1
	v_rcp_f32_e32 v34, v0
	v_mul_f32_e32 v0, 0xbfb8aa3b, v19
	v_exp_f32_e32 v0, v0
	s_nop 0
	v_add_f32_e32 v0, 1.0, v0
	v_rcp_f32_e32 v35, v0
	v_mul_f32_e32 v0, 0xbfb8aa3b, v20
	v_exp_f32_e32 v0, v0
	v_pk_mul_f32 v[18:19], v[18:19], v[34:35]
	s_nop 0
	v_pk_mul_f32 v[2:3], v[2:3], v[18:19]
	v_add_f32_e32 v0, 1.0, v0
	v_rcp_f32_e32 v18, v0
	v_mul_f32_e32 v0, 0xbfb8aa3b, v21
	v_exp_f32_e32 v0, v0
	v_cvt_pk_bf16_f32 v2, v2, v3
	v_add_f32_e32 v0, 1.0, v0
	v_rcp_f32_e32 v19, v0
	v_mul_f32_e32 v0, 0xbfb8aa3b, v22
	v_exp_f32_e32 v0, v0
	v_pk_mul_f32 v[18:19], v[20:21], v[18:19]
	s_nop 0
	v_pk_mul_f32 v[4:5], v[4:5], v[18:19]
	v_add_f32_e32 v0, 1.0, v0
	v_cvt_pk_bf16_f32 v3, v4, v5
	v_rcp_f32_e32 v4, v0
	v_mul_f32_e32 v0, 0xbfb8aa3b, v23
	v_exp_f32_e32 v0, v0
	s_nop 0
	v_add_f32_e32 v0, 1.0, v0
	v_rcp_f32_e32 v5, v0
	v_mul_f32_e32 v0, 0xbfb8aa3b, v24
	v_exp_f32_e32 v0, v0
	v_pk_mul_f32 v[4:5], v[22:23], v[4:5]
	s_nop 0
	v_pk_mul_f32 v[4:5], v[6:7], v[4:5]
	v_add_f32_e32 v0, 1.0, v0
	v_rcp_f32_e32 v6, v0
	v_mul_f32_e32 v0, 0xbfb8aa3b, v25
	v_exp_f32_e32 v0, v0
	v_cvt_pk_bf16_f32 v4, v4, v5
	v_add_f32_e32 v0, 1.0, v0
	v_rcp_f32_e32 v7, v0
	v_mul_f32_e32 v0, 0xbfb8aa3b, v26
	v_exp_f32_e32 v0, v0
	v_pk_mul_f32 v[6:7], v[24:25], v[6:7]
	s_nop 0
	v_pk_mul_f32 v[6:7], v[8:9], v[6:7]
	v_add_f32_e32 v0, 1.0, v0
	v_cvt_pk_bf16_f32 v5, v6, v7
	global_store_dwordx4 v[98:99], v[2:5], off offset:64
	s_nop 1
	v_rcp_f32_e32 v2, v0
	v_mul_f32_e32 v0, 0xbfb8aa3b, v27
	v_exp_f32_e32 v0, v0
	s_nop 0
	v_add_f32_e32 v0, 1.0, v0
	v_rcp_f32_e32 v3, v0
	v_mul_f32_e32 v0, 0xbfb8aa3b, v28
	v_exp_f32_e32 v0, v0
	v_pk_mul_f32 v[2:3], v[26:27], v[2:3]
	s_nop 0
	v_pk_mul_f32 v[2:3], v[10:11], v[2:3]
	v_add_f32_e32 v0, 1.0, v0
	v_rcp_f32_e32 v4, v0
	v_mul_f32_e32 v0, 0xbfb8aa3b, v29
	v_exp_f32_e32 v0, v0
	v_cvt_pk_bf16_f32 v2, v2, v3
	v_add_f32_e32 v0, 1.0, v0
	v_rcp_f32_e32 v5, v0
	v_mul_f32_e32 v0, 0xbfb8aa3b, v30
	v_exp_f32_e32 v0, v0
	v_pk_mul_f32 v[4:5], v[28:29], v[4:5]
	s_nop 0
	v_pk_mul_f32 v[4:5], v[12:13], v[4:5]
	v_add_f32_e32 v0, 1.0, v0
	v_cvt_pk_bf16_f32 v3, v4, v5
	v_rcp_f32_e32 v4, v0
	v_mul_f32_e32 v0, 0xbfb8aa3b, v31
	v_exp_f32_e32 v0, v0
	s_nop 0
	v_add_f32_e32 v0, 1.0, v0
	v_rcp_f32_e32 v5, v0
	v_mul_f32_e32 v0, 0xbfb8aa3b, v32
	v_exp_f32_e32 v0, v0
	v_pk_mul_f32 v[4:5], v[30:31], v[4:5]
	s_nop 0
	v_pk_mul_f32 v[4:5], v[14:15], v[4:5]
	v_add_f32_e32 v0, 1.0, v0
	v_rcp_f32_e32 v6, v0
	v_mul_f32_e32 v0, 0xbfb8aa3b, v33
	v_exp_f32_e32 v0, v0
	v_cvt_pk_bf16_f32 v4, v4, v5
	v_add_f32_e32 v0, 1.0, v0
	v_rcp_f32_e32 v7, v0
	s_nop 0
	v_pk_mul_f32 v[6:7], v[32:33], v[6:7]
	s_nop 0
	v_pk_mul_f32 v[6:7], v[16:17], v[6:7]
	s_nop 0
	v_cvt_pk_bf16_f32 v5, v6, v7
	global_store_dwordx4 v[98:99], v[2:5], off offset:80
	s_and_b64 vcc, exec, s[4:5]
	s_mov_b32 s16, s9
	s_cbranch_vccz .LBB0_736
	s_add_i32 s25, s24, 1
	s_cmp_ge_i32 s25, s79
	s_cbranch_scc1 .LBB0_762
	s_cmp_lg_u32 s24, s78
	s_mov_b64 s[4:5], -1
	v_mov_b32_e32 v206, v198
	v_mov_b32_e32 v207, v199
	s_cbranch_scc0 .LBB0_750
	s_waitcnt vmcnt(0)
	s_barrier
	s_mov_b64 s[4:5], exec
	v_readlane_b32 s2, v254, 26
	v_readlane_b32 s3, v254, 27
	s_and_b64 s[2:3], s[4:5], s[2:3]
	s_mov_b64 exec, s[2:3]
	s_cbranch_execz .LBB0_749
	s_load_dword s2, s[80:81], 0x0
	s_mov_b64 s[8:9], exec
	buffer_wbl2 sc1
	s_waitcnt vmcnt(0) lgkmcnt(0)
	s_waitcnt vmcnt(0)
	v_mbcnt_lo_u32_b32 v0, s8, 0
	s_add_u32 s6, s10, 0x1ee14400
	v_mbcnt_hi_u32_b32 v0, s9, v0
	s_addc_u32 s7, s11, 0
	v_cmp_eq_u32_e32 vcc, 0, v0
	s_and_saveexec_b64 s[10:11], vcc
	s_cbranch_execz .LBB0_746
	s_bcnt1_i32_b64 s3, s[8:9]
	v_mov_b32_e32 v0, s3
	global_atomic_add v1, v0, s[6:7]

; #define G_GLOAD(XR, WR, KT) { _Pragma("unroll") for (int i_ = 0; i_ < 4; ++i_) XR[i_] = *(const u32x4*)(Xt + ((size_t)(64 * i_) * ldx + (KT) * 64) * 2 + xoff); \
;     _Pragma("unroll") for (int i_ = 0; i_ < 4; ++i_) WR[i_] = *(const u32x4*)(Wtb + ((size_t)(64 * i_) * K + (KT) * 64) * 2 + woff); }
; #define G_LSTORE(XR, WR, STG) { char* xs_ = lds + (STG) * G_STAGE; char* ws_ = xs_ + G_XB; \
;     _Pragma("unroll") for (int i_ = 0; i_ < 4; ++i_) *(u32x4*)(xs_ + (lrow + 64 * i_) * LROW + lch * 16) = XR[i_]; \
;     _Pragma("unroll") for (int i_ = 0; i_ < 4; ++i_) *(u32x4*)(ws_ + (lrow + 64 * i_) * LROW + lch * 16) = WR[i_]; }
; template <class Epi>
; DI void gemm_phase(const bf16_t* __restrict__ X, const int ldx, const bf16_t* __restrict__ Wt, const int N, const int K, const Epi& epi, char* lds) {
;     ...
;     const int L = chunk * 32 + slot, band = L / (4 * nNt), rem = L % (4 * nNt);
;     const int mt_ = band * 4 + (rem & 3), nt_ = rem >> 2;
;     const char* Xt = (const char*)(X + (size_t)(mt_ * 256) * ldx);
;     const char* Wtb = (const char*)(Wt + (size_t)(nt_ * 256) * K);
;     const unsigned xoff = (unsigned)(lrow * ldx + lch * 8) * 2u, woff = (unsigned)(lrow * K + lch * 8) * 2u;
;     const bool has_next = !Epi::kFull && (chunk + 8 < nchunks);
;     const int Ln = (has_next ? chunk + 8 : chunk) * 32 + slot, band_n = Ln / (4 * nNt), rem_n = Ln % (4 * nNt);
;     const char* Xt_n = (const char*)(X + (size_t)((band_n * 4 + (rem_n & 3)) * 256) * ldx);
;     const char* Wtb_n = (const char*)(Wt + (size_t)((rem_n >> 2) * 256) * K);
;     f32x16 acc[2][2][2];
;     ...
;     asm volatile("" ::: "memory");
;     if (Epi::kFull || chunk == xcd) {
;       G_GLOAD(xr0, wr0, 0);
;       G_LSTORE(xr0, wr0, 0);
;       __syncthreads();
;       G_GLOAD(xr0, wr0, 1);
;     }
; #pragma unroll
;     for (int c = 0; c < 2; ++c)
; #pragma unroll
;       for (int a = 0; a < 2; ++a)
; #pragma unroll
;         for (int b = 0; b < 2; ++b)
; #pragma unroll
;           for (int i = 0; i < 16; ++i) acc[c][a][b][i] = 0.f;
.LBB0_768:
	s_lshl_b32 s2, s35, 5
	v_readlane_b32 s3, v254, 3
	s_add_i32 s2, s2, s3
	s_lshr_b32 s2, s2, 2
	s_and_b32 s2, s2, 0xffffffc
	s_or_b32 s36, s2, s90
	s_lshl_b32 s2, s36, 8
	s_mul_i32 s3, s36, 0x160000
	s_mul_hi_u32 s5, s2, 0x1600
	s_add_u32 s4, s31, s3
	s_addc_u32 s5, s34, s5
	v_lshl_add_u64 v[178:179], s[4:5], 0, v[162:163]
	v_add_co_u32_e32 v70, vcc, s93, v178
	s_mov_b64 s[18:19], 0xb0000
	s_nop 0
	v_addc_co_u32_e32 v71, vcc, 0, v179, vcc
	v_add_co_u32_e32 v72, vcc, s49, v178
	global_load_dwordx4 v[22:25], v[178:179], off
	global_load_dwordx4 v[26:29], v[70:71], off
	v_addc_co_u32_e32 v73, vcc, 0, v179, vcc
	global_load_dwordx4 v[30:33], v[72:73], off
	global_load_dwordx4 v[50:53], v[164:165], off
	global_load_dwordx4 v[54:57], v[198:199], off
	global_load_dwordx4 v[58:61], v[206:207], off
	global_load_dwordx4 v[62:65], v[170:171], off
	v_add_co_u32_e32 v74, vcc, s70, v178
	v_mov_b32_e32 v2, 0
	s_nop 0
	v_addc_co_u32_e32 v75, vcc, 0, v179, vcc
	global_load_dwordx4 v[66:69], v[74:75], off
	v_lshl_add_u64 v[180:181], v[178:179], 0, s[18:19]
	s_mov_b64 s[18:19], 0x108000
	s_mov_b32 s5, 0
	s_movk_i32 s3, 0x100
	v_mov_b32_e32 v3, v2
	v_mov_b64_e32 v[4:5], v[2:3]
	v_mov_b64_e32 v[6:7], v[2:3]
	v_mov_b64_e32 v[8:9], v[2:3]
	v_mov_b64_e32 v[10:11], v[2:3]
	v_mov_b64_e32 v[12:13], v[2:3]
	v_mov_b64_e32 v[14:15], v[2:3]
	v_mov_b64_e32 v[16:17], v[2:3]
	s_waitcnt vmcnt(13)
	v_mov_b64_e32 v[34:35], v[2:3]
	v_mov_b64_e32 v[36:37], v[2:3]
	s_waitcnt vmcnt(12)
	v_mov_b64_e32 v[38:39], v[2:3]
	v_mov_b64_e32 v[40:41], v[2:3]
	s_waitcnt vmcnt(11)
	v_mov_b64_e32 v[42:43], v[2:3]
	v_mov_b64_e32 v[44:45], v[2:3]
	s_waitcnt vmcnt(10)
	v_mov_b64_e32 v[46:47], v[2:3]
	v_mov_b64_e32 v[48:49], v[2:3]
	v_mov_b64_e32 v[18:19], v[2:3]
	v_mov_b64_e32 v[20:21], v[2:3]
	v_lshl_add_u64 v[182:183], v[178:179], 0, s[18:19]
	v_mov_b64_e32 v[82:83], v[2:3]
	v_mov_b64_e32 v[84:85], v[2:3]
	v_mov_b64_e32 v[86:87], v[2:3]
	v_mov_b64_e32 v[88:89], v[2:3]
	v_mov_b64_e32 v[90:91], v[2:3]
	v_mov_b64_e32 v[92:93], v[2:3]
	v_mov_b64_e32 v[94:95], v[2:3]
	v_mov_b64_e32 v[96:97], v[2:3]
	v_mov_b64_e32 v[98:99], v[2:3]
	v_mov_b64_e32 v[100:101], v[2:3]
	v_mov_b64_e32 v[102:103], v[2:3]
	s_waitcnt vmcnt(4)
	ds_write_b128 v224, v[50:53] offset:36864
	s_waitcnt vmcnt(3)
	ds_write_b128 v224, v[54:57] offset:46080
	s_waitcnt vmcnt(2)
	ds_write_b128 v224, v[58:61] offset:55296
	s_waitcnt vmcnt(1)
	ds_write_b128 v224, v[62:65] offset:64512
	ds_write_b128 v224, v[22:25]
	ds_write_b128 v224, v[30:33] offset:18432
	ds_write_b128 v224, v[26:29] offset:9216
	s_waitcnt vmcnt(0)
	ds_write_b128 v224, v[66:69] offset:27648
	s_waitcnt lgkmcnt(0)
	s_barrier
	global_load_dwordx4 v[130:133], v[174:175], off
	global_load_dwordx4 v[150:153], v[176:177], off
	global_load_dwordx4 v[158:161], v[172:173], off
	global_load_dwordx4 v[138:141], v[164:165], off offset:128
	global_load_dwordx4 v[146:149], v[74:75], off offset:128
	global_load_dwordx4 v[134:137], v[72:73], off offset:128
	global_load_dwordx4 v[154:157], v[70:71], off offset:128
	global_load_dwordx4 v[142:145], v[178:179], off offset:128
	v_mov_b64_e32 v[22:23], v[2:3]
	v_mov_b64_e32 v[24:25], v[2:3]
	v_mov_b64_e32 v[26:27], v[2:3]
	v_mov_b64_e32 v[28:29], v[2:3]
	v_mov_b64_e32 v[30:31], v[2:3]
	v_mov_b64_e32 v[32:33], v[2:3]
	v_mov_b64_e32 v[50:51], v[2:3]
	v_mov_b64_e32 v[52:53], v[2:3]
	v_mov_b64_e32 v[54:55], v[2:3]
	v_mov_b64_e32 v[56:57], v[2:3]
	v_mov_b64_e32 v[58:59], v[2:3]
	v_mov_b64_e32 v[60:61], v[2:3]
	v_mov_b64_e32 v[62:63], v[2:3]
	v_mov_b64_e32 v[64:65], v[2:3]
	v_mov_b64_e32 v[104:105], v[2:3]
	v_mov_b64_e32 v[106:107], v[2:3]
	v_mov_b64_e32 v[108:109], v[2:3]
	v_mov_b64_e32 v[110:111], v[2:3]
	v_mov_b64_e32 v[112:113], v[2:3]
	v_mov_b64_e32 v[66:67], v[2:3]
	v_mov_b64_e32 v[68:69], v[2:3]
	v_mov_b64_e32 v[70:71], v[2:3]
	v_mov_b64_e32 v[72:73], v[2:3]
	v_mov_b64_e32 v[74:75], v[2:3]
	v_mov_b64_e32 v[76:77], v[2:3]
	v_mov_b64_e32 v[78:79], v[2:3]
	v_mov_b64_e32 v[80:81], v[2:3]
	v_mov_b64_e32 v[114:115], v[2:3]
	v_mov_b32_e32 v116, v2
	v_mov_b32_e32 v117, v2
	v_mov_b32_e32 v118, v2
	v_mov_b32_e32 v119, v2
	v_mov_b32_e32 v120, v2
	v_mov_b32_e32 v121, v2
	v_mov_b32_e32 v122, v2
	v_mov_b32_e32 v123, v2
	v_mov_b32_e32 v124, v2
	v_mov_b32_e32 v125, v2
	v_mov_b32_e32 v126, v2
	v_mov_b32_e32 v127, v2
	v_mov_b32_e32 v128, v2
	v_mov_b32_e32 v129, v2
